# GEMM epilogue 16-byte stores made write-through (sc1) so the grid barrier release has less to flush
# baseline (speedup 1.0000x reference)
; __device__ __forceinline__ unsigned cvt_pk_bf16(float lo, float hi) { f32x2_t v = {lo, hi}; bf16x2_t b = __builtin_convertvector(v, bf16x2_t); return __builtin_bit_cast(unsigned, b); }
; #define LAS __attribute__((address_space(3)))
; __device__ __forceinline__ void transpose_item(const float* W, int K, int N, bf16* WT, LAS float* scr, int item, int lane) {
;     const int nblk = N / 64, kb = item / nblk, nb = item % nblk, k0 = 64 * kb, n0 = 64 * nb;
;     f32x4 v[16];
; #pragma unroll
;     for (int i = 0; i < 16; ++i) v[i] = __builtin_nontemporal_load((const f32x4*)(W + (size_t)(k0 + 4 * i + (lane >> 4)) * N + n0 + (lane & 15) * 4));
; #pragma unroll
;     for (int i = 0; i < 16; ++i) { LAS float* d = scr + (4 * i + (lane >> 4)) * 65 + (lane & 15) * 4; d[0] = v[i].x; d[1] = v[i].y; d[2] = v[i].z; d[3] = v[i].w; }
;     asm volatile("s_waitcnt lgkmcnt(0)" ::: "memory");
;     const int c = lane & 7;
; #pragma unroll
;     for (int j = 0; j < 8; ++j) { const int n = (lane >> 3) + 8 * j; const LAS float* s = scr + (8 * c) * 65 + n;
;         v4u o; o.x = pg8::cvt_pk_bf16(s[0 * 65], s[1 * 65]); o.y = pg8::cvt_pk_bf16(s[2 * 65], s[3 * 65]); o.z = pg8::cvt_pk_bf16(s[4 * 65], s[5 * 65]); o.w = pg8::cvt_pk_bf16(s[6 * 65], s[7 * 65]);
;         *(v4u*)(WT + (size_t)(n0 + n) * K + k0 + 8 * c) = o; }
;     asm volatile("s_waitcnt lgkmcnt(0)" ::: "memory");
; }
; __global__ void __launch_bounds__(NTHR, 2) mega_fwd(Args args) {
;     ...
;         for (int it = gw; it < NITEMS; it += NGW) {
;             int r = it;
;             if (r < I_IN) { transpose_item(w_in, DM, INW, WIN, scr, r, lane); continue; } r -= I_IN;
;             if (r < I_C) { transpose_item(w_conv_out, CW, DM, WC, scr, r, lane); continue; } r -= I_C;
;             if (r < I_C) { transpose_item(w_attn_out, CW, DM, WA, scr, r, lane); continue; } r -= I_C;
;             if (r < I_O) { transpose_item(w_out, DM, DM, WO, scr, r, lane); continue; } r -= I_O;
;             if (r < I_1) { transpose_item(w_mlp_in, DM, FF, W1, scr, r, lane); continue; } r -= I_1;
;             transpose_item(w_mlp_out, FF, DM, W2, scr, r, lane);
.LBB0_32:
	s_cmpk_gt_i32 s10, 0x11ff
	s_mov_b64 s[6:7], -1
	s_cbranch_scc0 .LBB0_50
	s_cmpk_gt_u32 s10, 0x13ff
	s_cbranch_scc0 .LBB0_47
	s_cmpk_gt_u32 s10, 0x15ff
	s_cbranch_scc0 .LBB0_44
	s_cmpk_gt_u32 s10, 0x19ff
	s_cbranch_scc0 .LBB0_41
	s_cmpk_gt_u32 s10, 0x29ff
	s_cbranch_scc0 .LBB0_38
	s_and_b32 s7, s18, 0x1ffc0
	s_and_b32 s6, s11, 0x7c0
	v_or_b32_e32 v0, s7, v26
	s_lshl_b32 s4, s6, 2
	v_lshl_add_u64 v[58:59], v[2:3], 0, s[4:5]
	v_lshlrev_b32_e32 v0, 13, v0
	v_lshl_add_u64 v[118:119], v[58:59], 0, v[0:1]
	v_add_co_u32_e32 v66, vcc, 0x8000, v118
	v_add_u32_e32 v0, 0x2cb0, v27
	s_nop 0
	v_addc_co_u32_e32 v67, vcc, 0, v119, vcc
	v_add_co_u32_e32 v74, vcc, 0x10000, v118
	global_load_dwordx4 v[58:61], v[118:119], off nt
	global_load_dwordx4 v[62:65], v[66:67], off nt
	v_addc_co_u32_e32 v75, vcc, 0, v119, vcc
	v_add_co_u32_e32 v76, vcc, 0x18000, v118
	v_add_u32_e32 v57, 0x400, v29
	s_nop 0
	v_addc_co_u32_e32 v77, vcc, 0, v119, vcc
	v_add_co_u32_e32 v82, vcc, 0x20000, v118
	global_load_dwordx4 v[66:69], v[74:75], off nt
	global_load_dwordx4 v[70:73], v[76:77], off nt
	v_addc_co_u32_e32 v83, vcc, 0, v119, vcc
	v_add_co_u32_e32 v84, vcc, 0x28000, v118
	s_lshl_b32 s4, s7, 1
	s_nop 0
	v_addc_co_u32_e32 v85, vcc, 0, v119, vcc
	v_add_co_u32_e32 v90, vcc, 0x30000, v118
	global_load_dwordx4 v[74:77], v[82:83], off nt
	global_load_dwordx4 v[78:81], v[84:85], off nt
	v_addc_co_u32_e32 v91, vcc, 0, v119, vcc
	v_add_co_u32_e32 v92, vcc, 0x38000, v118
	s_nop 1
	v_addc_co_u32_e32 v93, vcc, 0, v119, vcc
	v_add_co_u32_e32 v98, vcc, 0x40000, v118
	global_load_dwordx4 v[82:85], v[90:91], off nt
	global_load_dwordx4 v[86:89], v[92:93], off nt
	v_addc_co_u32_e32 v99, vcc, 0, v119, vcc
	v_add_co_u32_e32 v100, vcc, 0x48000, v118
	s_nop 1
	v_addc_co_u32_e32 v101, vcc, 0, v119, vcc
	v_add_co_u32_e32 v106, vcc, 0x50000, v118
	global_load_dwordx4 v[90:93], v[98:99], off nt
	global_load_dwordx4 v[94:97], v[100:101], off nt
	v_addc_co_u32_e32 v107, vcc, 0, v119, vcc
	v_add_co_u32_e32 v108, vcc, 0x58000, v118
	s_nop 1
	v_addc_co_u32_e32 v109, vcc, 0, v119, vcc
	global_load_dwordx4 v[98:101], v[106:107], off nt
	global_load_dwordx4 v[102:105], v[108:109], off nt
	v_add_co_u32_e32 v114, vcc, 0x60000, v118
	s_nop 1
	v_addc_co_u32_e32 v115, vcc, 0, v119, vcc
	v_add_co_u32_e32 v116, vcc, 0x68000, v118
	s_nop 1
	v_addc_co_u32_e32 v117, vcc, 0, v119, vcc
	global_load_dwordx4 v[106:109], v[114:115], off nt
	global_load_dwordx4 v[110:113], v[116:117], off nt
	v_add_co_u32_e32 v114, vcc, 0x70000, v118
	s_nop 1
	v_addc_co_u32_e32 v115, vcc, 0, v119, vcc
	global_load_dwordx4 v[114:117], v[114:115], off nt
	v_add_co_u32_e32 v118, vcc, 0x78000, v118
	s_nop 1
	v_addc_co_u32_e32 v119, vcc, 0, v119, vcc
	global_load_dwordx4 v[118:121], v[118:119], off nt
	s_waitcnt vmcnt(15)
	ds_write2_b32 v27, v58, v59 offset1:1
	ds_write2_b32 v27, v60, v61 offset0:2 offset1:3
	s_waitcnt vmcnt(14)
	ds_write2_b32 v37, v62, v63 offset1:1
	ds_write2_b32 v38, v64, v65 offset1:1
	s_waitcnt vmcnt(13)
	ds_write2_b32 v39, v66, v67 offset1:1
	ds_write2_b32 v40, v68, v69 offset1:1
	s_waitcnt vmcnt(12)
	ds_write2_b32 v41, v70, v71 offset1:1
	ds_write2_b32 v42, v72, v73 offset1:1
	s_waitcnt vmcnt(11)
	ds_write2_b32 v43, v74, v75 offset1:1
	ds_write2_b32 v44, v76, v77 offset1:1
	s_waitcnt vmcnt(10)
	ds_write2_b32 v45, v78, v79 offset1:1
	ds_write2_b32 v46, v80, v81 offset1:1
	s_waitcnt vmcnt(9)
	ds_write2_b32 v47, v82, v83 offset1:1
	ds_write2_b32 v48, v84, v85 offset1:1
	s_waitcnt vmcnt(8)
	ds_write2_b32 v49, v86, v87 offset1:1
	ds_write2_b32 v50, v88, v89 offset1:1
	s_waitcnt vmcnt(7)
	ds_write2_b32 v51, v90, v91 offset1:1
	ds_write2_b32 v52, v92, v93 offset1:1
	s_waitcnt vmcnt(6)
	ds_write2_b32 v53, v94, v95 offset1:1
	ds_write2_b32 v54, v96, v97 offset1:1
	s_waitcnt vmcnt(5)
	ds_write2_b32 v55, v98, v99 offset1:1
	ds_write2_b32 v56, v100, v101 offset1:1
	s_waitcnt vmcnt(4)
	ds_write2_b32 v0, v102, v103 offset1:1
	v_add_u32_e32 v0, 0x2cb8, v27
	ds_write2_b32 v0, v104, v105 offset1:1
	v_add_u32_e32 v0, 0x30c0, v27
	v_lshl_add_u64 v[78:79], v[4:5], 0, s[4:5]
	s_waitcnt vmcnt(3)
	ds_write2_b32 v0, v106, v107 offset1:1
	v_add_u32_e32 v0, 0x30c8, v27
	ds_write2_b32 v0, v108, v109 offset1:1
	v_add_u32_e32 v0, 0x34d0, v27
	s_waitcnt vmcnt(2)
	ds_write2_b32 v0, v110, v111 offset1:1
	v_add_u32_e32 v0, 0x34d8, v27
	ds_write2_b32 v0, v112, v113 offset1:1
	v_add_u32_e32 v0, 0x38e0, v27
	s_waitcnt vmcnt(1)
	ds_write2_b32 v0, v114, v115 offset1:1
	v_add_u32_e32 v0, 0x38e8, v27
	ds_write2_b32 v0, v116, v117 offset1:1
	v_add_u32_e32 v0, 0x3cf0, v27
	s_waitcnt vmcnt(0)
	ds_write2_b32 v0, v118, v119 offset1:1
	v_add_u32_e32 v0, 0x3cf8, v27
	ds_write2_b32 v0, v120, v121 offset1:1
	s_waitcnt lgkmcnt(0)
	ds_read2_b32 v[62:63], v29 offset0:65 offset1:73
	ds_read2_b32 v[64:65], v29 offset1:8
	ds_read2_b32 v[66:67], v29 offset0:130 offset1:138
	ds_read2_b32 v[68:69], v29 offset0:195 offset1:203
	ds_read2_b32 v[70:71], v57 offset0:4 offset1:12
	ds_read2_b32 v[72:73], v57 offset0:69 offset1:77
	ds_read2_b32 v[74:75], v57 offset0:134 offset1:142
	ds_read2_b32 v[76:77], v57 offset0:199 offset1:207
	v_or_b32_e32 v0, s6, v28
	v_lshlrev_b32_e32 v0, 14, v0
	s_waitcnt lgkmcnt(6)
	v_cvt_pk_bf16_f32 v58, v64, v62
	s_waitcnt lgkmcnt(4)
	v_cvt_pk_bf16_f32 v59, v66, v68
	s_waitcnt lgkmcnt(2)
	v_cvt_pk_bf16_f32 v60, v70, v72
	s_waitcnt lgkmcnt(0)
; __device__ __forceinline__ unsigned cvt_pk_bf16(float lo, float hi) { f32x2_t v = {lo, hi}; bf16x2_t b = __builtin_convertvector(v, bf16x2_t); return __builtin_bit_cast(unsigned, b); }
; #define LAS __attribute__((address_space(3)))
; __device__ __forceinline__ void transpose_item(const float* W, int K, int N, bf16* WT, LAS float* scr, int item, int lane) {
;     ...
;     for (int i = 0; i < 16; ++i) v[i] = __builtin_nontemporal_load((const f32x4*)(W + (size_t)(k0 + 4 * i + (lane >> 4)) * N + n0 + (lane & 15) * 4));
; #pragma unroll
;     for (int i = 0; i < 16; ++i) { LAS float* d = scr + (4 * i + (lane >> 4)) * 65 + (lane & 15) * 4; d[0] = v[i].x; d[1] = v[i].y; d[2] = v[i].z; d[3] = v[i].w; }
;     asm volatile("s_waitcnt lgkmcnt(0)" ::: "memory");
;     const int c = lane & 7;
; #pragma unroll
;     for (int j = 0; j < 8; ++j) { const int n = (lane >> 3) + 8 * j; const LAS float* s = scr + (8 * c) * 65 + n;
;         v4u o; o.x = pg8::cvt_pk_bf16(s[0 * 65], s[1 * 65]); o.y = pg8::cvt_pk_bf16(s[2 * 65], s[3 * 65]); o.z = pg8::cvt_pk_bf16(s[4 * 65], s[5 * 65]); o.w = pg8::cvt_pk_bf16(s[6 * 65], s[7 * 65]);
;         *(v4u*)(WT + (size_t)(n0 + n) * K + k0 + 8 * c) = o; }
;     asm volatile("s_waitcnt lgkmcnt(0)" ::: "memory");
; }
; __global__ void __launch_bounds__(NTHR, 2) mega_fwd(Args args) {
;     ...
;             if (r < I_1) { transpose_item(w_mlp_in, DM, FF, W1, scr, r, lane); continue; } r -= I_1;
;             transpose_item(w_mlp_out, FF, DM, W2, scr, r, lane);
	v_cvt_pk_bf16_f32 v61, v74, v76
	v_lshl_add_u64 v[80:81], v[78:79], 0, v[0:1]
	global_store_dwordx4 v[80:81], v[58:61], off sc1
	v_or_b32_e32 v0, s6, v30
	v_lshlrev_b32_e32 v0, 14, v0
	v_cvt_pk_bf16_f32 v58, v65, v63
	v_cvt_pk_bf16_f32 v59, v67, v69
	v_cvt_pk_bf16_f32 v60, v71, v73
	v_cvt_pk_bf16_f32 v61, v75, v77
	ds_read2_b32 v[64:65], v29 offset0:81 offset1:89
	ds_read2_b32 v[66:67], v29 offset0:16 offset1:24
	ds_read2_b32 v[68:69], v29 offset0:146 offset1:154
	ds_read2_b32 v[70:71], v29 offset0:211 offset1:219
	ds_read2_b32 v[72:73], v57 offset0:20 offset1:28
	ds_read2_b32 v[74:75], v57 offset0:85 offset1:93
	ds_read2_b32 v[76:77], v57 offset0:150 offset1:158
	ds_read2_b32 v[80:81], v57 offset0:215 offset1:223
	v_lshl_add_u64 v[62:63], v[78:79], 0, v[0:1]
	v_or_b32_e32 v0, s6, v31
	v_lshlrev_b32_e32 v0, 14, v0
	global_store_dwordx4 v[62:63], v[58:61], off sc1
	v_lshl_add_u64 v[62:63], v[78:79], 0, v[0:1]
	v_or_b32_e32 v0, s6, v32
	s_waitcnt lgkmcnt(6)
	v_cvt_pk_bf16_f32 v58, v66, v64
	s_waitcnt lgkmcnt(4)
	v_cvt_pk_bf16_f32 v59, v68, v70
	s_waitcnt lgkmcnt(2)
	v_cvt_pk_bf16_f32 v60, v72, v74
	s_waitcnt lgkmcnt(0)
	v_cvt_pk_bf16_f32 v61, v76, v80
	global_store_dwordx4 v[62:63], v[58:61], off sc1
	v_lshlrev_b32_e32 v0, 14, v0
	v_lshl_add_u64 v[62:63], v[78:79], 0, v[0:1]
	v_cvt_pk_bf16_f32 v58, v67, v65
	v_cvt_pk_bf16_f32 v59, v69, v71
	v_cvt_pk_bf16_f32 v60, v73, v75
	v_cvt_pk_bf16_f32 v61, v77, v81
	ds_read2_b32 v[64:65], v29 offset0:32 offset1:40
	ds_read2_b32 v[66:67], v29 offset0:97 offset1:105
	ds_read2_b32 v[68:69], v29 offset0:162 offset1:170
	ds_read2_b32 v[70:71], v29 offset0:227 offset1:235
	ds_read2_b32 v[72:73], v57 offset0:36 offset1:44
	ds_read2_b32 v[74:75], v57 offset0:101 offset1:109
	ds_read2_b32 v[76:77], v57 offset0:166 offset1:174
	ds_read2_b32 v[80:81], v57 offset0:231 offset1:239
	v_or_b32_e32 v0, s6, v33
	v_lshlrev_b32_e32 v0, 14, v0
	global_store_dwordx4 v[62:63], v[58:61], off sc1
	v_lshl_add_u64 v[62:63], v[78:79], 0, v[0:1]
	v_or_b32_e32 v0, s6, v34
	s_waitcnt lgkmcnt(6)
	v_cvt_pk_bf16_f32 v58, v64, v66
	s_waitcnt lgkmcnt(4)
	v_cvt_pk_bf16_f32 v59, v68, v70
	s_waitcnt lgkmcnt(2)
	v_cvt_pk_bf16_f32 v60, v72, v74
	s_waitcnt lgkmcnt(0)
	v_cvt_pk_bf16_f32 v61, v76, v80
	global_store_dwordx4 v[62:63], v[58:61], off sc1
	v_lshlrev_b32_e32 v0, 14, v0
	v_lshl_add_u64 v[62:63], v[78:79], 0, v[0:1]
	v_cvt_pk_bf16_f32 v58, v65, v67
	v_cvt_pk_bf16_f32 v59, v69, v71
	v_cvt_pk_bf16_f32 v60, v73, v75
	v_cvt_pk_bf16_f32 v61, v77, v81
	ds_read2_b32 v[64:65], v29 offset0:48 offset1:56
	ds_read2_b32 v[66:67], v29 offset0:113 offset1:121
	ds_read2_b32 v[68:69], v29 offset0:178 offset1:186
	ds_read2_b32 v[70:71], v29 offset0:243 offset1:251
	ds_read2_b32 v[72:73], v57 offset0:52 offset1:60
	ds_read2_b32 v[74:75], v57 offset0:117 offset1:125
	ds_read2_b32 v[76:77], v57 offset0:182 offset1:190
	ds_read2_b32 v[80:81], v57 offset0:247 offset1:255
	v_or_b32_e32 v0, s6, v35
	v_lshlrev_b32_e32 v0, 14, v0
	global_store_dwordx4 v[62:63], v[58:61], off sc1
	v_lshl_add_u64 v[62:63], v[78:79], 0, v[0:1]
	v_or_b32_e32 v0, s6, v36
	s_waitcnt lgkmcnt(6)
	v_cvt_pk_bf16_f32 v58, v64, v66
	s_waitcnt lgkmcnt(4)
	v_cvt_pk_bf16_f32 v59, v68, v70
	s_waitcnt lgkmcnt(2)
	v_cvt_pk_bf16_f32 v60, v72, v74
	s_waitcnt lgkmcnt(0)
	v_cvt_pk_bf16_f32 v61, v76, v80
	v_lshlrev_b32_e32 v0, 14, v0
	global_store_dwordx4 v[62:63], v[58:61], off sc1
	v_lshl_add_u64 v[62:63], v[78:79], 0, v[0:1]
	s_mov_b64 s[6:7], 0
	v_cvt_pk_bf16_f32 v58, v65, v67
	v_cvt_pk_bf16_f32 v59, v69, v71
	v_cvt_pk_bf16_f32 v60, v73, v75
	v_cvt_pk_bf16_f32 v61, v77, v81
	global_store_dwordx4 v[62:63], v[58:61], off sc1
	s_waitcnt lgkmcnt(0)
.LBB0_38:
	s_andn2_b64 vcc, exec, s[6:7]
	s_cbranch_vccnz .LBB0_40
	s_add_i32 s4, s10, 0xe600
	s_lshr_b32 s4, s4, 1
	s_and_b32 s7, s4, 0x7fc0
	s_and_b32 s6, s11, 0x1fc0
	v_or_b32_e32 v0, s7, v26
	s_lshl_b32 s4, s6, 2
	v_lshl_add_u64 v[58:59], v[6:7], 0, s[4:5]
	v_lshlrev_b32_e32 v0, 15, v0
	v_lshl_add_u64 v[118:119], v[58:59], 0, v[0:1]
	v_add_co_u32_e32 v66, vcc, 0x20000, v118
	v_add_u32_e32 v0, 0x2cb0, v27
	s_nop 0
	v_addc_co_u32_e32 v67, vcc, 0, v119, vcc
	v_add_co_u32_e32 v74, vcc, 0x40000, v118
	global_load_dwordx4 v[58:61], v[118:119], off nt
	global_load_dwordx4 v[62:65], v[66:67], off nt
	v_addc_co_u32_e32 v75, vcc, 0, v119, vcc
	v_add_co_u32_e32 v76, vcc, 0x60000, v118
	v_add_u32_e32 v57, 0x400, v29
	s_nop 0
	v_addc_co_u32_e32 v77, vcc, 0, v119, vcc
	v_add_co_u32_e32 v82, vcc, 0x80000, v118
	global_load_dwordx4 v[66:69], v[74:75], off nt
	global_load_dwordx4 v[70:73], v[76:77], off nt
	v_addc_co_u32_e32 v83, vcc, 0, v119, vcc
	v_add_co_u32_e32 v84, vcc, 0xa0000, v118
	s_lshl_b32 s4, s7, 1
	s_nop 0
	v_addc_co_u32_e32 v85, vcc, 0, v119, vcc
	v_add_co_u32_e32 v90, vcc, 0xc0000, v118
	global_load_dwordx4 v[74:77], v[82:83], off nt
	global_load_dwordx4 v[78:81], v[84:85], off nt
	v_addc_co_u32_e32 v91, vcc, 0, v119, vcc
	v_add_co_u32_e32 v92, vcc, 0xe0000, v118
	s_nop 1
	v_addc_co_u32_e32 v93, vcc, 0, v119, vcc
	v_add_co_u32_e32 v98, vcc, 0x100000, v118
	global_load_dwordx4 v[82:85], v[90:91], off nt
	global_load_dwordx4 v[86:89], v[92:93], off nt
	v_addc_co_u32_e32 v99, vcc, 0, v119, vcc
	v_add_co_u32_e32 v100, vcc, 0x120000, v118
	s_nop 1
	v_addc_co_u32_e32 v101, vcc, 0, v119, vcc
	v_add_co_u32_e32 v106, vcc, 0x140000, v118
	global_load_dwordx4 v[90:93], v[98:99], off nt
	global_load_dwordx4 v[94:97], v[100:101], off nt
	v_addc_co_u32_e32 v107, vcc, 0, v119, vcc
	v_add_co_u32_e32 v108, vcc, 0x160000, v118
	s_nop 1
	v_addc_co_u32_e32 v109, vcc, 0, v119, vcc
	global_load_dwordx4 v[98:101], v[106:107], off nt
	global_load_dwordx4 v[102:105], v[108:109], off nt
	v_add_co_u32_e32 v114, vcc, 0x180000, v118
	s_nop 1
	v_addc_co_u32_e32 v115, vcc, 0, v119, vcc
	v_add_co_u32_e32 v116, vcc, 0x1a0000, v118
	s_nop 1
	v_addc_co_u32_e32 v117, vcc, 0, v119, vcc
	global_load_dwordx4 v[106:109], v[114:115], off nt
	global_load_dwordx4 v[110:113], v[116:117], off nt
	v_add_co_u32_e32 v114, vcc, 0x1c0000, v118
	s_nop 1
	v_addc_co_u32_e32 v115, vcc, 0, v119, vcc
	global_load_dwordx4 v[114:117], v[114:115], off nt
	v_add_co_u32_e32 v118, vcc, 0x1e0000, v118
	s_nop 1
	v_addc_co_u32_e32 v119, vcc, 0, v119, vcc
	global_load_dwordx4 v[118:121], v[118:119], off nt
	s_waitcnt vmcnt(15)
; __device__ __forceinline__ unsigned cvt_pk_bf16(float lo, float hi) { f32x2_t v = {lo, hi}; bf16x2_t b = __builtin_convertvector(v, bf16x2_t); return __builtin_bit_cast(unsigned, b); }
; #define LAS __attribute__((address_space(3)))
; __device__ __forceinline__ void transpose_item(const float* W, int K, int N, bf16* WT, LAS float* scr, int item, int lane) {
;     ...
;     for (int i = 0; i < 16; ++i) v[i] = __builtin_nontemporal_load((const f32x4*)(W + (size_t)(k0 + 4 * i + (lane >> 4)) * N + n0 + (lane & 15) * 4));
; #pragma unroll
;     for (int i = 0; i < 16; ++i) { LAS float* d = scr + (4 * i + (lane >> 4)) * 65 + (lane & 15) * 4; d[0] = v[i].x; d[1] = v[i].y; d[2] = v[i].z; d[3] = v[i].w; }
;     asm volatile("s_waitcnt lgkmcnt(0)" ::: "memory");
;     const int c = lane & 7;
; #pragma unroll
;     for (int j = 0; j < 8; ++j) { const int n = (lane >> 3) + 8 * j; const LAS float* s = scr + (8 * c) * 65 + n;
;         v4u o; o.x = pg8::cvt_pk_bf16(s[0 * 65], s[1 * 65]); o.y = pg8::cvt_pk_bf16(s[2 * 65], s[3 * 65]); o.z = pg8::cvt_pk_bf16(s[4 * 65], s[5 * 65]); o.w = pg8::cvt_pk_bf16(s[6 * 65], s[7 * 65]);
;         *(v4u*)(WT + (size_t)(n0 + n) * K + k0 + 8 * c) = o; }
;     asm volatile("s_waitcnt lgkmcnt(0)" ::: "memory");
; }
	ds_write2_b32 v27, v58, v59 offset1:1
	ds_write2_b32 v27, v60, v61 offset0:2 offset1:3
	s_waitcnt vmcnt(14)
	ds_write2_b32 v37, v62, v63 offset1:1
	ds_write2_b32 v38, v64, v65 offset1:1
	s_waitcnt vmcnt(13)
	ds_write2_b32 v39, v66, v67 offset1:1
	ds_write2_b32 v40, v68, v69 offset1:1
	s_waitcnt vmcnt(12)
	ds_write2_b32 v41, v70, v71 offset1:1
	ds_write2_b32 v42, v72, v73 offset1:1
	s_waitcnt vmcnt(11)
	ds_write2_b32 v43, v74, v75 offset1:1
	ds_write2_b32 v44, v76, v77 offset1:1
	s_waitcnt vmcnt(10)
	ds_write2_b32 v45, v78, v79 offset1:1
	ds_write2_b32 v46, v80, v81 offset1:1
	s_waitcnt vmcnt(9)
	ds_write2_b32 v47, v82, v83 offset1:1
	ds_write2_b32 v48, v84, v85 offset1:1
	s_waitcnt vmcnt(8)
	ds_write2_b32 v49, v86, v87 offset1:1
	ds_write2_b32 v50, v88, v89 offset1:1
	s_waitcnt vmcnt(7)
	ds_write2_b32 v51, v90, v91 offset1:1
	ds_write2_b32 v52, v92, v93 offset1:1
	s_waitcnt vmcnt(6)
	ds_write2_b32 v53, v94, v95 offset1:1
	ds_write2_b32 v54, v96, v97 offset1:1
	s_waitcnt vmcnt(5)
	ds_write2_b32 v55, v98, v99 offset1:1
	ds_write2_b32 v56, v100, v101 offset1:1
	s_waitcnt vmcnt(4)
	ds_write2_b32 v0, v102, v103 offset1:1
	v_add_u32_e32 v0, 0x2cb8, v27
	ds_write2_b32 v0, v104, v105 offset1:1
	v_add_u32_e32 v0, 0x30c0, v27
	v_lshl_add_u64 v[78:79], v[8:9], 0, s[4:5]
	s_waitcnt vmcnt(3)
	ds_write2_b32 v0, v106, v107 offset1:1
	v_add_u32_e32 v0, 0x30c8, v27
	ds_write2_b32 v0, v108, v109 offset1:1
	v_add_u32_e32 v0, 0x34d0, v27
	s_waitcnt vmcnt(2)
	ds_write2_b32 v0, v110, v111 offset1:1
	v_add_u32_e32 v0, 0x34d8, v27
	ds_write2_b32 v0, v112, v113 offset1:1
	v_add_u32_e32 v0, 0x38e0, v27
	s_waitcnt vmcnt(1)
	ds_write2_b32 v0, v114, v115 offset1:1
	v_add_u32_e32 v0, 0x38e8, v27
	ds_write2_b32 v0, v116, v117 offset1:1
	v_add_u32_e32 v0, 0x3cf0, v27
	s_waitcnt vmcnt(0)
	ds_write2_b32 v0, v118, v119 offset1:1
	v_add_u32_e32 v0, 0x3cf8, v27
	ds_write2_b32 v0, v120, v121 offset1:1
	s_waitcnt lgkmcnt(0)
	ds_read2_b32 v[62:63], v29 offset0:65 offset1:73
	ds_read2_b32 v[64:65], v29 offset1:8
	ds_read2_b32 v[66:67], v29 offset0:130 offset1:138
	ds_read2_b32 v[68:69], v29 offset0:195 offset1:203
	ds_read2_b32 v[70:71], v57 offset0:4 offset1:12
	ds_read2_b32 v[72:73], v57 offset0:69 offset1:77
	ds_read2_b32 v[74:75], v57 offset0:134 offset1:142
	ds_read2_b32 v[76:77], v57 offset0:199 offset1:207
	v_or_b32_e32 v0, s6, v28
	v_lshlrev_b32_e32 v0, 12, v0
	s_waitcnt lgkmcnt(6)
	v_cvt_pk_bf16_f32 v58, v64, v62
	s_waitcnt lgkmcnt(4)
	v_cvt_pk_bf16_f32 v59, v66, v68
	s_waitcnt lgkmcnt(2)
	v_cvt_pk_bf16_f32 v60, v70, v72
	s_waitcnt lgkmcnt(0)
	v_cvt_pk_bf16_f32 v61, v74, v76
	v_lshl_add_u64 v[80:81], v[78:79], 0, v[0:1]
	global_store_dwordx4 v[80:81], v[58:61], off sc1
	v_or_b32_e32 v0, s6, v30
	v_lshlrev_b32_e32 v0, 12, v0
	v_cvt_pk_bf16_f32 v58, v65, v63
	v_cvt_pk_bf16_f32 v59, v67, v69
	v_cvt_pk_bf16_f32 v60, v71, v73
	v_cvt_pk_bf16_f32 v61, v75, v77
	ds_read2_b32 v[64:65], v29 offset0:81 offset1:89
	ds_read2_b32 v[66:67], v29 offset0:16 offset1:24
	ds_read2_b32 v[68:69], v29 offset0:146 offset1:154
	ds_read2_b32 v[70:71], v29 offset0:211 offset1:219
	ds_read2_b32 v[72:73], v57 offset0:20 offset1:28
	ds_read2_b32 v[74:75], v57 offset0:85 offset1:93
	ds_read2_b32 v[76:77], v57 offset0:150 offset1:158
	ds_read2_b32 v[80:81], v57 offset0:215 offset1:223
	v_lshl_add_u64 v[62:63], v[78:79], 0, v[0:1]
	v_or_b32_e32 v0, s6, v31
	v_lshlrev_b32_e32 v0, 12, v0
	global_store_dwordx4 v[62:63], v[58:61], off sc1
	v_lshl_add_u64 v[62:63], v[78:79], 0, v[0:1]
	v_or_b32_e32 v0, s6, v32
	s_waitcnt lgkmcnt(6)
	v_cvt_pk_bf16_f32 v58, v66, v64
	s_waitcnt lgkmcnt(4)
	v_cvt_pk_bf16_f32 v59, v68, v70
	s_waitcnt lgkmcnt(2)
	v_cvt_pk_bf16_f32 v60, v72, v74
	s_waitcnt lgkmcnt(0)
	v_cvt_pk_bf16_f32 v61, v76, v80
	global_store_dwordx4 v[62:63], v[58:61], off sc1
	v_lshlrev_b32_e32 v0, 12, v0
	v_lshl_add_u64 v[62:63], v[78:79], 0, v[0:1]
	v_cvt_pk_bf16_f32 v58, v67, v65
	v_cvt_pk_bf16_f32 v59, v69, v71
	v_cvt_pk_bf16_f32 v60, v73, v75
	v_cvt_pk_bf16_f32 v61, v77, v81
	ds_read2_b32 v[64:65], v29 offset0:32 offset1:40
	ds_read2_b32 v[66:67], v29 offset0:97 offset1:105
	ds_read2_b32 v[68:69], v29 offset0:162 offset1:170
	ds_read2_b32 v[70:71], v29 offset0:227 offset1:235
	ds_read2_b32 v[72:73], v57 offset0:36 offset1:44
	ds_read2_b32 v[74:75], v57 offset0:101 offset1:109
	ds_read2_b32 v[76:77], v57 offset0:166 offset1:174
	ds_read2_b32 v[80:81], v57 offset0:231 offset1:239
	v_or_b32_e32 v0, s6, v33
	v_lshlrev_b32_e32 v0, 12, v0
	global_store_dwordx4 v[62:63], v[58:61], off sc1
	v_lshl_add_u64 v[62:63], v[78:79], 0, v[0:1]
	v_or_b32_e32 v0, s6, v34
	s_waitcnt lgkmcnt(6)
	v_cvt_pk_bf16_f32 v58, v64, v66
	s_waitcnt lgkmcnt(4)
	v_cvt_pk_bf16_f32 v59, v68, v70
	s_waitcnt lgkmcnt(2)
	v_cvt_pk_bf16_f32 v60, v72, v74
	s_waitcnt lgkmcnt(0)
	v_cvt_pk_bf16_f32 v61, v76, v80
	global_store_dwordx4 v[62:63], v[58:61], off sc1
	v_lshlrev_b32_e32 v0, 12, v0
	v_lshl_add_u64 v[62:63], v[78:79], 0, v[0:1]
	v_cvt_pk_bf16_f32 v58, v65, v67
	v_cvt_pk_bf16_f32 v59, v69, v71
	v_cvt_pk_bf16_f32 v60, v73, v75
	v_cvt_pk_bf16_f32 v61, v77, v81
	ds_read2_b32 v[64:65], v29 offset0:48 offset1:56
	ds_read2_b32 v[66:67], v29 offset0:113 offset1:121
	ds_read2_b32 v[68:69], v29 offset0:178 offset1:186
	ds_read2_b32 v[70:71], v29 offset0:243 offset1:251
	ds_read2_b32 v[72:73], v57 offset0:52 offset1:60
	ds_read2_b32 v[74:75], v57 offset0:117 offset1:125
	ds_read2_b32 v[76:77], v57 offset0:182 offset1:190
	ds_read2_b32 v[80:81], v57 offset0:247 offset1:255
	v_or_b32_e32 v0, s6, v35
	v_lshlrev_b32_e32 v0, 12, v0
	global_store_dwordx4 v[62:63], v[58:61], off sc1
	v_lshl_add_u64 v[62:63], v[78:79], 0, v[0:1]
	v_or_b32_e32 v0, s6, v36
	s_waitcnt lgkmcnt(6)
	v_cvt_pk_bf16_f32 v58, v64, v66
	s_waitcnt lgkmcnt(4)
	v_cvt_pk_bf16_f32 v59, v68, v70
	s_waitcnt lgkmcnt(2)
	v_cvt_pk_bf16_f32 v60, v72, v74
	s_waitcnt lgkmcnt(0)
	v_cvt_pk_bf16_f32 v61, v76, v80
	v_lshlrev_b32_e32 v0, 12, v0
	global_store_dwordx4 v[62:63], v[58:61], off sc1
	v_lshl_add_u64 v[62:63], v[78:79], 0, v[0:1]
	s_nop 0
	v_cvt_pk_bf16_f32 v58, v65, v67
	v_cvt_pk_bf16_f32 v59, v69, v71
	v_cvt_pk_bf16_f32 v60, v73, v75
	v_cvt_pk_bf16_f32 v61, v77, v81
	global_store_dwordx4 v[62:63], v[58:61], off sc1
	s_waitcnt lgkmcnt(0)

; #define LAS __attribute__((address_space(3)))
; __device__ __forceinline__ void transpose_item(const float* W, int K, int N, bf16* WT, LAS float* scr, int item, int lane) {
;     ...
;     for (int i = 0; i < 16; ++i) v[i] = __builtin_nontemporal_load((const f32x4*)(W + (size_t)(k0 + 4 * i + (lane >> 4)) * N + n0 + (lane & 15) * 4));
; #pragma unroll
;     for (int i = 0; i < 16; ++i) { LAS float* d = scr + (4 * i + (lane >> 4)) * 65 + (lane & 15) * 4; d[0] = v[i].x; d[1] = v[i].y; d[2] = v[i].z; d[3] = v[i].w; }
;     asm volatile("s_waitcnt lgkmcnt(0)" ::: "memory");
;     const int c = lane & 7;
; __global__ void __launch_bounds__(NTHR, 2) mega_fwd(Args args) {
;     ...
;             if (r < I_O) { transpose_item(w_out, DM, DM, WO, scr, r, lane); continue; } r -= I_O;
.LBB0_41:
	s_andn2_b64 vcc, exec, s[6:7]
	s_cbranch_vccnz .LBB0_43
	s_add_i32 s4, s18, 0x2800
	s_and_b32 s7, s4, 0x1ffc0
	s_and_b32 s6, s11, 0x7c0
	v_or_b32_e32 v0, s7, v26
	s_lshl_b32 s4, s6, 2
	v_lshl_add_u64 v[58:59], v[10:11], 0, s[4:5]
	v_lshlrev_b32_e32 v0, 13, v0
	v_lshl_add_u64 v[118:119], v[58:59], 0, v[0:1]
	v_add_co_u32_e32 v66, vcc, 0x8000, v118
	v_add_u32_e32 v0, 0x2cb0, v27
	s_nop 0
	v_addc_co_u32_e32 v67, vcc, 0, v119, vcc
	v_add_co_u32_e32 v74, vcc, 0x10000, v118
	global_load_dwordx4 v[58:61], v[118:119], off nt
	global_load_dwordx4 v[62:65], v[66:67], off nt
	v_addc_co_u32_e32 v75, vcc, 0, v119, vcc
	v_add_co_u32_e32 v76, vcc, 0x18000, v118
	v_add_u32_e32 v57, 0x400, v29
	s_nop 0
	v_addc_co_u32_e32 v77, vcc, 0, v119, vcc
	v_add_co_u32_e32 v82, vcc, 0x20000, v118
	global_load_dwordx4 v[66:69], v[74:75], off nt
	global_load_dwordx4 v[70:73], v[76:77], off nt
	v_addc_co_u32_e32 v83, vcc, 0, v119, vcc
	v_add_co_u32_e32 v84, vcc, 0x28000, v118
	s_lshl_b32 s4, s7, 1
	s_nop 0
	v_addc_co_u32_e32 v85, vcc, 0, v119, vcc
	v_add_co_u32_e32 v90, vcc, 0x30000, v118
	global_load_dwordx4 v[74:77], v[82:83], off nt
	global_load_dwordx4 v[78:81], v[84:85], off nt
	v_addc_co_u32_e32 v91, vcc, 0, v119, vcc
	v_add_co_u32_e32 v92, vcc, 0x38000, v118
	s_nop 1
	v_addc_co_u32_e32 v93, vcc, 0, v119, vcc
	v_add_co_u32_e32 v98, vcc, 0x40000, v118
	global_load_dwordx4 v[82:85], v[90:91], off nt
	global_load_dwordx4 v[86:89], v[92:93], off nt
	v_addc_co_u32_e32 v99, vcc, 0, v119, vcc
	v_add_co_u32_e32 v100, vcc, 0x48000, v118
	s_nop 1
	v_addc_co_u32_e32 v101, vcc, 0, v119, vcc
	v_add_co_u32_e32 v106, vcc, 0x50000, v118
	global_load_dwordx4 v[90:93], v[98:99], off nt
	global_load_dwordx4 v[94:97], v[100:101], off nt
	v_addc_co_u32_e32 v107, vcc, 0, v119, vcc
	v_add_co_u32_e32 v108, vcc, 0x58000, v118
	s_nop 1
	v_addc_co_u32_e32 v109, vcc, 0, v119, vcc
	global_load_dwordx4 v[98:101], v[106:107], off nt
	global_load_dwordx4 v[102:105], v[108:109], off nt
	v_add_co_u32_e32 v114, vcc, 0x60000, v118
	s_nop 1
	v_addc_co_u32_e32 v115, vcc, 0, v119, vcc
	v_add_co_u32_e32 v116, vcc, 0x68000, v118
	s_nop 1
	v_addc_co_u32_e32 v117, vcc, 0, v119, vcc
	global_load_dwordx4 v[106:109], v[114:115], off nt
	global_load_dwordx4 v[110:113], v[116:117], off nt
	v_add_co_u32_e32 v114, vcc, 0x70000, v118
	s_nop 1
	v_addc_co_u32_e32 v115, vcc, 0, v119, vcc
	global_load_dwordx4 v[114:117], v[114:115], off nt
	v_add_co_u32_e32 v118, vcc, 0x78000, v118
	s_nop 1
	v_addc_co_u32_e32 v119, vcc, 0, v119, vcc
	global_load_dwordx4 v[118:121], v[118:119], off nt
	s_waitcnt vmcnt(15)
	ds_write2_b32 v27, v58, v59 offset1:1
	ds_write2_b32 v27, v60, v61 offset0:2 offset1:3
	s_waitcnt vmcnt(14)
	ds_write2_b32 v37, v62, v63 offset1:1
	ds_write2_b32 v38, v64, v65 offset1:1
	s_waitcnt vmcnt(13)
	ds_write2_b32 v39, v66, v67 offset1:1
	ds_write2_b32 v40, v68, v69 offset1:1
	s_waitcnt vmcnt(12)
	ds_write2_b32 v41, v70, v71 offset1:1
	ds_write2_b32 v42, v72, v73 offset1:1
	s_waitcnt vmcnt(11)
	ds_write2_b32 v43, v74, v75 offset1:1
	ds_write2_b32 v44, v76, v77 offset1:1
	s_waitcnt vmcnt(10)
	ds_write2_b32 v45, v78, v79 offset1:1
	ds_write2_b32 v46, v80, v81 offset1:1
	s_waitcnt vmcnt(9)
	ds_write2_b32 v47, v82, v83 offset1:1
	ds_write2_b32 v48, v84, v85 offset1:1
	s_waitcnt vmcnt(8)
	ds_write2_b32 v49, v86, v87 offset1:1
	ds_write2_b32 v50, v88, v89 offset1:1
	s_waitcnt vmcnt(7)
	ds_write2_b32 v51, v90, v91 offset1:1
	ds_write2_b32 v52, v92, v93 offset1:1
	s_waitcnt vmcnt(6)
	ds_write2_b32 v53, v94, v95 offset1:1
	ds_write2_b32 v54, v96, v97 offset1:1
	s_waitcnt vmcnt(5)
	ds_write2_b32 v55, v98, v99 offset1:1
	ds_write2_b32 v56, v100, v101 offset1:1
	s_waitcnt vmcnt(4)
	ds_write2_b32 v0, v102, v103 offset1:1
	v_add_u32_e32 v0, 0x2cb8, v27
	ds_write2_b32 v0, v104, v105 offset1:1
	v_add_u32_e32 v0, 0x30c0, v27
	v_lshl_add_u64 v[78:79], v[12:13], 0, s[4:5]
	s_waitcnt vmcnt(3)
	ds_write2_b32 v0, v106, v107 offset1:1
	v_add_u32_e32 v0, 0x30c8, v27
	ds_write2_b32 v0, v108, v109 offset1:1
	v_add_u32_e32 v0, 0x34d0, v27
	s_waitcnt vmcnt(2)
	ds_write2_b32 v0, v110, v111 offset1:1
	v_add_u32_e32 v0, 0x34d8, v27
	ds_write2_b32 v0, v112, v113 offset1:1
	v_add_u32_e32 v0, 0x38e0, v27
	s_waitcnt vmcnt(1)
	ds_write2_b32 v0, v114, v115 offset1:1
	v_add_u32_e32 v0, 0x38e8, v27
	ds_write2_b32 v0, v116, v117 offset1:1
	v_add_u32_e32 v0, 0x3cf0, v27
	s_waitcnt vmcnt(0)
; __device__ __forceinline__ unsigned cvt_pk_bf16(float lo, float hi) { f32x2_t v = {lo, hi}; bf16x2_t b = __builtin_convertvector(v, bf16x2_t); return __builtin_bit_cast(unsigned, b); }
; #define LAS __attribute__((address_space(3)))
; __device__ __forceinline__ void transpose_item(const float* W, int K, int N, bf16* WT, LAS float* scr, int item, int lane) {
;     ...
;     const int c = lane & 7;
; #pragma unroll
;     for (int j = 0; j < 8; ++j) { const int n = (lane >> 3) + 8 * j; const LAS float* s = scr + (8 * c) * 65 + n;
;         v4u o; o.x = pg8::cvt_pk_bf16(s[0 * 65], s[1 * 65]); o.y = pg8::cvt_pk_bf16(s[2 * 65], s[3 * 65]); o.z = pg8::cvt_pk_bf16(s[4 * 65], s[5 * 65]); o.w = pg8::cvt_pk_bf16(s[6 * 65], s[7 * 65]);
;         *(v4u*)(WT + (size_t)(n0 + n) * K + k0 + 8 * c) = o; }
;     asm volatile("s_waitcnt lgkmcnt(0)" ::: "memory");
; }
	ds_write2_b32 v0, v118, v119 offset1:1
	v_add_u32_e32 v0, 0x3cf8, v27
	ds_write2_b32 v0, v120, v121 offset1:1
	s_waitcnt lgkmcnt(0)
	ds_read2_b32 v[62:63], v29 offset0:65 offset1:73
	ds_read2_b32 v[64:65], v29 offset1:8
	ds_read2_b32 v[66:67], v29 offset0:130 offset1:138
	ds_read2_b32 v[68:69], v29 offset0:195 offset1:203
	ds_read2_b32 v[70:71], v57 offset0:4 offset1:12
	ds_read2_b32 v[72:73], v57 offset0:69 offset1:77
	ds_read2_b32 v[74:75], v57 offset0:134 offset1:142
	ds_read2_b32 v[76:77], v57 offset0:199 offset1:207
	v_or_b32_e32 v0, s6, v28
	v_lshlrev_b32_e32 v0, 12, v0
	s_waitcnt lgkmcnt(6)
	v_cvt_pk_bf16_f32 v58, v64, v62
	s_waitcnt lgkmcnt(4)
	v_cvt_pk_bf16_f32 v59, v66, v68
	s_waitcnt lgkmcnt(2)
	v_cvt_pk_bf16_f32 v60, v70, v72
	s_waitcnt lgkmcnt(0)
	v_cvt_pk_bf16_f32 v61, v74, v76
	v_lshl_add_u64 v[80:81], v[78:79], 0, v[0:1]
	global_store_dwordx4 v[80:81], v[58:61], off sc1
	v_or_b32_e32 v0, s6, v30
	v_lshlrev_b32_e32 v0, 12, v0
	v_cvt_pk_bf16_f32 v58, v65, v63
	v_cvt_pk_bf16_f32 v59, v67, v69
	v_cvt_pk_bf16_f32 v60, v71, v73
	v_cvt_pk_bf16_f32 v61, v75, v77
	ds_read2_b32 v[64:65], v29 offset0:81 offset1:89
	ds_read2_b32 v[66:67], v29 offset0:16 offset1:24
	ds_read2_b32 v[68:69], v29 offset0:146 offset1:154
	ds_read2_b32 v[70:71], v29 offset0:211 offset1:219
	ds_read2_b32 v[72:73], v57 offset0:20 offset1:28
	ds_read2_b32 v[74:75], v57 offset0:85 offset1:93
	ds_read2_b32 v[76:77], v57 offset0:150 offset1:158
	ds_read2_b32 v[80:81], v57 offset0:215 offset1:223
	v_lshl_add_u64 v[62:63], v[78:79], 0, v[0:1]
	v_or_b32_e32 v0, s6, v31
	v_lshlrev_b32_e32 v0, 12, v0
	global_store_dwordx4 v[62:63], v[58:61], off sc1
	v_lshl_add_u64 v[62:63], v[78:79], 0, v[0:1]
	v_or_b32_e32 v0, s6, v32
	s_waitcnt lgkmcnt(6)
	v_cvt_pk_bf16_f32 v58, v66, v64
	s_waitcnt lgkmcnt(4)
	v_cvt_pk_bf16_f32 v59, v68, v70
	s_waitcnt lgkmcnt(2)
	v_cvt_pk_bf16_f32 v60, v72, v74
	s_waitcnt lgkmcnt(0)
	v_cvt_pk_bf16_f32 v61, v76, v80
	global_store_dwordx4 v[62:63], v[58:61], off sc1
	v_lshlrev_b32_e32 v0, 12, v0
	v_lshl_add_u64 v[62:63], v[78:79], 0, v[0:1]
	v_cvt_pk_bf16_f32 v58, v67, v65
	v_cvt_pk_bf16_f32 v59, v69, v71
	v_cvt_pk_bf16_f32 v60, v73, v75
	v_cvt_pk_bf16_f32 v61, v77, v81
	ds_read2_b32 v[64:65], v29 offset0:32 offset1:40
	ds_read2_b32 v[66:67], v29 offset0:97 offset1:105
	ds_read2_b32 v[68:69], v29 offset0:162 offset1:170
	ds_read2_b32 v[70:71], v29 offset0:227 offset1:235
	ds_read2_b32 v[72:73], v57 offset0:36 offset1:44
	ds_read2_b32 v[74:75], v57 offset0:101 offset1:109
	ds_read2_b32 v[76:77], v57 offset0:166 offset1:174
	ds_read2_b32 v[80:81], v57 offset0:231 offset1:239
	v_or_b32_e32 v0, s6, v33
	v_lshlrev_b32_e32 v0, 12, v0
	global_store_dwordx4 v[62:63], v[58:61], off sc1
	v_lshl_add_u64 v[62:63], v[78:79], 0, v[0:1]
	v_or_b32_e32 v0, s6, v34
	s_waitcnt lgkmcnt(6)
	v_cvt_pk_bf16_f32 v58, v64, v66
	s_waitcnt lgkmcnt(4)
	v_cvt_pk_bf16_f32 v59, v68, v70
	s_waitcnt lgkmcnt(2)
	v_cvt_pk_bf16_f32 v60, v72, v74
	s_waitcnt lgkmcnt(0)
	v_cvt_pk_bf16_f32 v61, v76, v80
	global_store_dwordx4 v[62:63], v[58:61], off sc1
	v_lshlrev_b32_e32 v0, 12, v0
	v_lshl_add_u64 v[62:63], v[78:79], 0, v[0:1]
	v_cvt_pk_bf16_f32 v58, v65, v67
	v_cvt_pk_bf16_f32 v59, v69, v71
	v_cvt_pk_bf16_f32 v60, v73, v75
	v_cvt_pk_bf16_f32 v61, v77, v81
	ds_read2_b32 v[64:65], v29 offset0:48 offset1:56
	ds_read2_b32 v[66:67], v29 offset0:113 offset1:121
	ds_read2_b32 v[68:69], v29 offset0:178 offset1:186
	ds_read2_b32 v[70:71], v29 offset0:243 offset1:251
	ds_read2_b32 v[72:73], v57 offset0:52 offset1:60
	ds_read2_b32 v[74:75], v57 offset0:117 offset1:125
	ds_read2_b32 v[76:77], v57 offset0:182 offset1:190
	ds_read2_b32 v[80:81], v57 offset0:247 offset1:255
	v_or_b32_e32 v0, s6, v35
	v_lshlrev_b32_e32 v0, 12, v0
	global_store_dwordx4 v[62:63], v[58:61], off sc1
	v_lshl_add_u64 v[62:63], v[78:79], 0, v[0:1]
	v_or_b32_e32 v0, s6, v36
	s_waitcnt lgkmcnt(6)
	v_cvt_pk_bf16_f32 v58, v64, v66
	s_waitcnt lgkmcnt(4)
	v_cvt_pk_bf16_f32 v59, v68, v70
	s_waitcnt lgkmcnt(2)
	v_cvt_pk_bf16_f32 v60, v72, v74
	s_waitcnt lgkmcnt(0)
	v_cvt_pk_bf16_f32 v61, v76, v80
	v_lshlrev_b32_e32 v0, 12, v0
	global_store_dwordx4 v[62:63], v[58:61], off sc1
	v_lshl_add_u64 v[62:63], v[78:79], 0, v[0:1]
	s_nop 0
	v_cvt_pk_bf16_f32 v58, v65, v67
	v_cvt_pk_bf16_f32 v59, v69, v71
	v_cvt_pk_bf16_f32 v60, v73, v75
	v_cvt_pk_bf16_f32 v61, v77, v81
	global_store_dwordx4 v[62:63], v[58:61], off sc1
	s_waitcnt lgkmcnt(0)

; #define LAS __attribute__((address_space(3)))
; __device__ __forceinline__ void transpose_item(const float* W, int K, int N, bf16* WT, LAS float* scr, int item, int lane) {
;     const int nblk = N / 64, kb = item / nblk, nb = item % nblk, k0 = 64 * kb, n0 = 64 * nb;
;     f32x4 v[16];
; #pragma unroll
;     for (int i = 0; i < 16; ++i) v[i] = __builtin_nontemporal_load((const f32x4*)(W + (size_t)(k0 + 4 * i + (lane >> 4)) * N + n0 + (lane & 15) * 4));
; #pragma unroll
;     for (int i = 0; i < 16; ++i) { LAS float* d = scr + (4 * i + (lane >> 4)) * 65 + (lane & 15) * 4; d[0] = v[i].x; d[1] = v[i].y; d[2] = v[i].z; d[3] = v[i].w; }
.LBB0_44:
	s_andn2_b64 vcc, exec, s[6:7]
	s_cbranch_vccnz .LBB0_46
	s_add_i32 s4, s18, 0x2c00
	s_and_b32 s7, s4, 0x1ffc0
	s_and_b32 s6, s11, 0x7c0
	v_or_b32_e32 v0, s7, v26
	s_lshl_b32 s4, s6, 2
	v_lshl_add_u64 v[58:59], v[14:15], 0, s[4:5]
	v_lshlrev_b32_e32 v0, 13, v0
	v_lshl_add_u64 v[118:119], v[58:59], 0, v[0:1]
	v_add_co_u32_e32 v66, vcc, 0x8000, v118
	v_add_u32_e32 v0, 0x2cb0, v27
	s_nop 0
	v_addc_co_u32_e32 v67, vcc, 0, v119, vcc
	v_add_co_u32_e32 v74, vcc, 0x10000, v118
	global_load_dwordx4 v[58:61], v[118:119], off nt
	global_load_dwordx4 v[62:65], v[66:67], off nt
	v_addc_co_u32_e32 v75, vcc, 0, v119, vcc
	v_add_co_u32_e32 v76, vcc, 0x18000, v118
	v_add_u32_e32 v57, 0x400, v29
	s_nop 0
	v_addc_co_u32_e32 v77, vcc, 0, v119, vcc
	v_add_co_u32_e32 v82, vcc, 0x20000, v118
	global_load_dwordx4 v[66:69], v[74:75], off nt
	global_load_dwordx4 v[70:73], v[76:77], off nt
	v_addc_co_u32_e32 v83, vcc, 0, v119, vcc
	v_add_co_u32_e32 v84, vcc, 0x28000, v118
	s_lshl_b32 s4, s7, 1
	s_nop 0
	v_addc_co_u32_e32 v85, vcc, 0, v119, vcc
	v_add_co_u32_e32 v90, vcc, 0x30000, v118
	global_load_dwordx4 v[74:77], v[82:83], off nt
	global_load_dwordx4 v[78:81], v[84:85], off nt
	v_addc_co_u32_e32 v91, vcc, 0, v119, vcc
	v_add_co_u32_e32 v92, vcc, 0x38000, v118
	s_nop 1
	v_addc_co_u32_e32 v93, vcc, 0, v119, vcc
	v_add_co_u32_e32 v98, vcc, 0x40000, v118
	global_load_dwordx4 v[82:85], v[90:91], off nt
	global_load_dwordx4 v[86:89], v[92:93], off nt
	v_addc_co_u32_e32 v99, vcc, 0, v119, vcc
	v_add_co_u32_e32 v100, vcc, 0x48000, v118
	s_nop 1
	v_addc_co_u32_e32 v101, vcc, 0, v119, vcc
	v_add_co_u32_e32 v106, vcc, 0x50000, v118
	global_load_dwordx4 v[90:93], v[98:99], off nt
	global_load_dwordx4 v[94:97], v[100:101], off nt
	v_addc_co_u32_e32 v107, vcc, 0, v119, vcc
	v_add_co_u32_e32 v108, vcc, 0x58000, v118
	s_nop 1
	v_addc_co_u32_e32 v109, vcc, 0, v119, vcc
	global_load_dwordx4 v[98:101], v[106:107], off nt
	global_load_dwordx4 v[102:105], v[108:109], off nt
	v_add_co_u32_e32 v114, vcc, 0x60000, v118
	s_nop 1
	v_addc_co_u32_e32 v115, vcc, 0, v119, vcc
	v_add_co_u32_e32 v116, vcc, 0x68000, v118
	s_nop 1
	v_addc_co_u32_e32 v117, vcc, 0, v119, vcc
	global_load_dwordx4 v[106:109], v[114:115], off nt
	global_load_dwordx4 v[110:113], v[116:117], off nt
	v_add_co_u32_e32 v114, vcc, 0x70000, v118
	s_nop 1
	v_addc_co_u32_e32 v115, vcc, 0, v119, vcc
	global_load_dwordx4 v[114:117], v[114:115], off nt
	v_add_co_u32_e32 v118, vcc, 0x78000, v118
	s_nop 1
	v_addc_co_u32_e32 v119, vcc, 0, v119, vcc
	global_load_dwordx4 v[118:121], v[118:119], off nt
	s_waitcnt vmcnt(15)
	ds_write2_b32 v27, v58, v59 offset1:1
	ds_write2_b32 v27, v60, v61 offset0:2 offset1:3
	s_waitcnt vmcnt(14)
	ds_write2_b32 v37, v62, v63 offset1:1
	ds_write2_b32 v38, v64, v65 offset1:1
	s_waitcnt vmcnt(13)
	ds_write2_b32 v39, v66, v67 offset1:1
	ds_write2_b32 v40, v68, v69 offset1:1
	s_waitcnt vmcnt(12)
	ds_write2_b32 v41, v70, v71 offset1:1
	ds_write2_b32 v42, v72, v73 offset1:1
	s_waitcnt vmcnt(11)
	ds_write2_b32 v43, v74, v75 offset1:1
	ds_write2_b32 v44, v76, v77 offset1:1
	s_waitcnt vmcnt(10)
	ds_write2_b32 v45, v78, v79 offset1:1
	ds_write2_b32 v46, v80, v81 offset1:1
	s_waitcnt vmcnt(9)
	ds_write2_b32 v47, v82, v83 offset1:1
	ds_write2_b32 v48, v84, v85 offset1:1
	s_waitcnt vmcnt(8)
	ds_write2_b32 v49, v86, v87 offset1:1
	ds_write2_b32 v50, v88, v89 offset1:1
	s_waitcnt vmcnt(7)
	ds_write2_b32 v51, v90, v91 offset1:1
	ds_write2_b32 v52, v92, v93 offset1:1
	s_waitcnt vmcnt(6)
	ds_write2_b32 v53, v94, v95 offset1:1
	ds_write2_b32 v54, v96, v97 offset1:1
	s_waitcnt vmcnt(5)
	ds_write2_b32 v55, v98, v99 offset1:1
	ds_write2_b32 v56, v100, v101 offset1:1
	s_waitcnt vmcnt(4)
	ds_write2_b32 v0, v102, v103 offset1:1
	v_add_u32_e32 v0, 0x2cb8, v27
	ds_write2_b32 v0, v104, v105 offset1:1
	v_add_u32_e32 v0, 0x30c0, v27
	v_lshl_add_u64 v[78:79], v[16:17], 0, s[4:5]
	s_waitcnt vmcnt(3)
	ds_write2_b32 v0, v106, v107 offset1:1
	v_add_u32_e32 v0, 0x30c8, v27
	ds_write2_b32 v0, v108, v109 offset1:1
	v_add_u32_e32 v0, 0x34d0, v27
	s_waitcnt vmcnt(2)
	ds_write2_b32 v0, v110, v111 offset1:1
	v_add_u32_e32 v0, 0x34d8, v27
	ds_write2_b32 v0, v112, v113 offset1:1
	v_add_u32_e32 v0, 0x38e0, v27
	s_waitcnt vmcnt(1)
	ds_write2_b32 v0, v114, v115 offset1:1
	v_add_u32_e32 v0, 0x38e8, v27
	ds_write2_b32 v0, v116, v117 offset1:1
	v_add_u32_e32 v0, 0x3cf0, v27
	s_waitcnt vmcnt(0)
; __device__ __forceinline__ unsigned cvt_pk_bf16(float lo, float hi) { f32x2_t v = {lo, hi}; bf16x2_t b = __builtin_convertvector(v, bf16x2_t); return __builtin_bit_cast(unsigned, b); }
; #define LAS __attribute__((address_space(3)))
; __device__ __forceinline__ void transpose_item(const float* W, int K, int N, bf16* WT, LAS float* scr, int item, int lane) {
;     ...
;     const int c = lane & 7;
; #pragma unroll
;     for (int j = 0; j < 8; ++j) { const int n = (lane >> 3) + 8 * j; const LAS float* s = scr + (8 * c) * 65 + n;
;         v4u o; o.x = pg8::cvt_pk_bf16(s[0 * 65], s[1 * 65]); o.y = pg8::cvt_pk_bf16(s[2 * 65], s[3 * 65]); o.z = pg8::cvt_pk_bf16(s[4 * 65], s[5 * 65]); o.w = pg8::cvt_pk_bf16(s[6 * 65], s[7 * 65]);
;         *(v4u*)(WT + (size_t)(n0 + n) * K + k0 + 8 * c) = o; }
	ds_write2_b32 v0, v118, v119 offset1:1
	v_add_u32_e32 v0, 0x3cf8, v27
	ds_write2_b32 v0, v120, v121 offset1:1
	s_waitcnt lgkmcnt(0)
	ds_read2_b32 v[62:63], v29 offset0:65 offset1:73
	ds_read2_b32 v[64:65], v29 offset1:8
	ds_read2_b32 v[66:67], v29 offset0:130 offset1:138
	ds_read2_b32 v[68:69], v29 offset0:195 offset1:203
	ds_read2_b32 v[70:71], v57 offset0:4 offset1:12
	ds_read2_b32 v[72:73], v57 offset0:69 offset1:77
	ds_read2_b32 v[74:75], v57 offset0:134 offset1:142
	ds_read2_b32 v[76:77], v57 offset0:199 offset1:207
	v_or_b32_e32 v0, s6, v28
	v_lshlrev_b32_e32 v0, 11, v0
	s_waitcnt lgkmcnt(6)
	v_cvt_pk_bf16_f32 v58, v64, v62
	s_waitcnt lgkmcnt(4)
	v_cvt_pk_bf16_f32 v59, v66, v68
	s_waitcnt lgkmcnt(2)
	v_cvt_pk_bf16_f32 v60, v70, v72
	s_waitcnt lgkmcnt(0)
	v_cvt_pk_bf16_f32 v61, v74, v76
	v_lshl_add_u64 v[80:81], v[78:79], 0, v[0:1]
	global_store_dwordx4 v[80:81], v[58:61], off sc1
	v_or_b32_e32 v0, s6, v30
	v_lshlrev_b32_e32 v0, 11, v0
	v_cvt_pk_bf16_f32 v58, v65, v63
	v_cvt_pk_bf16_f32 v59, v67, v69
	v_cvt_pk_bf16_f32 v60, v71, v73
	v_cvt_pk_bf16_f32 v61, v75, v77
	ds_read2_b32 v[64:65], v29 offset0:81 offset1:89
	ds_read2_b32 v[66:67], v29 offset0:16 offset1:24
	ds_read2_b32 v[68:69], v29 offset0:146 offset1:154
	ds_read2_b32 v[70:71], v29 offset0:211 offset1:219
	ds_read2_b32 v[72:73], v57 offset0:20 offset1:28
	ds_read2_b32 v[74:75], v57 offset0:85 offset1:93
	ds_read2_b32 v[76:77], v57 offset0:150 offset1:158
	ds_read2_b32 v[80:81], v57 offset0:215 offset1:223
	v_lshl_add_u64 v[62:63], v[78:79], 0, v[0:1]
	v_or_b32_e32 v0, s6, v31
	v_lshlrev_b32_e32 v0, 11, v0
	global_store_dwordx4 v[62:63], v[58:61], off sc1
	v_lshl_add_u64 v[62:63], v[78:79], 0, v[0:1]
	v_or_b32_e32 v0, s6, v32
	s_waitcnt lgkmcnt(6)
	v_cvt_pk_bf16_f32 v58, v66, v64
	s_waitcnt lgkmcnt(4)
	v_cvt_pk_bf16_f32 v59, v68, v70
	s_waitcnt lgkmcnt(2)
	v_cvt_pk_bf16_f32 v60, v72, v74
	s_waitcnt lgkmcnt(0)
	v_cvt_pk_bf16_f32 v61, v76, v80
	global_store_dwordx4 v[62:63], v[58:61], off sc1
	v_lshlrev_b32_e32 v0, 11, v0
	v_lshl_add_u64 v[62:63], v[78:79], 0, v[0:1]
	v_cvt_pk_bf16_f32 v58, v67, v65
	v_cvt_pk_bf16_f32 v59, v69, v71
	v_cvt_pk_bf16_f32 v60, v73, v75
	v_cvt_pk_bf16_f32 v61, v77, v81
	ds_read2_b32 v[64:65], v29 offset0:32 offset1:40
	ds_read2_b32 v[66:67], v29 offset0:97 offset1:105
	ds_read2_b32 v[68:69], v29 offset0:162 offset1:170
	ds_read2_b32 v[70:71], v29 offset0:227 offset1:235
	ds_read2_b32 v[72:73], v57 offset0:36 offset1:44
	ds_read2_b32 v[74:75], v57 offset0:101 offset1:109
	ds_read2_b32 v[76:77], v57 offset0:166 offset1:174
	ds_read2_b32 v[80:81], v57 offset0:231 offset1:239
	v_or_b32_e32 v0, s6, v33
	v_lshlrev_b32_e32 v0, 11, v0
	global_store_dwordx4 v[62:63], v[58:61], off sc1
	v_lshl_add_u64 v[62:63], v[78:79], 0, v[0:1]
	v_or_b32_e32 v0, s6, v34
	s_waitcnt lgkmcnt(6)
	v_cvt_pk_bf16_f32 v58, v64, v66
	s_waitcnt lgkmcnt(4)
	v_cvt_pk_bf16_f32 v59, v68, v70
	s_waitcnt lgkmcnt(2)
	v_cvt_pk_bf16_f32 v60, v72, v74
	s_waitcnt lgkmcnt(0)
	v_cvt_pk_bf16_f32 v61, v76, v80
	global_store_dwordx4 v[62:63], v[58:61], off sc1
	v_lshlrev_b32_e32 v0, 11, v0
	v_lshl_add_u64 v[62:63], v[78:79], 0, v[0:1]
	v_cvt_pk_bf16_f32 v58, v65, v67
	v_cvt_pk_bf16_f32 v59, v69, v71
	v_cvt_pk_bf16_f32 v60, v73, v75
	v_cvt_pk_bf16_f32 v61, v77, v81
	ds_read2_b32 v[64:65], v29 offset0:48 offset1:56
	ds_read2_b32 v[66:67], v29 offset0:113 offset1:121
	ds_read2_b32 v[68:69], v29 offset0:178 offset1:186
	ds_read2_b32 v[70:71], v29 offset0:243 offset1:251
	ds_read2_b32 v[72:73], v57 offset0:52 offset1:60
	ds_read2_b32 v[74:75], v57 offset0:117 offset1:125
	ds_read2_b32 v[76:77], v57 offset0:182 offset1:190
	ds_read2_b32 v[80:81], v57 offset0:247 offset1:255
	v_or_b32_e32 v0, s6, v35
	v_lshlrev_b32_e32 v0, 11, v0
	global_store_dwordx4 v[62:63], v[58:61], off sc1
	v_lshl_add_u64 v[62:63], v[78:79], 0, v[0:1]
	v_or_b32_e32 v0, s6, v36
	s_waitcnt lgkmcnt(6)
	v_cvt_pk_bf16_f32 v58, v64, v66
	s_waitcnt lgkmcnt(4)
	v_cvt_pk_bf16_f32 v59, v68, v70
	s_waitcnt lgkmcnt(2)
	v_cvt_pk_bf16_f32 v60, v72, v74
	s_waitcnt lgkmcnt(0)
	v_cvt_pk_bf16_f32 v61, v76, v80
	v_lshlrev_b32_e32 v0, 11, v0
	global_store_dwordx4 v[62:63], v[58:61], off sc1
	v_lshl_add_u64 v[62:63], v[78:79], 0, v[0:1]
	s_nop 0
	v_cvt_pk_bf16_f32 v58, v65, v67
	v_cvt_pk_bf16_f32 v59, v69, v71
	v_cvt_pk_bf16_f32 v60, v73, v75
	v_cvt_pk_bf16_f32 v61, v77, v81
	global_store_dwordx4 v[62:63], v[58:61], off sc1
	s_waitcnt lgkmcnt(0)

; #define LAS __attribute__((address_space(3)))
; __device__ __forceinline__ void transpose_item(const float* W, int K, int N, bf16* WT, LAS float* scr, int item, int lane) {
;     const int nblk = N / 64, kb = item / nblk, nb = item % nblk, k0 = 64 * kb, n0 = 64 * nb;
;     f32x4 v[16];
; #pragma unroll
;     for (int i = 0; i < 16; ++i) v[i] = __builtin_nontemporal_load((const f32x4*)(W + (size_t)(k0 + 4 * i + (lane >> 4)) * N + n0 + (lane & 15) * 4));
; #pragma unroll
;     for (int i = 0; i < 16; ++i) { LAS float* d = scr + (4 * i + (lane >> 4)) * 65 + (lane & 15) * 4; d[0] = v[i].x; d[1] = v[i].y; d[2] = v[i].z; d[3] = v[i].w; }
.LBB0_47:
	s_andn2_b64 vcc, exec, s[6:7]
	s_cbranch_vccnz .LBB0_49
	s_add_i32 s4, s18, 0x3000
	s_and_b32 s7, s4, 0x1ffc0
	s_and_b32 s6, s11, 0x7c0
	v_or_b32_e32 v0, s7, v26
	s_lshl_b32 s4, s6, 2
	v_lshl_add_u64 v[58:59], v[18:19], 0, s[4:5]
	v_lshlrev_b32_e32 v0, 13, v0
	v_lshl_add_u64 v[118:119], v[58:59], 0, v[0:1]
	v_add_co_u32_e32 v66, vcc, 0x8000, v118
	v_add_u32_e32 v0, 0x2cb0, v27
	s_nop 0
	v_addc_co_u32_e32 v67, vcc, 0, v119, vcc
	v_add_co_u32_e32 v74, vcc, 0x10000, v118
	global_load_dwordx4 v[58:61], v[118:119], off nt
	global_load_dwordx4 v[62:65], v[66:67], off nt
	v_addc_co_u32_e32 v75, vcc, 0, v119, vcc
	v_add_co_u32_e32 v76, vcc, 0x18000, v118
	v_add_u32_e32 v57, 0x400, v29
	s_nop 0
	v_addc_co_u32_e32 v77, vcc, 0, v119, vcc
	v_add_co_u32_e32 v82, vcc, 0x20000, v118
	global_load_dwordx4 v[66:69], v[74:75], off nt
	global_load_dwordx4 v[70:73], v[76:77], off nt
	v_addc_co_u32_e32 v83, vcc, 0, v119, vcc
	v_add_co_u32_e32 v84, vcc, 0x28000, v118
	s_lshl_b32 s4, s7, 1
	s_nop 0
	v_addc_co_u32_e32 v85, vcc, 0, v119, vcc
	v_add_co_u32_e32 v90, vcc, 0x30000, v118
	global_load_dwordx4 v[74:77], v[82:83], off nt
	global_load_dwordx4 v[78:81], v[84:85], off nt
	v_addc_co_u32_e32 v91, vcc, 0, v119, vcc
	v_add_co_u32_e32 v92, vcc, 0x38000, v118
	s_nop 1
	v_addc_co_u32_e32 v93, vcc, 0, v119, vcc
	v_add_co_u32_e32 v98, vcc, 0x40000, v118
	global_load_dwordx4 v[82:85], v[90:91], off nt
	global_load_dwordx4 v[86:89], v[92:93], off nt
	v_addc_co_u32_e32 v99, vcc, 0, v119, vcc
	v_add_co_u32_e32 v100, vcc, 0x48000, v118
	s_nop 1
	v_addc_co_u32_e32 v101, vcc, 0, v119, vcc
	v_add_co_u32_e32 v106, vcc, 0x50000, v118
	global_load_dwordx4 v[90:93], v[98:99], off nt
	global_load_dwordx4 v[94:97], v[100:101], off nt
	v_addc_co_u32_e32 v107, vcc, 0, v119, vcc
	v_add_co_u32_e32 v108, vcc, 0x58000, v118
	s_nop 1
	v_addc_co_u32_e32 v109, vcc, 0, v119, vcc
	global_load_dwordx4 v[98:101], v[106:107], off nt
	global_load_dwordx4 v[102:105], v[108:109], off nt
	v_add_co_u32_e32 v114, vcc, 0x60000, v118
	s_nop 1
	v_addc_co_u32_e32 v115, vcc, 0, v119, vcc
	v_add_co_u32_e32 v116, vcc, 0x68000, v118
	s_nop 1
	v_addc_co_u32_e32 v117, vcc, 0, v119, vcc
	global_load_dwordx4 v[106:109], v[114:115], off nt
	global_load_dwordx4 v[110:113], v[116:117], off nt
	v_add_co_u32_e32 v114, vcc, 0x70000, v118
	s_nop 1
	v_addc_co_u32_e32 v115, vcc, 0, v119, vcc
	global_load_dwordx4 v[114:117], v[114:115], off nt
	v_add_co_u32_e32 v118, vcc, 0x78000, v118
	s_nop 1
	v_addc_co_u32_e32 v119, vcc, 0, v119, vcc
	global_load_dwordx4 v[118:121], v[118:119], off nt
	s_waitcnt vmcnt(15)
	ds_write2_b32 v27, v58, v59 offset1:1
	ds_write2_b32 v27, v60, v61 offset0:2 offset1:3
	s_waitcnt vmcnt(14)
	ds_write2_b32 v37, v62, v63 offset1:1
	ds_write2_b32 v38, v64, v65 offset1:1
	s_waitcnt vmcnt(13)
	ds_write2_b32 v39, v66, v67 offset1:1
	ds_write2_b32 v40, v68, v69 offset1:1
	s_waitcnt vmcnt(12)
	ds_write2_b32 v41, v70, v71 offset1:1
	ds_write2_b32 v42, v72, v73 offset1:1
	s_waitcnt vmcnt(11)
	ds_write2_b32 v43, v74, v75 offset1:1
	ds_write2_b32 v44, v76, v77 offset1:1
	s_waitcnt vmcnt(10)
	ds_write2_b32 v45, v78, v79 offset1:1
	ds_write2_b32 v46, v80, v81 offset1:1
	s_waitcnt vmcnt(9)
	ds_write2_b32 v47, v82, v83 offset1:1
	ds_write2_b32 v48, v84, v85 offset1:1
	s_waitcnt vmcnt(8)
	ds_write2_b32 v49, v86, v87 offset1:1
	ds_write2_b32 v50, v88, v89 offset1:1
	s_waitcnt vmcnt(7)
	ds_write2_b32 v51, v90, v91 offset1:1
	ds_write2_b32 v52, v92, v93 offset1:1
	s_waitcnt vmcnt(6)
	ds_write2_b32 v53, v94, v95 offset1:1
	ds_write2_b32 v54, v96, v97 offset1:1
	s_waitcnt vmcnt(5)
	ds_write2_b32 v55, v98, v99 offset1:1
	ds_write2_b32 v56, v100, v101 offset1:1
	s_waitcnt vmcnt(4)
	ds_write2_b32 v0, v102, v103 offset1:1
	v_add_u32_e32 v0, 0x2cb8, v27
	ds_write2_b32 v0, v104, v105 offset1:1
	v_add_u32_e32 v0, 0x30c0, v27
	v_lshl_add_u64 v[78:79], v[20:21], 0, s[4:5]
	s_waitcnt vmcnt(3)
	ds_write2_b32 v0, v106, v107 offset1:1
	v_add_u32_e32 v0, 0x30c8, v27
	ds_write2_b32 v0, v108, v109 offset1:1
	v_add_u32_e32 v0, 0x34d0, v27
	s_waitcnt vmcnt(2)
	ds_write2_b32 v0, v110, v111 offset1:1
	v_add_u32_e32 v0, 0x34d8, v27
	ds_write2_b32 v0, v112, v113 offset1:1
	v_add_u32_e32 v0, 0x38e0, v27
	s_waitcnt vmcnt(1)
	ds_write2_b32 v0, v114, v115 offset1:1
	v_add_u32_e32 v0, 0x38e8, v27
	ds_write2_b32 v0, v116, v117 offset1:1
	v_add_u32_e32 v0, 0x3cf0, v27
	s_waitcnt vmcnt(0)
; __device__ __forceinline__ unsigned cvt_pk_bf16(float lo, float hi) { f32x2_t v = {lo, hi}; bf16x2_t b = __builtin_convertvector(v, bf16x2_t); return __builtin_bit_cast(unsigned, b); }
; #define LAS __attribute__((address_space(3)))
; __device__ __forceinline__ void transpose_item(const float* W, int K, int N, bf16* WT, LAS float* scr, int item, int lane) {
;     ...
;     const int c = lane & 7;
; #pragma unroll
;     for (int j = 0; j < 8; ++j) { const int n = (lane >> 3) + 8 * j; const LAS float* s = scr + (8 * c) * 65 + n;
;         v4u o; o.x = pg8::cvt_pk_bf16(s[0 * 65], s[1 * 65]); o.y = pg8::cvt_pk_bf16(s[2 * 65], s[3 * 65]); o.z = pg8::cvt_pk_bf16(s[4 * 65], s[5 * 65]); o.w = pg8::cvt_pk_bf16(s[6 * 65], s[7 * 65]);
;         *(v4u*)(WT + (size_t)(n0 + n) * K + k0 + 8 * c) = o; }
	ds_write2_b32 v0, v118, v119 offset1:1
	v_add_u32_e32 v0, 0x3cf8, v27
	ds_write2_b32 v0, v120, v121 offset1:1
	s_waitcnt lgkmcnt(0)
	ds_read2_b32 v[62:63], v29 offset0:65 offset1:73
	ds_read2_b32 v[64:65], v29 offset1:8
	ds_read2_b32 v[66:67], v29 offset0:130 offset1:138
	ds_read2_b32 v[68:69], v29 offset0:195 offset1:203
	ds_read2_b32 v[70:71], v57 offset0:4 offset1:12
	ds_read2_b32 v[72:73], v57 offset0:69 offset1:77
	ds_read2_b32 v[74:75], v57 offset0:134 offset1:142
	ds_read2_b32 v[76:77], v57 offset0:199 offset1:207
	v_or_b32_e32 v0, s6, v28
	v_lshlrev_b32_e32 v0, 11, v0
	s_waitcnt lgkmcnt(6)
	v_cvt_pk_bf16_f32 v58, v64, v62
	s_waitcnt lgkmcnt(4)
	v_cvt_pk_bf16_f32 v59, v66, v68
	s_waitcnt lgkmcnt(2)
	v_cvt_pk_bf16_f32 v60, v70, v72
	s_waitcnt lgkmcnt(0)
	v_cvt_pk_bf16_f32 v61, v74, v76
	v_lshl_add_u64 v[80:81], v[78:79], 0, v[0:1]
	global_store_dwordx4 v[80:81], v[58:61], off sc1
	v_or_b32_e32 v0, s6, v30
	v_lshlrev_b32_e32 v0, 11, v0
	v_cvt_pk_bf16_f32 v58, v65, v63
	v_cvt_pk_bf16_f32 v59, v67, v69
	v_cvt_pk_bf16_f32 v60, v71, v73
	v_cvt_pk_bf16_f32 v61, v75, v77
	ds_read2_b32 v[64:65], v29 offset0:81 offset1:89
	ds_read2_b32 v[66:67], v29 offset0:16 offset1:24
	ds_read2_b32 v[68:69], v29 offset0:146 offset1:154
	ds_read2_b32 v[70:71], v29 offset0:211 offset1:219
	ds_read2_b32 v[72:73], v57 offset0:20 offset1:28
	ds_read2_b32 v[74:75], v57 offset0:85 offset1:93
	ds_read2_b32 v[76:77], v57 offset0:150 offset1:158
	ds_read2_b32 v[80:81], v57 offset0:215 offset1:223
	v_lshl_add_u64 v[62:63], v[78:79], 0, v[0:1]
	v_or_b32_e32 v0, s6, v31
	v_lshlrev_b32_e32 v0, 11, v0
	global_store_dwordx4 v[62:63], v[58:61], off sc1
	v_lshl_add_u64 v[62:63], v[78:79], 0, v[0:1]
	v_or_b32_e32 v0, s6, v32
	s_waitcnt lgkmcnt(6)
	v_cvt_pk_bf16_f32 v58, v66, v64
	s_waitcnt lgkmcnt(4)
	v_cvt_pk_bf16_f32 v59, v68, v70
	s_waitcnt lgkmcnt(2)
	v_cvt_pk_bf16_f32 v60, v72, v74
	s_waitcnt lgkmcnt(0)
	v_cvt_pk_bf16_f32 v61, v76, v80
	global_store_dwordx4 v[62:63], v[58:61], off sc1
	v_lshlrev_b32_e32 v0, 11, v0
	v_lshl_add_u64 v[62:63], v[78:79], 0, v[0:1]
	v_cvt_pk_bf16_f32 v58, v67, v65
	v_cvt_pk_bf16_f32 v59, v69, v71
	v_cvt_pk_bf16_f32 v60, v73, v75
	v_cvt_pk_bf16_f32 v61, v77, v81
	ds_read2_b32 v[64:65], v29 offset0:32 offset1:40
	ds_read2_b32 v[66:67], v29 offset0:97 offset1:105
	ds_read2_b32 v[68:69], v29 offset0:162 offset1:170
	ds_read2_b32 v[70:71], v29 offset0:227 offset1:235
	ds_read2_b32 v[72:73], v57 offset0:36 offset1:44
	ds_read2_b32 v[74:75], v57 offset0:101 offset1:109
	ds_read2_b32 v[76:77], v57 offset0:166 offset1:174
	ds_read2_b32 v[80:81], v57 offset0:231 offset1:239
	v_or_b32_e32 v0, s6, v33
	v_lshlrev_b32_e32 v0, 11, v0
	global_store_dwordx4 v[62:63], v[58:61], off sc1
	v_lshl_add_u64 v[62:63], v[78:79], 0, v[0:1]
	v_or_b32_e32 v0, s6, v34
	s_waitcnt lgkmcnt(6)
	v_cvt_pk_bf16_f32 v58, v64, v66
	s_waitcnt lgkmcnt(4)
	v_cvt_pk_bf16_f32 v59, v68, v70
	s_waitcnt lgkmcnt(2)
	v_cvt_pk_bf16_f32 v60, v72, v74
	s_waitcnt lgkmcnt(0)
	v_cvt_pk_bf16_f32 v61, v76, v80
	global_store_dwordx4 v[62:63], v[58:61], off sc1
	v_lshlrev_b32_e32 v0, 11, v0
	v_lshl_add_u64 v[62:63], v[78:79], 0, v[0:1]
	v_cvt_pk_bf16_f32 v58, v65, v67
	v_cvt_pk_bf16_f32 v59, v69, v71
	v_cvt_pk_bf16_f32 v60, v73, v75
	v_cvt_pk_bf16_f32 v61, v77, v81
	ds_read2_b32 v[64:65], v29 offset0:48 offset1:56
	ds_read2_b32 v[66:67], v29 offset0:113 offset1:121
	ds_read2_b32 v[68:69], v29 offset0:178 offset1:186
	ds_read2_b32 v[70:71], v29 offset0:243 offset1:251
	ds_read2_b32 v[72:73], v57 offset0:52 offset1:60
	ds_read2_b32 v[74:75], v57 offset0:117 offset1:125
	ds_read2_b32 v[76:77], v57 offset0:182 offset1:190
	ds_read2_b32 v[80:81], v57 offset0:247 offset1:255
	v_or_b32_e32 v0, s6, v35
	v_lshlrev_b32_e32 v0, 11, v0
	global_store_dwordx4 v[62:63], v[58:61], off sc1
	v_lshl_add_u64 v[62:63], v[78:79], 0, v[0:1]
	v_or_b32_e32 v0, s6, v36
	s_waitcnt lgkmcnt(6)
	v_cvt_pk_bf16_f32 v58, v64, v66
	s_waitcnt lgkmcnt(4)
	v_cvt_pk_bf16_f32 v59, v68, v70
	s_waitcnt lgkmcnt(2)
	v_cvt_pk_bf16_f32 v60, v72, v74
	s_waitcnt lgkmcnt(0)
	v_cvt_pk_bf16_f32 v61, v76, v80
	v_lshlrev_b32_e32 v0, 11, v0
	global_store_dwordx4 v[62:63], v[58:61], off sc1
	v_lshl_add_u64 v[62:63], v[78:79], 0, v[0:1]
	s_nop 0
	v_cvt_pk_bf16_f32 v58, v65, v67
	v_cvt_pk_bf16_f32 v59, v69, v71
	v_cvt_pk_bf16_f32 v60, v73, v75
	v_cvt_pk_bf16_f32 v61, v77, v81
	global_store_dwordx4 v[62:63], v[58:61], off sc1
	s_waitcnt lgkmcnt(0)

; #define LAS __attribute__((address_space(3)))
; __device__ __forceinline__ void transpose_item(const float* W, int K, int N, bf16* WT, LAS float* scr, int item, int lane) {
;     const int nblk = N / 64, kb = item / nblk, nb = item % nblk, k0 = 64 * kb, n0 = 64 * nb;
;     f32x4 v[16];
; #pragma unroll
;     for (int i = 0; i < 16; ++i) v[i] = __builtin_nontemporal_load((const f32x4*)(W + (size_t)(k0 + 4 * i + (lane >> 4)) * N + n0 + (lane & 15) * 4));
; #pragma unroll
;     for (int i = 0; i < 16; ++i) { LAS float* d = scr + (4 * i + (lane >> 4)) * 65 + (lane & 15) * 4; d[0] = v[i].x; d[1] = v[i].y; d[2] = v[i].z; d[3] = v[i].w; }
.LBB0_50:
	s_andn2_b64 vcc, exec, s[6:7]
	s_cbranch_vccnz .LBB0_31
	s_mul_hi_i32 s4, s10, 0x38e38e39
	s_lshr_b32 s6, s4, 31
	s_ashr_i32 s4, s4, 5
	s_add_i32 s4, s4, s6
	s_lshl_b32 s8, s4, 6
	s_mulk_i32 s4, 0xdc00
	s_add_i32 s6, s11, s4
	v_or_b32_e32 v0, s8, v26
	s_ashr_i32 s7, s6, 31
	v_lshl_add_u64 v[118:119], s[6:7], 2, v[22:23]
	v_or_b32_e32 v57, 4, v0
	v_mad_i64_i32 v[68:69], s[22:23], v57, s20, v[118:119]
	v_or_b32_e32 v57, 8, v0
	v_mad_i64_i32 v[74:75], s[22:23], v57, s20, v[118:119]
	v_or_b32_e32 v57, 12, v0
	v_mad_i64_i32 v[66:67], s[22:23], v0, s20, v[118:119]
	v_mad_i64_i32 v[76:77], s[22:23], v57, s20, v[118:119]
	global_load_dwordx4 v[58:61], v[66:67], off nt
	global_load_dwordx4 v[62:65], v[68:69], off nt
	s_nop 0
	global_load_dwordx4 v[66:69], v[74:75], off nt
	global_load_dwordx4 v[70:73], v[76:77], off nt
	v_or_b32_e32 v57, 16, v0
	v_or_b32_e32 v74, 20, v0
	v_or_b32_e32 v75, 24, v0
	v_or_b32_e32 v76, 28, v0
	v_or_b32_e32 v86, 32, v0
	v_or_b32_e32 v94, 36, v0
	v_or_b32_e32 v102, 40, v0
	v_or_b32_e32 v103, 44, v0
	v_mad_i64_i32 v[82:83], s[22:23], v57, s20, v[118:119]
	v_mad_i64_i32 v[84:85], s[22:23], v74, s20, v[118:119]
	v_mad_i64_i32 v[90:91], s[22:23], v75, s20, v[118:119]
	v_mad_i64_i32 v[92:93], s[22:23], v76, s20, v[118:119]
	v_mad_i64_i32 v[98:99], s[22:23], v86, s20, v[118:119]
	global_load_dwordx4 v[74:77], v[82:83], off nt
	global_load_dwordx4 v[78:81], v[84:85], off nt
	s_nop 0
	global_load_dwordx4 v[82:85], v[90:91], off nt
	global_load_dwordx4 v[86:89], v[92:93], off nt
	v_mad_i64_i32 v[100:101], s[22:23], v94, s20, v[118:119]
	global_load_dwordx4 v[90:93], v[98:99], off nt
	global_load_dwordx4 v[94:97], v[100:101], off nt
	v_mad_i64_i32 v[98:99], s[22:23], v102, s20, v[118:119]
	v_mad_i64_i32 v[102:103], s[22:23], v103, s20, v[118:119]
	global_load_dwordx4 v[98:101], v[98:99], off nt
	v_or_b32_e32 v57, 48, v0
	global_load_dwordx4 v[102:105], v[102:103], off nt
	v_mad_i64_i32 v[106:107], s[22:23], v57, s20, v[118:119]
	global_load_dwordx4 v[106:109], v[106:107], off nt
	v_or_b32_e32 v57, 52, v0
	v_mad_i64_i32 v[110:111], s[22:23], v57, s20, v[118:119]
	global_load_dwordx4 v[110:113], v[110:111], off nt
	v_or_b32_e32 v57, 56, v0
	v_mad_i64_i32 v[114:115], s[22:23], v57, s20, v[118:119]
	global_load_dwordx4 v[114:117], v[114:115], off nt
	v_or_b32_e32 v0, 60, v0
	v_mad_i64_i32 v[118:119], s[22:23], v0, s20, v[118:119]
	global_load_dwordx4 v[118:121], v[118:119], off nt
	v_add_u32_e32 v0, 0x2cb0, v27
	s_ashr_i32 s9, s8, 31
	s_waitcnt vmcnt(15)
	ds_write2_b32 v27, v58, v59 offset1:1
	ds_write2_b32 v27, v60, v61 offset0:2 offset1:3
	s_waitcnt vmcnt(14)
	ds_write2_b32 v37, v62, v63 offset1:1
	ds_write2_b32 v38, v64, v65 offset1:1
	s_waitcnt vmcnt(13)
	ds_write2_b32 v39, v66, v67 offset1:1
	ds_write2_b32 v40, v68, v69 offset1:1
	s_waitcnt vmcnt(12)
	ds_write2_b32 v41, v70, v71 offset1:1
	ds_write2_b32 v42, v72, v73 offset1:1
	s_waitcnt vmcnt(11)
	ds_write2_b32 v43, v74, v75 offset1:1
	ds_write2_b32 v44, v76, v77 offset1:1
	s_waitcnt vmcnt(10)
	ds_write2_b32 v45, v78, v79 offset1:1
	ds_write2_b32 v46, v80, v81 offset1:1
	s_waitcnt vmcnt(9)
	ds_write2_b32 v47, v82, v83 offset1:1
	ds_write2_b32 v48, v84, v85 offset1:1
	s_waitcnt vmcnt(8)
	ds_write2_b32 v49, v86, v87 offset1:1
	ds_write2_b32 v50, v88, v89 offset1:1
	s_waitcnt vmcnt(7)
	ds_write2_b32 v51, v90, v91 offset1:1
	ds_write2_b32 v52, v92, v93 offset1:1
	s_waitcnt vmcnt(6)
	ds_write2_b32 v53, v94, v95 offset1:1
	ds_write2_b32 v54, v96, v97 offset1:1
	s_waitcnt vmcnt(5)
	ds_write2_b32 v55, v98, v99 offset1:1
	ds_write2_b32 v56, v100, v101 offset1:1
	v_add_u32_e32 v80, s6, v28
	v_ashrrev_i32_e32 v81, 31, v80
	v_lshl_add_u64 v[78:79], s[8:9], 1, v[24:25]
	v_lshlrev_b64 v[82:83], 12, v[80:81]
	v_lshl_add_u64 v[82:83], v[78:79], 0, v[82:83]
	s_waitcnt vmcnt(4)
	ds_write2_b32 v0, v102, v103 offset1:1
	v_add_u32_e32 v0, 0x2cb8, v27
	ds_write2_b32 v0, v104, v105 offset1:1
	v_add_u32_e32 v0, 0x30c0, v27
	s_waitcnt vmcnt(3)
	ds_write2_b32 v0, v106, v107 offset1:1
	v_add_u32_e32 v0, 0x30c8, v27
	ds_write2_b32 v0, v108, v109 offset1:1
	v_add_u32_e32 v0, 0x34d0, v27
	s_waitcnt vmcnt(2)
	ds_write2_b32 v0, v110, v111 offset1:1
	v_add_u32_e32 v0, 0x34d8, v27
	ds_write2_b32 v0, v112, v113 offset1:1
	v_add_u32_e32 v0, 0x38e0, v27
	s_waitcnt vmcnt(1)
	ds_write2_b32 v0, v114, v115 offset1:1
	v_add_u32_e32 v0, 0x38e8, v27
	ds_write2_b32 v0, v116, v117 offset1:1
	v_add_u32_e32 v0, 0x3cf0, v27
	s_waitcnt vmcnt(0)
	ds_write2_b32 v0, v118, v119 offset1:1
	v_add_u32_e32 v0, 0x3cf8, v27
	ds_write2_b32 v0, v120, v121 offset1:1
	s_waitcnt lgkmcnt(0)
; __device__ __forceinline__ unsigned cvt_pk_bf16(float lo, float hi) { f32x2_t v = {lo, hi}; bf16x2_t b = __builtin_convertvector(v, bf16x2_t); return __builtin_bit_cast(unsigned, b); }
; #define LAS __attribute__((address_space(3)))
; __device__ __forceinline__ void transpose_item(const float* W, int K, int N, bf16* WT, LAS float* scr, int item, int lane) {
;     ...
;     const int c = lane & 7;
; #pragma unroll
;     for (int j = 0; j < 8; ++j) { const int n = (lane >> 3) + 8 * j; const LAS float* s = scr + (8 * c) * 65 + n;
;         v4u o; o.x = pg8::cvt_pk_bf16(s[0 * 65], s[1 * 65]); o.y = pg8::cvt_pk_bf16(s[2 * 65], s[3 * 65]); o.z = pg8::cvt_pk_bf16(s[4 * 65], s[5 * 65]); o.w = pg8::cvt_pk_bf16(s[6 * 65], s[7 * 65]);
;         *(v4u*)(WT + (size_t)(n0 + n) * K + k0 + 8 * c) = o; }
	v_add_u32_e32 v0, 0x400, v29
	ds_read2_b32 v[62:63], v29 offset0:65 offset1:73
	ds_read2_b32 v[64:65], v29 offset1:8
	ds_read2_b32 v[66:67], v29 offset0:130 offset1:138
	ds_read2_b32 v[68:69], v29 offset0:195 offset1:203
	ds_read2_b32 v[70:71], v0 offset0:4 offset1:12
	ds_read2_b32 v[72:73], v0 offset0:69 offset1:77
	ds_read2_b32 v[74:75], v0 offset0:134 offset1:142
	ds_read2_b32 v[76:77], v0 offset0:199 offset1:207
	s_waitcnt lgkmcnt(6)
	v_cvt_pk_bf16_f32 v58, v64, v62
	s_waitcnt lgkmcnt(2)
	v_cvt_pk_bf16_f32 v60, v70, v72
	v_cvt_pk_bf16_f32 v59, v66, v68
	s_waitcnt lgkmcnt(0)
	v_cvt_pk_bf16_f32 v61, v74, v76
	v_add_u32_e32 v62, 8, v80
	global_store_dwordx4 v[82:83], v[58:61], off sc1
	s_nop 1
	v_cvt_pk_bf16_f32 v58, v65, v63
	v_ashrrev_i32_e32 v63, 31, v62
	v_cvt_pk_bf16_f32 v59, v67, v69
	v_cvt_pk_bf16_f32 v60, v71, v73
	v_cvt_pk_bf16_f32 v61, v75, v77
	v_lshlrev_b64 v[62:63], 12, v[62:63]
	ds_read2_b32 v[64:65], v29 offset0:81 offset1:89
	ds_read2_b32 v[66:67], v29 offset0:16 offset1:24
	ds_read2_b32 v[68:69], v29 offset0:146 offset1:154
	ds_read2_b32 v[70:71], v29 offset0:211 offset1:219
	ds_read2_b32 v[72:73], v0 offset0:20 offset1:28
	ds_read2_b32 v[74:75], v0 offset0:85 offset1:93
	ds_read2_b32 v[76:77], v0 offset0:150 offset1:158
	ds_read2_b32 v[82:83], v0 offset0:215 offset1:223
	v_lshl_add_u64 v[62:63], v[78:79], 0, v[62:63]
	global_store_dwordx4 v[62:63], v[58:61], off sc1
	v_add_u32_e32 v62, 16, v80
	v_ashrrev_i32_e32 v63, 31, v62
	v_lshlrev_b64 v[62:63], 12, v[62:63]
	s_waitcnt lgkmcnt(6)
	v_cvt_pk_bf16_f32 v58, v66, v64
	s_waitcnt lgkmcnt(4)
	v_cvt_pk_bf16_f32 v59, v68, v70
	s_waitcnt lgkmcnt(2)
	v_cvt_pk_bf16_f32 v60, v72, v74
	s_waitcnt lgkmcnt(0)
	v_cvt_pk_bf16_f32 v61, v76, v82
	v_lshl_add_u64 v[62:63], v[78:79], 0, v[62:63]
	global_store_dwordx4 v[62:63], v[58:61], off sc1
	v_add_u32_e32 v62, 24, v80
	v_ashrrev_i32_e32 v63, 31, v62
	v_cvt_pk_bf16_f32 v58, v67, v65
	v_cvt_pk_bf16_f32 v59, v69, v71
	v_cvt_pk_bf16_f32 v60, v73, v75
	v_cvt_pk_bf16_f32 v61, v77, v83
	v_lshlrev_b64 v[62:63], 12, v[62:63]
	ds_read2_b32 v[64:65], v29 offset0:32 offset1:40
	ds_read2_b32 v[66:67], v29 offset0:97 offset1:105
	ds_read2_b32 v[68:69], v29 offset0:162 offset1:170
	ds_read2_b32 v[70:71], v29 offset0:227 offset1:235
	ds_read2_b32 v[72:73], v0 offset0:36 offset1:44
	ds_read2_b32 v[74:75], v0 offset0:101 offset1:109
	ds_read2_b32 v[76:77], v0 offset0:166 offset1:174
	ds_read2_b32 v[82:83], v0 offset0:231 offset1:239
	v_lshl_add_u64 v[62:63], v[78:79], 0, v[62:63]
	global_store_dwordx4 v[62:63], v[58:61], off sc1
	v_add_u32_e32 v62, 32, v80
	v_ashrrev_i32_e32 v63, 31, v62
	v_lshlrev_b64 v[62:63], 12, v[62:63]
	s_waitcnt lgkmcnt(6)
	v_cvt_pk_bf16_f32 v58, v64, v66
	s_waitcnt lgkmcnt(4)
	v_cvt_pk_bf16_f32 v59, v68, v70
	s_waitcnt lgkmcnt(2)
	v_cvt_pk_bf16_f32 v60, v72, v74
	s_waitcnt lgkmcnt(0)
	v_cvt_pk_bf16_f32 v61, v76, v82
	v_lshl_add_u64 v[62:63], v[78:79], 0, v[62:63]
	global_store_dwordx4 v[62:63], v[58:61], off sc1
	v_add_u32_e32 v62, 40, v80
	v_ashrrev_i32_e32 v63, 31, v62
	v_cvt_pk_bf16_f32 v58, v65, v67
	v_cvt_pk_bf16_f32 v59, v69, v71
	v_cvt_pk_bf16_f32 v60, v73, v75
	v_cvt_pk_bf16_f32 v61, v77, v83
	v_lshlrev_b64 v[62:63], 12, v[62:63]
	ds_read2_b32 v[64:65], v29 offset0:48 offset1:56
	ds_read2_b32 v[66:67], v29 offset0:113 offset1:121
	ds_read2_b32 v[68:69], v29 offset0:178 offset1:186
	ds_read2_b32 v[70:71], v29 offset0:243 offset1:251
	ds_read2_b32 v[72:73], v0 offset0:52 offset1:60
	ds_read2_b32 v[74:75], v0 offset0:117 offset1:125
	ds_read2_b32 v[76:77], v0 offset0:182 offset1:190
	ds_read2_b32 v[82:83], v0 offset0:247 offset1:255
	v_lshl_add_u64 v[62:63], v[78:79], 0, v[62:63]
	global_store_dwordx4 v[62:63], v[58:61], off sc1
	v_add_u32_e32 v62, 48, v80
	v_ashrrev_i32_e32 v63, 31, v62
	v_lshlrev_b64 v[62:63], 12, v[62:63]
	s_waitcnt lgkmcnt(6)
	v_cvt_pk_bf16_f32 v58, v64, v66
	s_waitcnt lgkmcnt(4)
	v_cvt_pk_bf16_f32 v59, v68, v70
	s_waitcnt lgkmcnt(2)
	v_cvt_pk_bf16_f32 v60, v72, v74
	s_waitcnt lgkmcnt(0)
	v_cvt_pk_bf16_f32 v61, v76, v82
	v_lshl_add_u64 v[62:63], v[78:79], 0, v[62:63]
	global_store_dwordx4 v[62:63], v[58:61], off sc1
	v_add_u32_e32 v62, 56, v80
	v_ashrrev_i32_e32 v63, 31, v62
	v_lshlrev_b64 v[62:63], 12, v[62:63]
	v_cvt_pk_bf16_f32 v58, v65, v67
	v_cvt_pk_bf16_f32 v59, v69, v71
	v_cvt_pk_bf16_f32 v60, v73, v75
	v_cvt_pk_bf16_f32 v61, v77, v83
	v_lshl_add_u64 v[62:63], v[78:79], 0, v[62:63]
	global_store_dwordx4 v[62:63], v[58:61], off sc1
	s_waitcnt lgkmcnt(0)
	s_branch .LBB0_31

; __device__ __forceinline__ float sigmoidf_(float x) { return __builtin_amdgcn_rcpf(1.0f + __expf(-x)); }
; __device__ __forceinline__ u32x4 pack8f(f32x4 v0, f32x4 v1) { u32x4 w; w.x = cvt_pk_bf16(v0[0], v0[1]); w.y = cvt_pk_bf16(v0[2], v0[3]); w.z = cvt_pk_bf16(v1[0], v1[1]); w.w = cvt_pk_bf16(v1[2], v1[3]); return w; }
;     __device__ __forceinline__ void operator()(const f32x4 (&acc)[2][2][4][2], const Unit& u, int wr, int wc, int fr, int fq) const {
;     ...
;             const int c0 = (pn - 20) * BM + cin;
;             f32x4 bv[2][2];
; #pragma unroll
;             for (int bj = 0; bj < 2; ++bj)
; #pragma unroll
;                 for (int n = 0; n < 2; ++n) bv[bj][n] = *(const f32x4*)(gate_b + c0 + bj * HALF + 4 * n);
; #pragma unroll
;             for (int ai = 0; ai < 2; ++ai)
; #pragma unroll
;                 for (int m = 0; m < 4; ++m) { bf16_t* rowp = GT + (size_t)(row0 + ai * HALF + m * 16) * 4096 + c0;
; #pragma unroll
;                     for (int bj = 0; bj < 2; ++bj) { f32x4 v0 = acc[ai][bj][m][0] + bv[bj][0], v1 = acc[ai][bj][m][1] + bv[bj][1];
; #pragma unroll
;                         for (int e = 0; e < 4; ++e) { v0[e] = sigmoidf_(v0[e]); v1[e] = sigmoidf_(v1[e]); }
;                         *(u32x4*)(rowp + bj * HALF) = pack8f(v0, v1); } }
.LBB0_177:
	s_cmp_gt_u32 s64, 19
	s_cbranch_scc0 .LBB0_179
	v_lshl_add_u32 v166, s64, 8, v174
	v_mov_b32_e32 v167, v153
	v_lshl_add_u64 v[132:133], v[166:167], 2, s[16:17]
	global_load_dwordx4 v[136:139], v[132:133], off offset:16
	global_load_dwordx4 v[140:143], v[132:133], off
	global_load_dwordx4 v[128:131], v[132:133], off offset:528
	s_nop 0
	global_load_dwordx4 v[132:135], v[132:133], off offset:512
	v_ashrrev_i32_e32 v165, 31, v164
	v_lshlrev_b64 v[168:169], 13, v[164:165]
	v_lshl_add_u64 v[170:171], s[20:21], 0, v[168:169]
	v_lshlrev_b64 v[168:169], 1, v[166:167]
	v_lshl_add_u64 v[166:167], v[170:171], 0, v[168:169]
	s_mov_b32 s29, 0x100000
	s_mov_b64 s[36:37], 0x100000
	s_waitcnt vmcnt(0)
	v_pk_add_f32 v[182:183], v[120:121], v[136:137]
	v_pk_add_f32 v[178:179], v[124:125], v[140:141]
	v_pk_add_f32 v[180:181], v[122:123], v[138:139]
	v_mul_f32_e32 v165, 0xbfb8aa3b, v178
	v_mul_f32_e32 v178, 0xbfb8aa3b, v182
	v_exp_f32_e32 v178, v178
	v_pk_add_f32 v[170:171], v[126:127], v[142:143]
	v_exp_f32_e32 v165, v165
	v_mul_f32_e32 v170, 0xbfb8aa3b, v170
	v_add_f32_e32 v178, 1.0, v178
	v_rcp_f32_e32 v182, v178
	v_mul_f32_e32 v178, 0xbfb8aa3b, v179
	v_mul_f32_e32 v179, 0xbfb8aa3b, v183
	v_exp_f32_e32 v179, v179
	v_mul_f32_e32 v171, 0xbfb8aa3b, v171
	v_exp_f32_e32 v178, v178
	v_exp_f32_e32 v170, v170
	v_add_f32_e32 v179, 1.0, v179
	v_rcp_f32_e32 v183, v179
	v_mul_f32_e32 v179, 0xbfb8aa3b, v180
	v_exp_f32_e32 v179, v179
	v_exp_f32_e32 v171, v171
	v_add_f32_e32 v165, 1.0, v165
	v_add_f32_e32 v178, 1.0, v178
	v_add_f32_e32 v179, 1.0, v179
	v_rcp_f32_e32 v184, v179
	v_mul_f32_e32 v179, 0xbfb8aa3b, v181
	v_exp_f32_e32 v179, v179
	v_add_f32_e32 v170, 1.0, v170
	v_add_f32_e32 v171, 1.0, v171
	v_rcp_f32_e32 v165, v165
	v_add_f32_e32 v179, 1.0, v179
	v_rcp_f32_e32 v178, v178
	v_rcp_f32_e32 v170, v170
	v_rcp_f32_e32 v171, v171
	v_rcp_f32_e32 v181, v179
	v_cvt_pk_bf16_f32 v178, v165, v178
	v_cvt_pk_bf16_f32 v180, v182, v183
	v_cvt_pk_bf16_f32 v179, v170, v171
	v_cvt_pk_bf16_f32 v181, v184, v181
	global_store_dwordx4 v[166:167], v[178:181], off sc1
	v_pk_add_f32 v[182:183], v[104:105], v[128:129]
	v_pk_add_f32 v[170:171], v[110:111], v[134:135]
	v_pk_add_f32 v[178:179], v[108:109], v[132:133]
	v_pk_add_f32 v[180:181], v[106:107], v[130:131]
	v_mul_f32_e32 v165, 0xbfb8aa3b, v178
	v_mul_f32_e32 v178, 0xbfb8aa3b, v182
	v_exp_f32_e32 v178, v178
	v_mul_f32_e32 v170, 0xbfb8aa3b, v170
	v_mul_f32_e32 v171, 0xbfb8aa3b, v171
	v_exp_f32_e32 v165, v165
	v_add_f32_e32 v178, 1.0, v178
	v_rcp_f32_e32 v182, v178
	v_mul_f32_e32 v178, 0xbfb8aa3b, v179
	v_mul_f32_e32 v179, 0xbfb8aa3b, v183
	v_exp_f32_e32 v179, v179
	v_exp_f32_e32 v178, v178
	v_exp_f32_e32 v170, v170
	v_exp_f32_e32 v171, v171
	v_add_f32_e32 v179, 1.0, v179
	v_rcp_f32_e32 v183, v179
	v_mul_f32_e32 v179, 0xbfb8aa3b, v180
	v_exp_f32_e32 v179, v179
	v_add_f32_e32 v165, 1.0, v165
	v_add_f32_e32 v178, 1.0, v178
	v_add_f32_e32 v170, 1.0, v170
	v_add_f32_e32 v179, 1.0, v179
	v_rcp_f32_e32 v184, v179
	v_mul_f32_e32 v179, 0xbfb8aa3b, v181
	v_exp_f32_e32 v179, v179
	v_add_f32_e32 v171, 1.0, v171
	v_rcp_f32_e32 v165, v165
	v_rcp_f32_e32 v178, v178
	v_add_f32_e32 v179, 1.0, v179
	v_rcp_f32_e32 v170, v170
	v_rcp_f32_e32 v171, v171
	v_rcp_f32_e32 v181, v179
	v_cvt_pk_bf16_f32 v178, v165, v178
	v_cvt_pk_bf16_f32 v180, v182, v183
	v_cvt_pk_bf16_f32 v179, v170, v171
	v_cvt_pk_bf16_f32 v181, v184, v181
	global_store_dwordx4 v[166:167], v[178:181], off offset:256 sc1
	v_pk_add_f32 v[182:183], v[114:115], v[138:139]
	v_pk_add_f32 v[184:185], v[112:113], v[136:137]
	v_pk_add_f32 v[178:179], v[118:119], v[142:143]
	v_pk_add_f32 v[180:181], v[116:117], v[140:141]
	v_mul_f32_e32 v178, 0xbfb8aa3b, v178
	v_exp_f32_e32 v178, v178
	v_mul_f32_e32 v165, 0xbfb8aa3b, v180
	v_mul_f32_e32 v180, 0xbfb8aa3b, v184
	v_mul_f32_e32 v184, 0xbfb8aa3b, v185
	v_add_f32_e32 v178, 1.0, v178
	v_rcp_f32_e32 v185, v178
	v_mul_f32_e32 v178, 0xbfb8aa3b, v182
	v_exp_f32_e32 v178, v178
	v_mul_f32_e32 v181, 0xbfb8aa3b, v181
	v_exp_f32_e32 v165, v165
	v_exp_f32_e32 v180, v180
	v_add_f32_e32 v178, 1.0, v178
	v_rcp_f32_e32 v182, v178
	v_mul_f32_e32 v178, 0xbfb8aa3b, v179
	v_exp_f32_e32 v178, v178
	v_exp_f32_e32 v181, v181
	v_exp_f32_e32 v184, v184
	v_add_f32_e32 v165, 1.0, v165
	v_add_f32_e32 v178, 1.0, v178
	v_rcp_f32_e32 v179, v178
	v_mul_f32_e32 v178, 0xbfb8aa3b, v183
	v_exp_f32_e32 v178, v178
	v_add_f32_e32 v180, 1.0, v180
	v_add_f32_e32 v181, 1.0, v181
	v_add_f32_e32 v184, 1.0, v184
	v_add_f32_e32 v178, 1.0, v178
	v_or_b32_e32 v170, 16, v164
	v_rcp_f32_e32 v165, v165
	v_rcp_f32_e32 v180, v180
	v_rcp_f32_e32 v181, v181
	v_rcp_f32_e32 v184, v184
	v_rcp_f32_e32 v183, v178
	v_ashrrev_i32_e32 v171, 31, v170
	v_lshlrev_b64 v[170:171], 13, v[170:171]
	v_lshl_add_u64 v[170:171], s[20:21], 0, v[170:171]
	v_lshl_add_u64 v[170:171], v[170:171], 0, v[168:169]
	v_cvt_pk_bf16_f32 v178, v165, v181
	v_cvt_pk_bf16_f32 v179, v185, v179
	v_cvt_pk_bf16_f32 v180, v180, v184
	v_cvt_pk_bf16_f32 v181, v182, v183
	global_store_dwordx4 v[170:171], v[178:181], off sc1
	v_pk_add_f32 v[182:183], v[90:91], v[130:131]
	v_pk_add_f32 v[184:185], v[88:89], v[128:129]
	v_pk_add_f32 v[178:179], v[94:95], v[134:135]
	v_pk_add_f32 v[180:181], v[92:93], v[132:133]
	v_mul_f32_e32 v178, 0xbfb8aa3b, v178
	v_exp_f32_e32 v178, v178
	v_mul_f32_e32 v165, 0xbfb8aa3b, v180
	v_mul_f32_e32 v180, 0xbfb8aa3b, v184
	v_mul_f32_e32 v184, 0xbfb8aa3b, v185
	v_add_f32_e32 v178, 1.0, v178
	v_rcp_f32_e32 v185, v178
	v_mul_f32_e32 v178, 0xbfb8aa3b, v182
	v_exp_f32_e32 v178, v178
	v_mul_f32_e32 v181, 0xbfb8aa3b, v181
	v_exp_f32_e32 v165, v165
	v_exp_f32_e32 v180, v180
	v_add_f32_e32 v178, 1.0, v178
	v_rcp_f32_e32 v182, v178
; __device__ __forceinline__ float sigmoidf_(float x) { return __builtin_amdgcn_rcpf(1.0f + __expf(-x)); }
; __device__ __forceinline__ u32x4 pack8f(f32x4 v0, f32x4 v1) { u32x4 w; w.x = cvt_pk_bf16(v0[0], v0[1]); w.y = cvt_pk_bf16(v0[2], v0[3]); w.z = cvt_pk_bf16(v1[0], v1[1]); w.w = cvt_pk_bf16(v1[2], v1[3]); return w; }
;     __device__ __forceinline__ void operator()(const f32x4 (&acc)[2][2][4][2], const Unit& u, int wr, int wc, int fr, int fq) const {
;     ...
;                 for (int m = 0; m < 4; ++m) { bf16_t* rowp = GT + (size_t)(row0 + ai * HALF + m * 16) * 4096 + c0;
; #pragma unroll
;                     for (int bj = 0; bj < 2; ++bj) { f32x4 v0 = acc[ai][bj][m][0] + bv[bj][0], v1 = acc[ai][bj][m][1] + bv[bj][1];
; #pragma unroll
;                         for (int e = 0; e < 4; ++e) { v0[e] = sigmoidf_(v0[e]); v1[e] = sigmoidf_(v1[e]); }
;                         *(u32x4*)(rowp + bj * HALF) = pack8f(v0, v1); } }
	v_mul_f32_e32 v178, 0xbfb8aa3b, v179
	v_exp_f32_e32 v178, v178
	v_exp_f32_e32 v181, v181
	v_exp_f32_e32 v184, v184
	v_add_f32_e32 v165, 1.0, v165
	v_add_f32_e32 v178, 1.0, v178
	v_rcp_f32_e32 v179, v178
	v_mul_f32_e32 v178, 0xbfb8aa3b, v183
	v_exp_f32_e32 v178, v178
	v_add_f32_e32 v180, 1.0, v180
	v_add_f32_e32 v181, 1.0, v181
	v_add_f32_e32 v184, 1.0, v184
	v_add_f32_e32 v178, 1.0, v178
	v_rcp_f32_e32 v165, v165
	v_rcp_f32_e32 v180, v180
	v_rcp_f32_e32 v181, v181
	v_rcp_f32_e32 v184, v184
	v_rcp_f32_e32 v183, v178
	v_cvt_pk_bf16_f32 v179, v185, v179
	v_cvt_pk_bf16_f32 v178, v165, v181
	v_cvt_pk_bf16_f32 v180, v180, v184
	v_cvt_pk_bf16_f32 v181, v182, v183
	global_store_dwordx4 v[170:171], v[178:181], off offset:256 sc1
	v_pk_add_f32 v[182:183], v[98:99], v[138:139]
	v_pk_add_f32 v[184:185], v[96:97], v[136:137]
	v_pk_add_f32 v[178:179], v[102:103], v[142:143]
	v_pk_add_f32 v[180:181], v[100:101], v[140:141]
	v_mul_f32_e32 v178, 0xbfb8aa3b, v178
	v_exp_f32_e32 v178, v178
	v_mul_f32_e32 v165, 0xbfb8aa3b, v180
	v_mul_f32_e32 v180, 0xbfb8aa3b, v184
	v_mul_f32_e32 v184, 0xbfb8aa3b, v185
	v_add_f32_e32 v178, 1.0, v178
	v_rcp_f32_e32 v185, v178
	v_mul_f32_e32 v178, 0xbfb8aa3b, v182
	v_exp_f32_e32 v178, v178
	v_mul_f32_e32 v181, 0xbfb8aa3b, v181
	v_exp_f32_e32 v165, v165
	v_exp_f32_e32 v180, v180
	v_add_f32_e32 v178, 1.0, v178
	v_rcp_f32_e32 v182, v178
	v_mul_f32_e32 v178, 0xbfb8aa3b, v179
	v_exp_f32_e32 v178, v178
	v_exp_f32_e32 v181, v181
	v_exp_f32_e32 v184, v184
	v_add_f32_e32 v165, 1.0, v165
	v_add_f32_e32 v178, 1.0, v178
	v_rcp_f32_e32 v179, v178
	v_mul_f32_e32 v178, 0xbfb8aa3b, v183
	v_exp_f32_e32 v178, v178
	v_add_f32_e32 v180, 1.0, v180
	v_add_f32_e32 v181, 1.0, v181
	v_add_f32_e32 v184, 1.0, v184
	v_add_f32_e32 v178, 1.0, v178
	v_or_b32_e32 v170, 32, v164
	v_rcp_f32_e32 v165, v165
	v_rcp_f32_e32 v180, v180
	v_rcp_f32_e32 v181, v181
	v_rcp_f32_e32 v184, v184
	v_rcp_f32_e32 v183, v178
	v_ashrrev_i32_e32 v171, 31, v170
	v_lshlrev_b64 v[170:171], 13, v[170:171]
	v_lshl_add_u64 v[170:171], s[20:21], 0, v[170:171]
	v_lshl_add_u64 v[170:171], v[170:171], 0, v[168:169]
	v_cvt_pk_bf16_f32 v178, v165, v181
	v_cvt_pk_bf16_f32 v179, v185, v179
	v_cvt_pk_bf16_f32 v180, v180, v184
	v_cvt_pk_bf16_f32 v181, v182, v183
	global_store_dwordx4 v[170:171], v[178:181], off sc1
	v_pk_add_f32 v[182:183], v[74:75], v[130:131]
	v_pk_add_f32 v[184:185], v[72:73], v[128:129]
	v_pk_add_f32 v[178:179], v[78:79], v[134:135]
	v_pk_add_f32 v[180:181], v[76:77], v[132:133]
	v_mul_f32_e32 v178, 0xbfb8aa3b, v178
	v_exp_f32_e32 v178, v178
	v_mul_f32_e32 v165, 0xbfb8aa3b, v180
	v_mul_f32_e32 v180, 0xbfb8aa3b, v184
	v_mul_f32_e32 v184, 0xbfb8aa3b, v185
	v_add_f32_e32 v178, 1.0, v178
	v_rcp_f32_e32 v185, v178
	v_mul_f32_e32 v178, 0xbfb8aa3b, v182
	v_exp_f32_e32 v178, v178
	v_mul_f32_e32 v181, 0xbfb8aa3b, v181
	v_exp_f32_e32 v165, v165
	v_exp_f32_e32 v180, v180
	v_add_f32_e32 v178, 1.0, v178
	v_rcp_f32_e32 v182, v178
	v_mul_f32_e32 v178, 0xbfb8aa3b, v179
	v_exp_f32_e32 v178, v178
	v_exp_f32_e32 v181, v181
	v_exp_f32_e32 v184, v184
	v_add_f32_e32 v165, 1.0, v165
	v_add_f32_e32 v178, 1.0, v178
	v_rcp_f32_e32 v179, v178
	v_mul_f32_e32 v178, 0xbfb8aa3b, v183
	v_exp_f32_e32 v178, v178
	v_add_f32_e32 v180, 1.0, v180
	v_add_f32_e32 v181, 1.0, v181
	v_add_f32_e32 v184, 1.0, v184
	v_add_f32_e32 v178, 1.0, v178
	v_rcp_f32_e32 v165, v165
	v_rcp_f32_e32 v180, v180
	v_rcp_f32_e32 v181, v181
	v_rcp_f32_e32 v184, v184
	v_rcp_f32_e32 v183, v178
	v_cvt_pk_bf16_f32 v179, v185, v179
	v_cvt_pk_bf16_f32 v178, v165, v181
	v_cvt_pk_bf16_f32 v180, v180, v184
	v_cvt_pk_bf16_f32 v181, v182, v183
	global_store_dwordx4 v[170:171], v[178:181], off offset:256 sc1
	v_pk_add_f32 v[182:183], v[80:81], v[136:137]
	v_or_b32_e32 v170, 48, v164
	v_pk_add_f32 v[178:179], v[84:85], v[140:141]
	v_pk_add_f32 v[180:181], v[82:83], v[138:139]
	v_mul_f32_e32 v165, 0xbfb8aa3b, v178
	v_mul_f32_e32 v178, 0xbfb8aa3b, v182
	v_exp_f32_e32 v178, v178
	v_ashrrev_i32_e32 v171, 31, v170
	v_lshlrev_b64 v[170:171], 13, v[170:171]
	v_lshl_add_u64 v[170:171], s[20:21], 0, v[170:171]
	v_add_f32_e32 v178, 1.0, v178
	v_rcp_f32_e32 v182, v178
	v_mul_f32_e32 v178, 0xbfb8aa3b, v179
	v_mul_f32_e32 v179, 0xbfb8aa3b, v183
	v_exp_f32_e32 v179, v179
	v_lshl_add_u64 v[168:169], v[170:171], 0, v[168:169]
	v_pk_add_f32 v[170:171], v[86:87], v[142:143]
	v_exp_f32_e32 v165, v165
	v_add_f32_e32 v179, 1.0, v179
	v_rcp_f32_e32 v183, v179
	v_mul_f32_e32 v179, 0xbfb8aa3b, v180
	v_exp_f32_e32 v179, v179
	v_mul_f32_e32 v170, 0xbfb8aa3b, v170
	v_mul_f32_e32 v171, 0xbfb8aa3b, v171
	v_exp_f32_e32 v178, v178
	v_add_f32_e32 v179, 1.0, v179
	v_rcp_f32_e32 v184, v179
	v_mul_f32_e32 v179, 0xbfb8aa3b, v181
	v_exp_f32_e32 v170, v170
	v_exp_f32_e32 v171, v171
	v_exp_f32_e32 v179, v179
	v_add_f32_e32 v165, 1.0, v165
	v_add_f32_e32 v178, 1.0, v178
	v_add_f32_e32 v170, 1.0, v170
	v_add_f32_e32 v171, 1.0, v171
	v_add_f32_e32 v179, 1.0, v179
	v_rcp_f32_e32 v165, v165
	v_rcp_f32_e32 v178, v178
	v_rcp_f32_e32 v170, v170
	v_rcp_f32_e32 v171, v171
	v_rcp_f32_e32 v181, v179
	v_cvt_pk_bf16_f32 v178, v165, v178
	v_cvt_pk_bf16_f32 v180, v182, v183
	v_cvt_pk_bf16_f32 v179, v170, v171
	v_cvt_pk_bf16_f32 v181, v184, v181
	global_store_dwordx4 v[168:169], v[178:181], off sc1
	v_pk_add_f32 v[182:183], v[64:65], v[128:129]
	v_pk_add_f32 v[170:171], v[70:71], v[134:135]
	v_pk_add_f32 v[178:179], v[68:69], v[132:133]
	v_pk_add_f32 v[180:181], v[66:67], v[130:131]
	v_mul_f32_e32 v165, 0xbfb8aa3b, v178
	v_mul_f32_e32 v178, 0xbfb8aa3b, v182
	v_exp_f32_e32 v178, v178
	v_mul_f32_e32 v170, 0xbfb8aa3b, v170
	v_mul_f32_e32 v171, 0xbfb8aa3b, v171
	v_exp_f32_e32 v165, v165
	v_add_f32_e32 v178, 1.0, v178
; __device__ __forceinline__ float sigmoidf_(float x) { return __builtin_amdgcn_rcpf(1.0f + __expf(-x)); }
; __device__ __forceinline__ u32x4 pack8f(f32x4 v0, f32x4 v1) { u32x4 w; w.x = cvt_pk_bf16(v0[0], v0[1]); w.y = cvt_pk_bf16(v0[2], v0[3]); w.z = cvt_pk_bf16(v1[0], v1[1]); w.w = cvt_pk_bf16(v1[2], v1[3]); return w; }
;     __device__ __forceinline__ void operator()(const f32x4 (&acc)[2][2][4][2], const Unit& u, int wr, int wc, int fr, int fq) const {
;     ...
;                 for (int m = 0; m < 4; ++m) { bf16_t* rowp = GT + (size_t)(row0 + ai * HALF + m * 16) * 4096 + c0;
; #pragma unroll
;                     for (int bj = 0; bj < 2; ++bj) { f32x4 v0 = acc[ai][bj][m][0] + bv[bj][0], v1 = acc[ai][bj][m][1] + bv[bj][1];
; #pragma unroll
;                         for (int e = 0; e < 4; ++e) { v0[e] = sigmoidf_(v0[e]); v1[e] = sigmoidf_(v1[e]); }
;                         *(u32x4*)(rowp + bj * HALF) = pack8f(v0, v1); } }
	v_rcp_f32_e32 v182, v178
	v_mul_f32_e32 v178, 0xbfb8aa3b, v179
	v_mul_f32_e32 v179, 0xbfb8aa3b, v183
	v_exp_f32_e32 v179, v179
	v_exp_f32_e32 v178, v178
	v_exp_f32_e32 v170, v170
	v_exp_f32_e32 v171, v171
	v_add_f32_e32 v179, 1.0, v179
	v_rcp_f32_e32 v183, v179
	v_mul_f32_e32 v179, 0xbfb8aa3b, v180
	v_exp_f32_e32 v179, v179
	v_add_f32_e32 v165, 1.0, v165
	v_add_f32_e32 v178, 1.0, v178
	v_add_f32_e32 v170, 1.0, v170
	v_add_f32_e32 v179, 1.0, v179
	v_rcp_f32_e32 v184, v179
	v_mul_f32_e32 v179, 0xbfb8aa3b, v181
	v_exp_f32_e32 v179, v179
	v_add_f32_e32 v171, 1.0, v171
	v_rcp_f32_e32 v165, v165
	v_rcp_f32_e32 v178, v178
	v_add_f32_e32 v179, 1.0, v179
	v_rcp_f32_e32 v170, v170
	v_rcp_f32_e32 v171, v171
	v_rcp_f32_e32 v181, v179
	v_cvt_pk_bf16_f32 v178, v165, v178
	v_cvt_pk_bf16_f32 v180, v182, v183
	v_cvt_pk_bf16_f32 v179, v170, v171
	v_cvt_pk_bf16_f32 v181, v184, v181
	global_store_dwordx4 v[168:169], v[178:181], off offset:256 sc1
	v_pk_add_f32 v[182:183], v[56:57], v[136:137]
	v_pk_add_f32 v[170:171], v[62:63], v[142:143]
	v_pk_add_f32 v[178:179], v[60:61], v[140:141]
	v_pk_add_f32 v[180:181], v[58:59], v[138:139]
	v_mul_f32_e32 v165, 0xbfb8aa3b, v178
	v_mul_f32_e32 v178, 0xbfb8aa3b, v182
	v_exp_f32_e32 v178, v178
	v_mul_f32_e32 v170, 0xbfb8aa3b, v170
	v_mul_f32_e32 v171, 0xbfb8aa3b, v171
	v_exp_f32_e32 v170, v170
	v_add_f32_e32 v178, 1.0, v178
	v_rcp_f32_e32 v182, v178
	v_mul_f32_e32 v178, 0xbfb8aa3b, v179
	v_mul_f32_e32 v179, 0xbfb8aa3b, v183
	v_exp_f32_e32 v179, v179
	v_exp_f32_e32 v171, v171
	v_exp_f32_e32 v165, v165
	v_exp_f32_e32 v178, v178
	v_add_f32_e32 v179, 1.0, v179
	v_rcp_f32_e32 v183, v179
	v_mul_f32_e32 v179, 0xbfb8aa3b, v180
	v_exp_f32_e32 v179, v179
	v_add_f32_e32 v170, 1.0, v170
	v_add_f32_e32 v171, 1.0, v171
	v_add_f32_e32 v165, 1.0, v165
	v_add_f32_e32 v179, 1.0, v179
	v_rcp_f32_e32 v184, v179
	v_mul_f32_e32 v179, 0xbfb8aa3b, v181
	v_exp_f32_e32 v179, v179
	v_add_f32_e32 v178, 1.0, v178
	v_rcp_f32_e32 v170, v170
	v_rcp_f32_e32 v171, v171
	v_add_f32_e32 v179, 1.0, v179
	v_rcp_f32_e32 v165, v165
	v_rcp_f32_e32 v178, v178
	v_rcp_f32_e32 v181, v179
	v_cvt_pk_bf16_f32 v179, v170, v171
	v_add_co_u32_e32 v170, vcc, s29, v166
	v_cvt_pk_bf16_f32 v178, v165, v178
	v_cvt_pk_bf16_f32 v180, v182, v183
	v_cvt_pk_bf16_f32 v181, v184, v181
	v_addc_co_u32_e32 v171, vcc, 0, v167, vcc
	global_store_dwordx4 v[170:171], v[178:181], off sc1
	v_pk_add_f32 v[182:183], v[40:41], v[128:129]
	v_pk_add_f32 v[170:171], v[46:47], v[134:135]
	v_pk_add_f32 v[178:179], v[44:45], v[132:133]
	v_pk_add_f32 v[180:181], v[42:43], v[130:131]
	v_mul_f32_e32 v165, 0xbfb8aa3b, v178
	v_mul_f32_e32 v178, 0xbfb8aa3b, v182
	v_exp_f32_e32 v178, v178
	v_mul_f32_e32 v170, 0xbfb8aa3b, v170
	v_mul_f32_e32 v171, 0xbfb8aa3b, v171
	v_exp_f32_e32 v165, v165
	v_add_f32_e32 v178, 1.0, v178
	v_rcp_f32_e32 v182, v178
	v_mul_f32_e32 v178, 0xbfb8aa3b, v179
	v_mul_f32_e32 v179, 0xbfb8aa3b, v183
	v_exp_f32_e32 v179, v179
	v_exp_f32_e32 v178, v178
	v_exp_f32_e32 v170, v170
	v_exp_f32_e32 v171, v171
	v_add_f32_e32 v179, 1.0, v179
	v_rcp_f32_e32 v183, v179
	v_mul_f32_e32 v179, 0xbfb8aa3b, v180
	v_exp_f32_e32 v179, v179
	v_add_f32_e32 v165, 1.0, v165
	v_add_f32_e32 v178, 1.0, v178
	v_add_f32_e32 v170, 1.0, v170
	v_add_f32_e32 v179, 1.0, v179
	v_rcp_f32_e32 v184, v179
	v_mul_f32_e32 v179, 0xbfb8aa3b, v181
	v_exp_f32_e32 v179, v179
	v_add_f32_e32 v171, 1.0, v171
	v_rcp_f32_e32 v165, v165
	v_rcp_f32_e32 v178, v178
	v_add_f32_e32 v179, 1.0, v179
	v_rcp_f32_e32 v170, v170
	v_rcp_f32_e32 v171, v171
	v_rcp_f32_e32 v181, v179
	v_lshl_add_u64 v[168:169], v[166:167], 0, s[36:37]
	v_cvt_pk_bf16_f32 v178, v165, v178
	v_cvt_pk_bf16_f32 v179, v170, v171
	v_cvt_pk_bf16_f32 v180, v182, v183
	v_cvt_pk_bf16_f32 v181, v184, v181
	global_store_dwordx4 v[168:169], v[178:181], off offset:256 sc1
	v_pk_add_f32 v[182:183], v[48:49], v[136:137]
	v_pk_add_f32 v[170:171], v[54:55], v[142:143]
	v_pk_add_f32 v[178:179], v[52:53], v[140:141]
	v_pk_add_f32 v[180:181], v[50:51], v[138:139]
	v_mul_f32_e32 v165, 0xbfb8aa3b, v178
	v_mul_f32_e32 v178, 0xbfb8aa3b, v182
	v_exp_f32_e32 v178, v178
	v_mul_f32_e32 v170, 0xbfb8aa3b, v170
	v_mul_f32_e32 v171, 0xbfb8aa3b, v171
	v_exp_f32_e32 v170, v170
	v_add_f32_e32 v178, 1.0, v178
	v_rcp_f32_e32 v182, v178
	v_mul_f32_e32 v178, 0xbfb8aa3b, v179
	v_mul_f32_e32 v179, 0xbfb8aa3b, v183
	v_exp_f32_e32 v179, v179
	v_exp_f32_e32 v171, v171
	v_exp_f32_e32 v165, v165
	v_exp_f32_e32 v178, v178
	v_add_f32_e32 v179, 1.0, v179
	v_rcp_f32_e32 v183, v179
	v_mul_f32_e32 v179, 0xbfb8aa3b, v180
	v_exp_f32_e32 v179, v179
	v_add_f32_e32 v170, 1.0, v170
	v_add_f32_e32 v171, 1.0, v171
	v_add_f32_e32 v165, 1.0, v165
	v_add_f32_e32 v179, 1.0, v179
	v_rcp_f32_e32 v184, v179
	v_mul_f32_e32 v179, 0xbfb8aa3b, v181
	v_exp_f32_e32 v179, v179
	v_add_f32_e32 v178, 1.0, v178
	v_rcp_f32_e32 v170, v170
	v_rcp_f32_e32 v171, v171
	v_add_f32_e32 v179, 1.0, v179
	v_rcp_f32_e32 v165, v165
	v_rcp_f32_e32 v178, v178
	v_rcp_f32_e32 v181, v179
	s_mov_b32 s29, 0x120000
	v_cvt_pk_bf16_f32 v179, v170, v171
	v_add_co_u32_e32 v170, vcc, s29, v166
	v_cvt_pk_bf16_f32 v178, v165, v178
	v_cvt_pk_bf16_f32 v180, v182, v183
	v_cvt_pk_bf16_f32 v181, v184, v181
	v_addc_co_u32_e32 v171, vcc, 0, v167, vcc
	global_store_dwordx4 v[170:171], v[178:181], off sc1
	v_pk_add_f32 v[182:183], v[24:25], v[128:129]
	v_pk_add_f32 v[170:171], v[30:31], v[134:135]
	v_pk_add_f32 v[178:179], v[28:29], v[132:133]
	v_pk_add_f32 v[180:181], v[26:27], v[130:131]
	v_mul_f32_e32 v165, 0xbfb8aa3b, v178
	v_mul_f32_e32 v178, 0xbfb8aa3b, v182
	v_exp_f32_e32 v178, v178
	v_mul_f32_e32 v170, 0xbfb8aa3b, v170
	v_mul_f32_e32 v171, 0xbfb8aa3b, v171
	v_exp_f32_e32 v165, v165
; __device__ __forceinline__ float sigmoidf_(float x) { return __builtin_amdgcn_rcpf(1.0f + __expf(-x)); }
; __device__ __forceinline__ u32x4 pack8f(f32x4 v0, f32x4 v1) { u32x4 w; w.x = cvt_pk_bf16(v0[0], v0[1]); w.y = cvt_pk_bf16(v0[2], v0[3]); w.z = cvt_pk_bf16(v1[0], v1[1]); w.w = cvt_pk_bf16(v1[2], v1[3]); return w; }
;     __device__ __forceinline__ void operator()(const f32x4 (&acc)[2][2][4][2], const Unit& u, int wr, int wc, int fr, int fq) const {
;     ...
;                 for (int m = 0; m < 4; ++m) { bf16_t* rowp = GT + (size_t)(row0 + ai * HALF + m * 16) * 4096 + c0;
; #pragma unroll
;                     for (int bj = 0; bj < 2; ++bj) { f32x4 v0 = acc[ai][bj][m][0] + bv[bj][0], v1 = acc[ai][bj][m][1] + bv[bj][1];
; #pragma unroll
;                         for (int e = 0; e < 4; ++e) { v0[e] = sigmoidf_(v0[e]); v1[e] = sigmoidf_(v1[e]); }
;                         *(u32x4*)(rowp + bj * HALF) = pack8f(v0, v1); } }
	v_add_f32_e32 v178, 1.0, v178
	v_rcp_f32_e32 v182, v178
	v_mul_f32_e32 v178, 0xbfb8aa3b, v179
	v_mul_f32_e32 v179, 0xbfb8aa3b, v183
	v_exp_f32_e32 v179, v179
	v_exp_f32_e32 v178, v178
	v_exp_f32_e32 v170, v170
	v_exp_f32_e32 v171, v171
	v_add_f32_e32 v179, 1.0, v179
	v_rcp_f32_e32 v183, v179
	v_mul_f32_e32 v179, 0xbfb8aa3b, v180
	v_exp_f32_e32 v179, v179
	v_add_f32_e32 v165, 1.0, v165
	v_add_f32_e32 v178, 1.0, v178
	v_add_f32_e32 v170, 1.0, v170
	v_add_f32_e32 v179, 1.0, v179
	v_rcp_f32_e32 v184, v179
	v_mul_f32_e32 v179, 0xbfb8aa3b, v181
	v_exp_f32_e32 v179, v179
	v_add_f32_e32 v171, 1.0, v171
	v_rcp_f32_e32 v165, v165
	v_rcp_f32_e32 v178, v178
	v_add_f32_e32 v179, 1.0, v179
	v_rcp_f32_e32 v170, v170
	v_rcp_f32_e32 v171, v171
	v_rcp_f32_e32 v181, v179
	s_mov_b64 s[36:37], 0x120000
	v_lshl_add_u64 v[168:169], v[166:167], 0, s[36:37]
	v_cvt_pk_bf16_f32 v178, v165, v178
	v_cvt_pk_bf16_f32 v179, v170, v171
	v_cvt_pk_bf16_f32 v180, v182, v183
	v_cvt_pk_bf16_f32 v181, v184, v181
	global_store_dwordx4 v[168:169], v[178:181], off offset:256 sc1
	v_pk_add_f32 v[182:183], v[32:33], v[136:137]
	v_pk_add_f32 v[170:171], v[38:39], v[142:143]
	v_pk_add_f32 v[178:179], v[36:37], v[140:141]
	v_pk_add_f32 v[180:181], v[34:35], v[138:139]
	v_mul_f32_e32 v165, 0xbfb8aa3b, v178
	v_mul_f32_e32 v178, 0xbfb8aa3b, v182
	v_exp_f32_e32 v178, v178
	v_mul_f32_e32 v170, 0xbfb8aa3b, v170
	v_mul_f32_e32 v171, 0xbfb8aa3b, v171
	v_exp_f32_e32 v170, v170
	v_add_f32_e32 v178, 1.0, v178
	v_rcp_f32_e32 v182, v178
	v_mul_f32_e32 v178, 0xbfb8aa3b, v179
	v_mul_f32_e32 v179, 0xbfb8aa3b, v183
	v_exp_f32_e32 v179, v179
	v_exp_f32_e32 v171, v171
	v_exp_f32_e32 v165, v165
	v_exp_f32_e32 v178, v178
	v_add_f32_e32 v179, 1.0, v179
	v_rcp_f32_e32 v183, v179
	v_mul_f32_e32 v179, 0xbfb8aa3b, v180
	v_exp_f32_e32 v179, v179
	v_add_f32_e32 v170, 1.0, v170
	v_add_f32_e32 v171, 1.0, v171
	v_add_f32_e32 v165, 1.0, v165
	v_add_f32_e32 v179, 1.0, v179
	v_rcp_f32_e32 v184, v179
	v_mul_f32_e32 v179, 0xbfb8aa3b, v181
	v_exp_f32_e32 v179, v179
	v_add_f32_e32 v178, 1.0, v178
	v_rcp_f32_e32 v170, v170
	v_rcp_f32_e32 v171, v171
	v_add_f32_e32 v179, 1.0, v179
	v_rcp_f32_e32 v165, v165
	v_rcp_f32_e32 v178, v178
	v_rcp_f32_e32 v181, v179
	s_mov_b32 s29, 0x140000
	v_cvt_pk_bf16_f32 v179, v170, v171
	v_add_co_u32_e32 v170, vcc, s29, v166
	v_cvt_pk_bf16_f32 v178, v165, v178
	v_cvt_pk_bf16_f32 v180, v182, v183
	v_cvt_pk_bf16_f32 v181, v184, v181
	v_addc_co_u32_e32 v171, vcc, 0, v167, vcc
	global_store_dwordx4 v[170:171], v[178:181], off sc1
	v_pk_add_f32 v[182:183], v[8:9], v[128:129]
	v_pk_add_f32 v[136:137], v[16:17], v[136:137]
	v_pk_add_f32 v[178:179], v[12:13], v[132:133]
	v_pk_add_f32 v[138:139], v[18:19], v[138:139]
	v_mul_f32_e32 v165, 0xbfb8aa3b, v178
	v_mul_f32_e32 v178, 0xbfb8aa3b, v182
	v_exp_f32_e32 v178, v178
	v_exp_f32_e32 v165, v165
	v_mul_f32_e32 v136, 0xbfb8aa3b, v136
	v_exp_f32_e32 v136, v136
	v_add_f32_e32 v178, 1.0, v178
	v_rcp_f32_e32 v182, v178
	v_mul_f32_e32 v178, 0xbfb8aa3b, v179
	v_exp_f32_e32 v178, v178
	v_add_f32_e32 v165, 1.0, v165
	v_mul_f32_e32 v137, 0xbfb8aa3b, v137
	v_mul_f32_e32 v138, 0xbfb8aa3b, v138
	v_add_f32_e32 v178, 1.0, v178
	v_rcp_f32_e32 v165, v165
	v_rcp_f32_e32 v178, v178
	v_exp_f32_e32 v137, v137
	v_exp_f32_e32 v138, v138
	v_mul_f32_e32 v179, 0xbfb8aa3b, v183
	v_pk_add_f32 v[140:141], v[20:21], v[140:141]
	v_add_f32_e32 v136, 1.0, v136
	v_exp_f32_e32 v179, v179
	v_cvt_pk_bf16_f32 v178, v165, v178
	v_pk_add_f32 v[142:143], v[22:23], v[142:143]
	v_mul_f32_e32 v140, 0xbfb8aa3b, v140
	v_rcp_f32_e32 v165, v136
	v_mul_f32_e32 v136, 0xbfb8aa3b, v141
	v_add_f32_e32 v137, 1.0, v137
	v_add_f32_e32 v138, 1.0, v138
	v_exp_f32_e32 v140, v140
	v_exp_f32_e32 v136, v136
	v_rcp_f32_e32 v141, v137
	v_mul_f32_e32 v137, 0xbfb8aa3b, v142
	v_rcp_f32_e32 v142, v138
	v_mul_f32_e32 v138, 0xbfb8aa3b, v143
	v_mul_f32_e32 v139, 0xbfb8aa3b, v139
	v_exp_f32_e32 v137, v137
	v_exp_f32_e32 v138, v138
	v_exp_f32_e32 v139, v139
	v_pk_add_f32 v[180:181], v[10:11], v[130:131]
	v_add_f32_e32 v179, 1.0, v179
	v_rcp_f32_e32 v183, v179
	v_mul_f32_e32 v179, 0xbfb8aa3b, v180
	v_add_f32_e32 v140, 1.0, v140
	v_add_f32_e32 v136, 1.0, v136
	v_pk_add_f32 v[130:131], v[2:3], v[130:131]
	v_pk_add_f32 v[128:129], v[0:1], v[128:129]
	v_exp_f32_e32 v179, v179
	v_rcp_f32_e32 v140, v140
	v_rcp_f32_e32 v136, v136
	v_add_f32_e32 v137, 1.0, v137
	v_add_f32_e32 v138, 1.0, v138
	v_add_f32_e32 v139, 1.0, v139
	v_mul_f32_e32 v128, 0xbfb8aa3b, v128
	v_mul_f32_e32 v129, 0xbfb8aa3b, v129
	v_mul_f32_e32 v130, 0xbfb8aa3b, v130
	v_rcp_f32_e32 v137, v137
	v_rcp_f32_e32 v138, v138
	v_rcp_f32_e32 v139, v139
	v_exp_f32_e32 v128, v128
	v_exp_f32_e32 v129, v129
	v_exp_f32_e32 v130, v130
	s_mov_b32 s29, 0x160000
	v_pk_add_f32 v[170:171], v[14:15], v[134:135]
	v_add_f32_e32 v179, 1.0, v179
	v_cvt_pk_bf16_f32 v136, v140, v136
	v_add_co_u32_e32 v140, vcc, s29, v166
	v_mul_f32_e32 v170, 0xbfb8aa3b, v170
	v_rcp_f32_e32 v184, v179
	v_mul_f32_e32 v171, 0xbfb8aa3b, v171
	v_mul_f32_e32 v179, 0xbfb8aa3b, v181
	v_cvt_pk_bf16_f32 v137, v137, v138
	v_cvt_pk_bf16_f32 v138, v165, v141
	v_cvt_pk_bf16_f32 v139, v142, v139
	v_addc_co_u32_e32 v141, vcc, 0, v167, vcc
	v_pk_add_f32 v[134:135], v[6:7], v[134:135]
	v_pk_add_f32 v[132:133], v[4:5], v[132:133]
	v_add_f32_e32 v128, 1.0, v128
	v_add_f32_e32 v129, 1.0, v129
	v_add_f32_e32 v130, 1.0, v130
	v_exp_f32_e32 v170, v170
	v_exp_f32_e32 v171, v171
	v_exp_f32_e32 v179, v179
	global_store_dwordx4 v[140:141], v[136:139], off sc1
	v_mul_f32_e32 v132, 0xbfb8aa3b, v132
	v_mul_f32_e32 v131, 0xbfb8aa3b, v131
	v_rcp_f32_e32 v136, v128
	v_mul_f32_e32 v128, 0xbfb8aa3b, v133
	v_rcp_f32_e32 v133, v129
	v_mul_f32_e32 v129, 0xbfb8aa3b, v134
	v_rcp_f32_e32 v134, v130
	v_mul_f32_e32 v130, 0xbfb8aa3b, v135
	v_exp_f32_e32 v132, v132
	v_exp_f32_e32 v128, v128
	v_exp_f32_e32 v129, v129
	v_exp_f32_e32 v130, v130
	v_exp_f32_e32 v131, v131
	v_add_f32_e32 v170, 1.0, v170
	v_add_f32_e32 v171, 1.0, v171
	v_add_f32_e32 v179, 1.0, v179
	v_rcp_f32_e32 v170, v170
	v_rcp_f32_e32 v171, v171
	v_rcp_f32_e32 v181, v179
	v_add_f32_e32 v132, 1.0, v132
	v_add_f32_e32 v128, 1.0, v128
	v_add_f32_e32 v129, 1.0, v129
	v_add_f32_e32 v130, 1.0, v130
	v_add_f32_e32 v131, 1.0, v131
	v_rcp_f32_e32 v132, v132
	v_rcp_f32_e32 v128, v128
	v_rcp_f32_e32 v129, v129
	v_rcp_f32_e32 v130, v130
	v_rcp_f32_e32 v131, v131
	s_mov_b64 s[36:37], 0x140000
	v_lshl_add_u64 v[168:169], v[166:167], 0, s[36:37]
	v_cvt_pk_bf16_f32 v179, v170, v171
	v_cvt_pk_bf16_f32 v180, v182, v183
	v_cvt_pk_bf16_f32 v181, v184, v181
	s_mov_b64 s[36:37], 0x160000
	global_store_dwordx4 v[168:169], v[178:181], off offset:256 sc1
	v_lshl_add_u64 v[168:169], v[166:167], 0, s[36:37]
	v_cvt_pk_bf16_f32 v128, v132, v128
	v_cvt_pk_bf16_f32 v129, v129, v130
	v_cvt_pk_bf16_f32 v130, v136, v133
	v_cvt_pk_bf16_f32 v131, v134, v131
	global_store_dwordx4 v[168:169], v[128:131], off offset:256 sc1
	s_mov_b64 s[36:37], 0
; __device__ __forceinline__ u32x4 pack8f(f32x4 v0, f32x4 v1) { u32x4 w; w.x = cvt_pk_bf16(v0[0], v0[1]); w.y = cvt_pk_bf16(v0[2], v0[3]); w.z = cvt_pk_bf16(v1[0], v1[1]); w.w = cvt_pk_bf16(v1[2], v1[3]); return w; }
;     __device__ __forceinline__ void operator()(const f32x4 (&acc)[2][2][4][2], const Unit& u, int wr, int wc, int fr, int fq) const {
;     ...
;             const int h = pn - 16;
; #pragma unroll
;             for (int ai = 0; ai < 2; ++ai)
; #pragma unroll
;                 for (int m = 0; m < 4; ++m) { const int r = row0 + ai * HALF + m * 16, b = r >> 13, s = r & 8191;
; #pragma unroll
;                     for (int bj = 0; bj < 2; ++bj) *(u32x4*)(VH + ((size_t)((b * 8 + h * 2 + bj) * 8192 + s)) * 128 + cin) = pack8f(acc[ai][bj][m][0], acc[ai][bj][m][1]); }
.LBB0_179:
	s_andn2_b64 vcc, exec, s[36:37]
	s_cbranch_vccnz .LBB0_181
	s_lshl_b32 s29, s64, 1
	s_lshr_b32 s27, s27, 10
	s_sub_i32 s29, s29, 32
	s_and_b32 s27, s27, 0x7fff8
	s_add_i32 s27, s27, s29
	v_and_b32_e32 v134, 0x1fcf, v164
	s_lshl_b32 s27, s27, 13
	v_or_b32_e32 v132, s27, v134
	v_ashrrev_i32_e32 v133, 31, v132
	v_lshlrev_b64 v[132:133], 8, v[132:133]
	v_cvt_pk_bf16_f32 v128, v124, v125
	v_cvt_pk_bf16_f32 v129, v126, v127
	v_cvt_pk_bf16_f32 v130, v120, v121
	v_cvt_pk_bf16_f32 v131, v122, v123
	v_lshl_add_u64 v[132:133], v[154:155], 0, v[132:133]
	s_or_b32 s36, s27, 0x2000
	global_store_dwordx4 v[132:133], v[128:131], off sc1
	v_or_b32_e32 v132, s36, v134
	v_ashrrev_i32_e32 v133, 31, v132
	v_lshlrev_b64 v[132:133], 8, v[132:133]
	v_cvt_pk_bf16_f32 v128, v108, v109
	v_cvt_pk_bf16_f32 v129, v110, v111
	v_cvt_pk_bf16_f32 v130, v104, v105
	v_cvt_pk_bf16_f32 v131, v106, v107
	v_lshl_add_u64 v[132:133], v[154:155], 0, v[132:133]
	v_or_b32_e32 v135, 16, v134
	global_store_dwordx4 v[132:133], v[128:131], off sc1
	v_or_b32_e32 v132, s27, v135
	v_ashrrev_i32_e32 v133, 31, v132
	v_lshlrev_b64 v[132:133], 8, v[132:133]
	v_cvt_pk_bf16_f32 v128, v116, v117
	v_cvt_pk_bf16_f32 v129, v118, v119
	v_cvt_pk_bf16_f32 v130, v112, v113
	v_cvt_pk_bf16_f32 v131, v114, v115
	v_lshl_add_u64 v[132:133], v[154:155], 0, v[132:133]
	global_store_dwordx4 v[132:133], v[128:131], off sc1
	v_or_b32_e32 v132, s36, v135
	v_ashrrev_i32_e32 v133, 31, v132
	v_lshlrev_b64 v[132:133], 8, v[132:133]
	v_cvt_pk_bf16_f32 v128, v92, v93
	v_cvt_pk_bf16_f32 v129, v94, v95
	v_cvt_pk_bf16_f32 v130, v88, v89
	v_cvt_pk_bf16_f32 v131, v90, v91
	v_lshl_add_u64 v[132:133], v[154:155], 0, v[132:133]
	v_or_b32_e32 v135, 32, v134
	global_store_dwordx4 v[132:133], v[128:131], off sc1
	v_or_b32_e32 v132, s27, v135
	v_ashrrev_i32_e32 v133, 31, v132
	v_lshlrev_b64 v[132:133], 8, v[132:133]
	v_cvt_pk_bf16_f32 v128, v100, v101
	v_cvt_pk_bf16_f32 v129, v102, v103
	v_cvt_pk_bf16_f32 v130, v96, v97
	v_cvt_pk_bf16_f32 v131, v98, v99
	v_lshl_add_u64 v[132:133], v[154:155], 0, v[132:133]
	global_store_dwordx4 v[132:133], v[128:131], off sc1
	v_or_b32_e32 v132, s36, v135
	v_ashrrev_i32_e32 v133, 31, v132
	v_lshlrev_b64 v[132:133], 8, v[132:133]
	v_cvt_pk_bf16_f32 v128, v76, v77
	v_cvt_pk_bf16_f32 v129, v78, v79
	v_cvt_pk_bf16_f32 v130, v72, v73
	v_cvt_pk_bf16_f32 v131, v74, v75
	v_lshl_add_u64 v[132:133], v[154:155], 0, v[132:133]
	v_or_b32_e32 v134, 48, v134
	global_store_dwordx4 v[132:133], v[128:131], off sc1
	v_or_b32_e32 v132, s27, v134
	v_ashrrev_i32_e32 v133, 31, v132
	v_lshlrev_b64 v[132:133], 8, v[132:133]
	v_cvt_pk_bf16_f32 v128, v84, v85
	v_cvt_pk_bf16_f32 v129, v86, v87
	v_cvt_pk_bf16_f32 v130, v80, v81
	v_cvt_pk_bf16_f32 v131, v82, v83
	v_lshl_add_u64 v[132:133], v[154:155], 0, v[132:133]
	global_store_dwordx4 v[132:133], v[128:131], off sc1
	v_or_b32_e32 v132, s36, v134
	v_ashrrev_i32_e32 v133, 31, v132
	v_lshlrev_b64 v[132:133], 8, v[132:133]
	v_cvt_pk_bf16_f32 v128, v68, v69
	v_cvt_pk_bf16_f32 v129, v70, v71
	v_cvt_pk_bf16_f32 v130, v64, v65
	v_cvt_pk_bf16_f32 v131, v66, v67
	v_lshl_add_u64 v[132:133], v[154:155], 0, v[132:133]
	global_store_dwordx4 v[132:133], v[128:131], off sc1
	s_nop 1
	v_add_u32_e32 v128, 0x80, v164
	v_and_b32_e32 v134, 0x1fcf, v128
	v_lshrrev_b32_e32 v128, 10, v128
	v_and_b32_e32 v132, 0x7fff8, v128
	v_add_lshl_u32 v135, v132, s29, 13
	v_or_b32_e32 v132, v135, v134
	v_ashrrev_i32_e32 v133, 31, v132
	v_lshlrev_b64 v[132:133], 8, v[132:133]
	v_cvt_pk_bf16_f32 v128, v60, v61
	v_cvt_pk_bf16_f32 v129, v62, v63
	v_cvt_pk_bf16_f32 v130, v56, v57
	v_cvt_pk_bf16_f32 v131, v58, v59
	v_lshl_add_u64 v[132:133], v[154:155], 0, v[132:133]
	v_or_b32_e32 v136, 0x2000, v135
	global_store_dwordx4 v[132:133], v[128:131], off sc1
	v_or_b32_e32 v132, v136, v134
	v_ashrrev_i32_e32 v133, 31, v132
	v_lshlrev_b64 v[132:133], 8, v[132:133]
	v_cvt_pk_bf16_f32 v128, v44, v45
	v_cvt_pk_bf16_f32 v129, v46, v47
	v_cvt_pk_bf16_f32 v130, v40, v41
	v_cvt_pk_bf16_f32 v131, v42, v43
	v_lshl_add_u64 v[132:133], v[154:155], 0, v[132:133]
	v_or_b32_e32 v137, 16, v134
	global_store_dwordx4 v[132:133], v[128:131], off sc1
	v_or_b32_e32 v132, v135, v137
	v_ashrrev_i32_e32 v133, 31, v132
	v_lshlrev_b64 v[132:133], 8, v[132:133]
	v_cvt_pk_bf16_f32 v128, v52, v53
	v_cvt_pk_bf16_f32 v129, v54, v55
	v_cvt_pk_bf16_f32 v130, v48, v49
	v_cvt_pk_bf16_f32 v131, v50, v51
	v_lshl_add_u64 v[132:133], v[154:155], 0, v[132:133]
	global_store_dwordx4 v[132:133], v[128:131], off sc1
	v_or_b32_e32 v132, v136, v137
	v_ashrrev_i32_e32 v133, 31, v132
	v_lshlrev_b64 v[132:133], 8, v[132:133]
	v_cvt_pk_bf16_f32 v128, v28, v29
	v_cvt_pk_bf16_f32 v129, v30, v31
	v_cvt_pk_bf16_f32 v130, v24, v25
	v_cvt_pk_bf16_f32 v131, v26, v27
	v_lshl_add_u64 v[132:133], v[154:155], 0, v[132:133]
	v_or_b32_e32 v137, 32, v134
	global_store_dwordx4 v[132:133], v[128:131], off sc1
	v_or_b32_e32 v132, v135, v137
	v_ashrrev_i32_e32 v133, 31, v132
	v_lshlrev_b64 v[132:133], 8, v[132:133]
	v_cvt_pk_bf16_f32 v128, v36, v37
	v_cvt_pk_bf16_f32 v129, v38, v39
	v_cvt_pk_bf16_f32 v130, v32, v33
	v_cvt_pk_bf16_f32 v131, v34, v35
	v_lshl_add_u64 v[132:133], v[154:155], 0, v[132:133]
	global_store_dwordx4 v[132:133], v[128:131], off sc1
	v_or_b32_e32 v132, v136, v137
	v_ashrrev_i32_e32 v133, 31, v132
	v_lshlrev_b64 v[132:133], 8, v[132:133]
	v_cvt_pk_bf16_f32 v128, v12, v13
	v_cvt_pk_bf16_f32 v129, v14, v15
	v_cvt_pk_bf16_f32 v130, v8, v9
	v_cvt_pk_bf16_f32 v131, v10, v11
	v_lshl_add_u64 v[132:133], v[154:155], 0, v[132:133]
	v_or_b32_e32 v134, 48, v134
	global_store_dwordx4 v[132:133], v[128:131], off sc1
	v_or_b32_e32 v132, v135, v134
	v_ashrrev_i32_e32 v133, 31, v132
	v_lshlrev_b64 v[132:133], 8, v[132:133]
	v_cvt_pk_bf16_f32 v128, v20, v21
	v_cvt_pk_bf16_f32 v129, v22, v23
	v_cvt_pk_bf16_f32 v130, v16, v17
	v_cvt_pk_bf16_f32 v131, v18, v19
	v_lshl_add_u64 v[132:133], v[154:155], 0, v[132:133]
	global_store_dwordx4 v[132:133], v[128:131], off sc1
	v_or_b32_e32 v132, v136, v134
	v_ashrrev_i32_e32 v133, 31, v132
	v_lshlrev_b64 v[132:133], 8, v[132:133]
	v_cvt_pk_bf16_f32 v128, v4, v5
	v_cvt_pk_bf16_f32 v129, v6, v7
	v_cvt_pk_bf16_f32 v130, v0, v1
	v_cvt_pk_bf16_f32 v131, v2, v3
	v_lshl_add_u64 v[132:133], v[154:155], 0, v[132:133]
	global_store_dwordx4 v[132:133], v[128:131], off sc1

; __device__ __forceinline__ u32x4 pack8f(f32x4 v0, f32x4 v1) { u32x4 w; w.x = cvt_pk_bf16(v0[0], v0[1]); w.y = cvt_pk_bf16(v0[2], v0[3]); w.z = cvt_pk_bf16(v1[0], v1[1]); w.w = cvt_pk_bf16(v1[2], v1[3]); return w; }
;     __device__ __forceinline__ void operator()(const f32x4 (&acc)[2][2][4][2], const Unit& u, int wr, int wc, int fr, int fq) const {
;     ...
;         if (pn < 16) {
;             bf16_t* base = (pn < 8 ? CG + pn * BM : QK + (pn - 8) * BM) + cin;
; #pragma unroll
;             for (int ai = 0; ai < 2; ++ai)
; #pragma unroll
;                 for (int m = 0; m < 4; ++m) { bf16_t* rowp = base + (size_t)(row0 + ai * HALF + m * 16) * 2048;
; #pragma unroll
;                     for (int bj = 0; bj < 2; ++bj) *(u32x4*)(rowp + bj * HALF) = pack8f(acc[ai][bj][m][0], acc[ai][bj][m][1]); }
.LBB0_182:
	s_lshl_b32 s36, s64, 8
	s_ashr_i32 s37, s36, 31
	s_lshl_b64 s[40:41], s[36:37], 1
	s_add_u32 s27, s56, s40
	s_mov_b32 s37, 0
	s_addc_u32 s29, s57, s41
	s_lshl_b64 s[36:37], s[36:37], 1
	s_add_u32 s36, s14, s36
	s_addc_u32 s37, s15, s37
	s_add_u32 s36, s36, 0x177ff000
	s_addc_u32 s37, s37, 0
	s_cmp_lt_i32 s64, 8
	s_cselect_b32 s37, s29, s37
	s_cselect_b32 s36, s27, s36
	v_ashrrev_i32_e32 v165, 31, v164
	v_lshl_add_u64 v[128:129], s[36:37], 0, v[152:153]
	v_lshlrev_b64 v[130:131], 12, v[164:165]
	v_lshl_add_u64 v[130:131], v[128:129], 0, v[130:131]
	s_mov_b32 s27, 0x80000
	s_mov_b64 s[36:37], 0x80000
	v_cvt_pk_bf16_f32 v60, v60, v61
	v_cvt_pk_bf16_f32 v61, v62, v63
	v_cvt_pk_bf16_f32 v62, v56, v57
	v_add_co_u32_e32 v56, vcc, s27, v130
	v_cvt_pk_bf16_f32 v68, v68, v69
	v_cvt_pk_bf16_f32 v69, v70, v71
	v_cvt_pk_bf16_f32 v70, v64, v65
	v_lshl_add_u64 v[64:65], v[130:131], 0, s[36:37]
	v_addc_co_u32_e32 v57, vcc, 0, v131, vcc
	v_cvt_pk_bf16_f32 v44, v44, v45
	v_cvt_pk_bf16_f32 v45, v46, v47
	v_cvt_pk_bf16_f32 v46, v40, v41
	v_cvt_pk_bf16_f32 v47, v42, v43
	s_mov_b32 s27, 0x90000
	v_cvt_pk_bf16_f32 v108, v108, v109
	v_cvt_pk_bf16_f32 v109, v110, v111
	v_cvt_pk_bf16_f32 v110, v104, v105
	v_or_b32_e32 v104, 16, v164
	global_store_dwordx4 v[64:65], v[44:47], off offset:256 sc1
	s_mov_b64 s[36:37], 0x90000
	v_ashrrev_i32_e32 v105, 31, v104
	v_add_co_u32_e32 v46, vcc, s27, v130
	v_cvt_pk_bf16_f32 v92, v92, v93
	v_cvt_pk_bf16_f32 v93, v94, v95
	v_cvt_pk_bf16_f32 v94, v88, v89
	v_or_b32_e32 v88, 32, v164
	v_lshl_add_u64 v[44:45], v[130:131], 0, s[36:37]
	v_addc_co_u32_e32 v47, vcc, 0, v131, vcc
	v_cvt_pk_bf16_f32 v28, v28, v29
	v_cvt_pk_bf16_f32 v29, v30, v31
	v_cvt_pk_bf16_f32 v30, v24, v25
	v_cvt_pk_bf16_f32 v31, v26, v27
	s_mov_b32 s27, 0xa0000
	v_cvt_pk_bf16_f32 v111, v106, v107
	v_lshlrev_b64 v[104:105], 12, v[104:105]
	v_ashrrev_i32_e32 v89, 31, v88
	v_cvt_pk_bf16_f32 v76, v76, v77
	v_cvt_pk_bf16_f32 v77, v78, v79
	v_cvt_pk_bf16_f32 v78, v72, v73
	v_or_b32_e32 v72, 48, v164
	global_store_dwordx4 v[44:45], v[28:31], off offset:256 sc1
	s_mov_b64 s[36:37], 0xa0000
	global_store_dwordx4 v[130:131], v[108:111], off offset:256 sc1
	v_add_co_u32_e32 v30, vcc, s27, v130
	s_nop 0
	v_lshl_add_u64 v[108:109], v[128:129], 0, v[104:105]
	v_cvt_pk_bf16_f32 v95, v90, v91
	v_lshlrev_b64 v[88:89], 12, v[88:89]
	v_ashrrev_i32_e32 v73, 31, v72
	v_lshl_add_u64 v[28:29], v[130:131], 0, s[36:37]
	v_addc_co_u32_e32 v31, vcc, 0, v131, vcc
	v_cvt_pk_bf16_f32 v12, v12, v13
	v_cvt_pk_bf16_f32 v13, v14, v15
	v_cvt_pk_bf16_f32 v14, v8, v9
	v_cvt_pk_bf16_f32 v15, v10, v11
	s_mov_b32 s27, 0xb0000
	global_store_dwordx4 v[108:109], v[92:95], off offset:256 sc1
	v_cvt_pk_bf16_f32 v79, v74, v75
	v_lshlrev_b64 v[72:73], 12, v[72:73]
	v_lshl_add_u64 v[92:93], v[128:129], 0, v[88:89]
	global_store_dwordx4 v[28:29], v[12:15], off offset:256 sc1
	s_mov_b64 s[36:37], 0xb0000
	v_cvt_pk_bf16_f32 v124, v124, v125
	v_add_co_u32_e32 v14, vcc, s27, v130
	v_cvt_pk_bf16_f32 v125, v126, v127
	v_cvt_pk_bf16_f32 v126, v120, v121
	v_cvt_pk_bf16_f32 v127, v122, v123
	v_cvt_pk_bf16_f32 v104, v116, v117
	v_cvt_pk_bf16_f32 v105, v118, v119
	v_cvt_pk_bf16_f32 v106, v112, v113
	v_cvt_pk_bf16_f32 v107, v114, v115
	v_cvt_pk_bf16_f32 v88, v100, v101
	v_cvt_pk_bf16_f32 v89, v102, v103
	v_cvt_pk_bf16_f32 v90, v96, v97
	v_cvt_pk_bf16_f32 v91, v98, v99
	global_store_dwordx4 v[92:93], v[76:79], off offset:256 sc1
	v_cvt_pk_bf16_f32 v74, v80, v81
	v_cvt_pk_bf16_f32 v75, v82, v83
	v_lshl_add_u64 v[76:77], v[128:129], 0, v[72:73]
	v_cvt_pk_bf16_f32 v72, v84, v85
	v_cvt_pk_bf16_f32 v73, v86, v87
	v_cvt_pk_bf16_f32 v71, v66, v67
	v_cvt_pk_bf16_f32 v63, v58, v59
	v_cvt_pk_bf16_f32 v40, v52, v53
	v_cvt_pk_bf16_f32 v41, v54, v55
	v_cvt_pk_bf16_f32 v42, v48, v49
	v_cvt_pk_bf16_f32 v43, v50, v51
	v_cvt_pk_bf16_f32 v24, v36, v37
	v_cvt_pk_bf16_f32 v25, v38, v39
	v_cvt_pk_bf16_f32 v26, v32, v33
	v_cvt_pk_bf16_f32 v27, v34, v35
	v_lshl_add_u64 v[12:13], v[130:131], 0, s[36:37]
	v_cvt_pk_bf16_f32 v8, v20, v21
	v_cvt_pk_bf16_f32 v9, v22, v23
	v_cvt_pk_bf16_f32 v10, v16, v17
	v_cvt_pk_bf16_f32 v11, v18, v19
	v_addc_co_u32_e32 v15, vcc, 0, v131, vcc
	v_cvt_pk_bf16_f32 v4, v4, v5
	v_cvt_pk_bf16_f32 v5, v6, v7
	v_cvt_pk_bf16_f32 v6, v0, v1
	v_cvt_pk_bf16_f32 v7, v2, v3
	global_store_dwordx4 v[130:131], v[124:127], off sc1
	global_store_dwordx4 v[108:109], v[104:107], off sc1
	global_store_dwordx4 v[92:93], v[88:91], off sc1
	global_store_dwordx4 v[76:77], v[72:75], off sc1
	global_store_dwordx4 v[76:77], v[68:71], off offset:256 sc1
	global_store_dwordx4 v[56:57], v[60:63], off sc1
	global_store_dwordx4 v[46:47], v[40:43], off sc1
	global_store_dwordx4 v[30:31], v[24:27], off sc1
	global_store_dwordx4 v[14:15], v[8:11], off sc1
	global_store_dwordx4 v[12:13], v[4:7], off offset:256 sc1
	s_andn2_b64 vcc, exec, s[38:39]
	s_mov_b64 s[36:37], -1
	s_cbranch_vccnz .LBB0_167

; __device__ __forceinline__ float bflo(unsigned w) { return __uint_as_float(w << 16); }
; __device__ __forceinline__ float bfhi(unsigned w) { return __uint_as_float(w & 0xffff0000u); }
; __global__ void __launch_bounds__(NTHR, 2) mega_fwd(Args args) {
;     ...
;                     for (int r0 = wave * 8; r0 < 512; r0 += NWAVES * 8) {
;                         v4u uu[2][4];
; #pragma unroll
;                         for (int q = 0; q < 2; ++q) { const int rr = r0 + q * 4 + rq, s_ = (rr < 256 ? 31 - j_ : j_) * 256 + (rr & 255);
;                             const bf16* base = O16 + ((size_t)((b_ * 16 + h_ * 4) * SEQ + s_)) * 128 + 8 * l16;
; #pragma unroll
;                             for (int c = 0; c < 4; ++c) uu[q][c] = __builtin_nontemporal_load((const v4u*)(base + (size_t)c * SEQ * 128)); }
; #pragma unroll
;                         for (int q = 0; q < 2; ++q) { const int rr = r0 + q * 4 + rq, s_ = (rr < 256 ? 31 - j_ : j_) * 256 + (rr & 255);
;                             float d[2][8]; float ss = 0.f;
; #pragma unroll
;                             for (int vh = 0; vh < 2; ++vh) { const v4u p = uu[q][vh], n = uu[q][2 + vh];
;                                 d[vh][0] = pg8::bflo(p.x) - lam * pg8::bflo(n.x); d[vh][1] = pg8::bfhi(p.x) - lam * pg8::bfhi(n.x); d[vh][2] = pg8::bflo(p.y) - lam * pg8::bflo(n.y); d[vh][3] = pg8::bfhi(p.y) - lam * pg8::bfhi(n.y);
;                                 d[vh][4] = pg8::bflo(p.z) - lam * pg8::bflo(n.z); d[vh][5] = pg8::bfhi(p.z) - lam * pg8::bfhi(n.z); d[vh][6] = pg8::bflo(p.w) - lam * pg8::bflo(n.w); d[vh][7] = pg8::bfhi(p.w) - lam * pg8::bfhi(n.w);
; #pragma unroll
;                                 for (int e = 0; e < 8; ++e) ss += d[vh][e] * d[vh][e]; }
;                             ss += __shfl_xor(ss, 1); ss += __shfl_xor(ss, 2); ss += __shfl_xor(ss, 4); ss += __shfl_xor(ss, 8);
.LBB0_484:
	v_add_u32_e32 v23, s49, v193
	v_cmp_gt_i32_e32 vcc, s13, v23
	v_mov_b32_e32 v40, s40
	v_mov_b32_e32 v41, s41
	v_cndmask_b32_e32 v24, v40, v41, vcc
	s_movk_i32 s38, 0xfb
	v_and_or_b32 v60, v23, s38, v24
	v_or_b32_e32 v24, s42, v60
	v_ashrrev_i32_e32 v25, 31, v24
	v_lshlrev_b64 v[24:25], 8, v[24:25]
	v_lshl_add_u64 v[36:37], v[196:197], 0, v[24:25]
	v_add_co_u32_e32 v28, vcc, s64, v36
	global_load_dwordx4 v[24:27], v[36:37], off nt
	s_nop 0
	v_addc_co_u32_e32 v29, vcc, 0, v37, vcc
	v_add_co_u32_e32 v32, vcc, s65, v36
	global_load_dwordx4 v[28:31], v[28:29], off nt
	s_nop 0
	v_addc_co_u32_e32 v33, vcc, 0, v37, vcc
	global_load_dwordx4 v[32:35], v[32:33], off nt
	v_add_co_u32_e32 v36, vcc, s27, v36
	v_add_u32_e32 v23, 4, v23
	s_nop 0
	v_addc_co_u32_e32 v37, vcc, 0, v37, vcc
	global_load_dwordx4 v[36:39], v[36:37], off nt
	v_cmp_gt_i32_e32 vcc, s13, v23
	s_movk_i32 s38, 0xff
	v_or_b32_e32 v60, s43, v60
	v_cndmask_b32_e32 v40, v40, v41, vcc
	v_and_or_b32 v23, v23, s38, v40
	v_or_b32_e32 v40, s42, v23
	v_ashrrev_i32_e32 v41, 31, v40
	v_lshlrev_b64 v[40:41], 8, v[40:41]
	v_lshl_add_u64 v[52:53], v[196:197], 0, v[40:41]
	v_add_co_u32_e32 v44, vcc, s64, v52
	global_load_dwordx4 v[40:43], v[52:53], off nt
	s_nop 0
	v_addc_co_u32_e32 v45, vcc, 0, v53, vcc
	v_add_co_u32_e32 v48, vcc, s65, v52
	global_load_dwordx4 v[44:47], v[44:45], off nt
	s_nop 0
	v_addc_co_u32_e32 v49, vcc, 0, v53, vcc
	global_load_dwordx4 v[48:51], v[48:49], off nt
	v_add_co_u32_e32 v52, vcc, s27, v52
	v_ashrrev_i32_e32 v61, 31, v60
	s_nop 0
	v_addc_co_u32_e32 v53, vcc, 0, v53, vcc
	global_load_dwordx4 v[52:55], v[52:53], off nt
	v_lshlrev_b64 v[60:61], 11, v[60:61]
	v_lshl_add_u64 v[60:61], v[18:19], 0, v[60:61]
	s_waitcnt vmcnt(7)
	v_lshlrev_b32_e32 v62, 16, v27
	v_and_b32_e32 v63, 0xffff0000, v27
	v_lshlrev_b32_e32 v66, 16, v26
	v_and_b32_e32 v67, 0xffff0000, v26
	v_lshlrev_b32_e32 v70, 16, v24
	v_and_b32_e32 v71, 0xffff0000, v24
	s_waitcnt vmcnt(6)
	v_lshlrev_b32_e32 v74, 16, v28
	v_and_b32_e32 v75, 0xffff0000, v28
	s_waitcnt vmcnt(5)
	v_lshlrev_b32_e32 v26, 16, v34
	v_and_b32_e32 v27, 0xffff0000, v34
	v_pk_fma_f32 v[26:27], v[0:1], v[26:27], v[66:67] neg_lo:[1,0,0] neg_hi:[1,0,0]
	v_lshlrev_b32_e32 v66, 16, v25
	v_and_b32_e32 v67, 0xffff0000, v25
	v_lshlrev_b32_e32 v24, 16, v32
	v_and_b32_e32 v25, 0xffff0000, v32
	v_lshlrev_b32_e32 v68, 16, v33
	v_and_b32_e32 v69, 0xffff0000, v33
	v_pk_fma_f32 v[24:25], v[0:1], v[24:25], v[70:71] neg_lo:[1,0,0] neg_hi:[1,0,0]
	v_pk_fma_f32 v[66:67], v[0:1], v[68:69], v[66:67] neg_lo:[1,0,0] neg_hi:[1,0,0]
	v_pk_mul_f32 v[32:33], v[24:25], v[24:25]
	v_pk_mul_f32 v[68:69], v[66:67], v[66:67]
	v_add_f32_e32 v32, v32, v33
	v_add_f32_e32 v32, v32, v68
	v_lshlrev_b32_e32 v64, 16, v35
	v_and_b32_e32 v65, 0xffff0000, v35
	v_pk_mul_f32 v[34:35], v[26:27], v[26:27]
	v_add_f32_e32 v32, v32, v69
	v_pk_fma_f32 v[62:63], v[0:1], v[64:65], v[62:63] neg_lo:[1,0,0] neg_hi:[1,0,0]
	v_add_f32_e32 v32, v32, v34
	v_pk_mul_f32 v[64:65], v[62:63], v[62:63]
	v_lshlrev_b32_e32 v70, 16, v29
	v_and_b32_e32 v71, 0xffff0000, v29
	s_waitcnt vmcnt(4)
	v_lshlrev_b32_e32 v28, 16, v36
	v_and_b32_e32 v29, 0xffff0000, v36
	v_add_f32_e32 v32, v32, v35
	v_pk_fma_f32 v[28:29], v[0:1], v[28:29], v[74:75] neg_lo:[1,0,0] neg_hi:[1,0,0]
	v_add_f32_e32 v32, v32, v64
	v_lshlrev_b32_e32 v72, 16, v37
	v_and_b32_e32 v73, 0xffff0000, v37
	v_pk_mul_f32 v[36:37], v[28:29], v[28:29]
	v_add_f32_e32 v32, v32, v65
	v_pk_fma_f32 v[70:71], v[0:1], v[72:73], v[70:71] neg_lo:[1,0,0] neg_hi:[1,0,0]
	v_add_f32_e32 v32, v32, v36
	v_lshlrev_b32_e32 v56, 16, v30
	v_and_b32_e32 v57, 0xffff0000, v30
	v_lshlrev_b32_e32 v58, 16, v38
	v_and_b32_e32 v59, 0xffff0000, v38
	v_pk_mul_f32 v[72:73], v[70:71], v[70:71]
	v_add_f32_e32 v32, v32, v37
	v_pk_fma_f32 v[56:57], v[0:1], v[58:59], v[56:57] neg_lo:[1,0,0] neg_hi:[1,0,0]
	v_add_f32_e32 v32, v32, v72
	v_pk_mul_f32 v[58:59], v[56:57], v[56:57]
	v_lshlrev_b32_e32 v30, 16, v31
	v_and_b32_e32 v31, 0xffff0000, v31
	v_lshlrev_b32_e32 v38, 16, v39
	v_and_b32_e32 v39, 0xffff0000, v39
	v_add_f32_e32 v32, v32, v73
	v_pk_fma_f32 v[30:31], v[0:1], v[38:39], v[30:31] neg_lo:[1,0,0] neg_hi:[1,0,0]
	v_add_f32_e32 v32, v32, v58
	v_pk_mul_f32 v[38:39], v[30:31], v[30:31]
	v_add_f32_e32 v32, v32, v59
	v_add_f32_e32 v32, v32, v38
	v_add_f32_e32 v32, v32, v39
	ds_bpermute_b32 v33, v76, v32
	s_waitcnt vmcnt(3)
	v_lshlrev_b32_e32 v38, 16, v42
	v_and_b32_e32 v39, 0xffff0000, v42
	s_waitcnt vmcnt(1)
	v_lshlrev_b32_e32 v42, 16, v50
	v_lshlrev_b32_e32 v58, 16, v44
	s_waitcnt lgkmcnt(0)
	v_add_f32_e32 v32, v32, v33
	ds_bpermute_b32 v33, v20, v32
	v_and_b32_e32 v59, 0xffff0000, v44
	s_waitcnt vmcnt(0)
	v_lshlrev_b32_e32 v44, 16, v52
	s_waitcnt lgkmcnt(0)
	v_add_f32_e32 v32, v32, v33
	ds_bpermute_b32 v33, v21, v32
	s_waitcnt lgkmcnt(0)
	v_add_f32_e32 v32, v32, v33
	ds_bpermute_b32 v33, v22, v32
	s_waitcnt lgkmcnt(0)
; __device__ __forceinline__ unsigned cvt_pk_bf16(float lo, float hi) { f32x2_t v = {lo, hi}; bf16x2_t b = __builtin_convertvector(v, bf16x2_t); return __builtin_bit_cast(unsigned, b); }
; __global__ void __launch_bounds__(NTHR, 2) mega_fwd(Args args) {
;     ...
;                             ss += __shfl_xor(ss, 1); ss += __shfl_xor(ss, 2); ss += __shfl_xor(ss, 4); ss += __shfl_xor(ss, 8);
;                             const float rs = 1.0f / sqrtf(ss * (1.f / 256.f) + EPS);
;                             bf16* dst = OA + ((size_t)(b_ * SEQ + s_)) * 1024 + h_ * 256 + 8 * l16;
; #pragma unroll
;                             for (int vh = 0; vh < 2; ++vh) { v4u o;
;                                 o.x = pg8::cvt_pk_bf16(d[vh][0] * rs * sg[vh][0].x, d[vh][1] * rs * sg[vh][0].y); o.y = pg8::cvt_pk_bf16(d[vh][2] * rs * sg[vh][0].z, d[vh][3] * rs * sg[vh][0].w);
;                                 o.z = pg8::cvt_pk_bf16(d[vh][4] * rs * sg[vh][1].x, d[vh][5] * rs * sg[vh][1].y); o.w = pg8::cvt_pk_bf16(d[vh][6] * rs * sg[vh][1].z, d[vh][7] * rs * sg[vh][1].w);
;                                 *(v4u*)(dst + vh * 128) = o; } }
	v_add_f32_e32 v32, v32, v33
	v_fmamk_f32 v32, v32, 0x3b800000, v218
	v_cmp_gt_f32_e32 vcc, s47, v32
	v_mul_f32_e32 v33, 0x4f800000, v32
	s_nop 0
	v_cndmask_b32_e32 v32, v32, v33, vcc
	v_sqrt_f32_e32 v33, v32
	s_nop 0
	v_add_u32_e32 v34, -1, v33
	v_fma_f32 v35, -v34, v33, v32
	v_cmp_ge_f32_e64 s[38:39], 0, v35
	v_add_u32_e32 v35, 1, v33
	s_nop 0
	v_cndmask_b32_e64 v34, v33, v34, s[38:39]
	v_fma_f32 v33, -v35, v33, v32
	v_cmp_lt_f32_e64 s[38:39], 0, v33
	s_nop 1
	v_cndmask_b32_e64 v33, v34, v35, s[38:39]
	v_mul_f32_e32 v34, 0x37800000, v33
	v_cndmask_b32_e32 v33, v33, v34, vcc
	v_cmp_class_f32_e32 vcc, v32, v219
	s_nop 1
	v_cndmask_b32_e32 v32, v33, v32, vcc
	v_div_scale_f32 v33, s[38:39], v32, v32, 1.0
	v_rcp_f32_e32 v34, v33
	s_nop 0
	v_fma_f32 v35, -v33, v34, 1.0
	v_fmac_f32_e32 v34, v35, v34
	v_div_scale_f32 v35, vcc, 1.0, v32, 1.0
	v_mul_f32_e32 v36, v35, v34
	v_fma_f32 v37, -v33, v36, v35
	v_fmac_f32_e32 v36, v37, v34
	v_fma_f32 v33, -v33, v36, v35
	v_div_fmas_f32 v33, v33, v34, v36
	v_div_fixup_f32 v32, v33, v32, 1.0
	v_pk_mul_f32 v[24:25], v[32:33], v[24:25] op_sel_hi:[0,1]
	v_pk_mul_f32 v[34:35], v[32:33], v[66:67] op_sel_hi:[0,1]
	v_pk_mul_f32 v[24:25], v[16:17], v[24:25]
	v_pk_mul_f32 v[34:35], v[14:15], v[34:35]
	v_cvt_pk_bf16_f32 v24, v24, v25
	v_cvt_pk_bf16_f32 v25, v34, v35
	v_pk_mul_f32 v[26:27], v[32:33], v[26:27] op_sel_hi:[0,1]
	v_pk_mul_f32 v[34:35], v[32:33], v[62:63] op_sel_hi:[0,1]
	v_pk_mul_f32 v[26:27], v[12:13], v[26:27]
	v_pk_mul_f32 v[34:35], v[10:11], v[34:35]
	v_cvt_pk_bf16_f32 v26, v26, v27
	v_cvt_pk_bf16_f32 v27, v34, v35
	global_store_dwordx4 v[60:61], v[24:27], off sc1
	v_lshlrev_b32_e32 v34, 16, v43
	v_and_b32_e32 v35, 0xffff0000, v43
	v_pk_mul_f32 v[24:25], v[32:33], v[28:29] op_sel_hi:[0,1]
	v_pk_mul_f32 v[26:27], v[32:33], v[70:71] op_sel_hi:[0,1]
	v_pk_mul_f32 v[24:25], v[8:9], v[24:25]
	v_pk_mul_f32 v[26:27], v[6:7], v[26:27]
	v_cvt_pk_bf16_f32 v24, v24, v25
	v_cvt_pk_bf16_f32 v25, v26, v27
	v_pk_mul_f32 v[26:27], v[32:33], v[56:57] op_sel_hi:[0,1]
	v_pk_mul_f32 v[28:29], v[32:33], v[30:31] op_sel_hi:[0,1]
	v_pk_mul_f32 v[26:27], v[4:5], v[26:27]
	v_pk_mul_f32 v[28:29], v[2:3], v[28:29]
	v_cvt_pk_bf16_f32 v26, v26, v27
	v_cvt_pk_bf16_f32 v27, v28, v29
	global_store_dwordx4 v[60:61], v[24:27], off offset:256 sc1
	v_lshlrev_b32_e32 v30, 16, v55
	v_and_b32_e32 v31, 0xffff0000, v55
	v_lshlrev_b32_e32 v24, 16, v46
	v_and_b32_e32 v25, 0xffff0000, v46
	v_lshlrev_b32_e32 v26, 16, v54
	v_and_b32_e32 v27, 0xffff0000, v54
	v_pk_fma_f32 v[28:29], v[0:1], v[26:27], v[24:25] neg_lo:[1,0,0] neg_hi:[1,0,0]
	v_lshlrev_b32_e32 v26, 16, v47
	v_and_b32_e32 v27, 0xffff0000, v47
	v_lshlrev_b32_e32 v46, 16, v41
	v_and_b32_e32 v47, 0xffff0000, v41
	v_lshlrev_b32_e32 v54, 16, v40
	v_and_b32_e32 v55, 0xffff0000, v40
	v_lshlrev_b32_e32 v40, 16, v48
	v_and_b32_e32 v41, 0xffff0000, v48
	v_lshlrev_b32_e32 v36, 16, v51
	v_and_b32_e32 v37, 0xffff0000, v51
	v_and_b32_e32 v43, 0xffff0000, v50
	v_lshlrev_b32_e32 v50, 16, v49
	v_and_b32_e32 v51, 0xffff0000, v49
	v_pk_fma_f32 v[40:41], v[0:1], v[40:41], v[54:55] neg_lo:[1,0,0] neg_hi:[1,0,0]
	v_pk_fma_f32 v[46:47], v[0:1], v[50:51], v[46:47] neg_lo:[1,0,0] neg_hi:[1,0,0]
	v_pk_mul_f32 v[48:49], v[40:41], v[40:41]
	v_or_b32_e32 v32, s43, v23
	v_pk_mul_f32 v[50:51], v[46:47], v[46:47]
	v_add_f32_e32 v23, v48, v49
	v_pk_fma_f32 v[38:39], v[0:1], v[42:43], v[38:39] neg_lo:[1,0,0] neg_hi:[1,0,0]
	v_add_f32_e32 v23, v23, v50
	v_pk_mul_f32 v[42:43], v[38:39], v[38:39]
	v_add_f32_e32 v23, v23, v51
	v_pk_fma_f32 v[34:35], v[0:1], v[36:37], v[34:35] neg_lo:[1,0,0] neg_hi:[1,0,0]
	v_add_f32_e32 v23, v23, v42
	v_pk_mul_f32 v[36:37], v[34:35], v[34:35]
	v_lshlrev_b32_e32 v54, 16, v45
	v_and_b32_e32 v55, 0xffff0000, v45
	v_and_b32_e32 v45, 0xffff0000, v52
	v_add_f32_e32 v23, v23, v43
	v_pk_fma_f32 v[44:45], v[0:1], v[44:45], v[58:59] neg_lo:[1,0,0] neg_hi:[1,0,0]
	v_add_f32_e32 v23, v23, v36
	v_lshlrev_b32_e32 v56, 16, v53
	v_and_b32_e32 v57, 0xffff0000, v53
	v_pk_mul_f32 v[52:53], v[44:45], v[44:45]
	v_add_f32_e32 v23, v23, v37
	v_pk_fma_f32 v[54:55], v[0:1], v[56:57], v[54:55] neg_lo:[1,0,0] neg_hi:[1,0,0]
	v_add_f32_e32 v23, v23, v52
	v_pk_mul_f32 v[56:57], v[54:55], v[54:55]
	v_add_f32_e32 v23, v23, v53
	v_add_f32_e32 v23, v23, v56
	v_pk_mul_f32 v[24:25], v[28:29], v[28:29]
	v_add_f32_e32 v23, v23, v57
	v_pk_fma_f32 v[30:31], v[0:1], v[30:31], v[26:27] neg_lo:[1,0,0] neg_hi:[1,0,0]
	v_add_f32_e32 v23, v23, v24
	v_pk_mul_f32 v[26:27], v[30:31], v[30:31]
	v_add_f32_e32 v23, v23, v25
	v_add_f32_e32 v23, v23, v26
	v_add_f32_e32 v23, v23, v27
	ds_bpermute_b32 v24, v76, v23
	v_ashrrev_i32_e32 v33, 31, v32
	v_lshlrev_b64 v[32:33], 11, v[32:33]
	v_lshl_add_u64 v[32:33], v[18:19], 0, v[32:33]
	s_waitcnt lgkmcnt(0)
; __device__ __forceinline__ unsigned cvt_pk_bf16(float lo, float hi) { f32x2_t v = {lo, hi}; bf16x2_t b = __builtin_convertvector(v, bf16x2_t); return __builtin_bit_cast(unsigned, b); }
; __global__ void __launch_bounds__(NTHR, 2) mega_fwd(Args args) {
;     ...
;                             ss += __shfl_xor(ss, 1); ss += __shfl_xor(ss, 2); ss += __shfl_xor(ss, 4); ss += __shfl_xor(ss, 8);
;                             const float rs = 1.0f / sqrtf(ss * (1.f / 256.f) + EPS);
;                             bf16* dst = OA + ((size_t)(b_ * SEQ + s_)) * 1024 + h_ * 256 + 8 * l16;
; #pragma unroll
;                             for (int vh = 0; vh < 2; ++vh) { v4u o;
;                                 o.x = pg8::cvt_pk_bf16(d[vh][0] * rs * sg[vh][0].x, d[vh][1] * rs * sg[vh][0].y); o.y = pg8::cvt_pk_bf16(d[vh][2] * rs * sg[vh][0].z, d[vh][3] * rs * sg[vh][0].w);
;                                 o.z = pg8::cvt_pk_bf16(d[vh][4] * rs * sg[vh][1].x, d[vh][5] * rs * sg[vh][1].y); o.w = pg8::cvt_pk_bf16(d[vh][6] * rs * sg[vh][1].z, d[vh][7] * rs * sg[vh][1].w);
;                                 *(v4u*)(dst + vh * 128) = o; } }
	v_add_f32_e32 v23, v23, v24
	ds_bpermute_b32 v24, v20, v23
	s_waitcnt lgkmcnt(0)
	v_add_f32_e32 v23, v23, v24
	ds_bpermute_b32 v24, v21, v23
	s_waitcnt lgkmcnt(0)
	v_add_f32_e32 v23, v23, v24
	ds_bpermute_b32 v24, v22, v23
	s_waitcnt lgkmcnt(0)
	v_add_f32_e32 v23, v23, v24
	v_fmamk_f32 v23, v23, 0x3b800000, v218
	v_cmp_gt_f32_e32 vcc, s47, v23
	v_mul_f32_e32 v24, 0x4f800000, v23
	s_nop 0
	v_cndmask_b32_e32 v23, v23, v24, vcc
	v_sqrt_f32_e32 v24, v23
	s_nop 0
	v_add_u32_e32 v25, -1, v24
	v_fma_f32 v26, -v25, v24, v23
	v_cmp_ge_f32_e64 s[38:39], 0, v26
	v_add_u32_e32 v26, 1, v24
	s_nop 0
	v_cndmask_b32_e64 v25, v24, v25, s[38:39]
	v_fma_f32 v24, -v26, v24, v23
	v_cmp_lt_f32_e64 s[38:39], 0, v24
	s_nop 1
	v_cndmask_b32_e64 v24, v25, v26, s[38:39]
	v_mul_f32_e32 v25, 0x37800000, v24
	v_cndmask_b32_e32 v24, v24, v25, vcc
	v_cmp_class_f32_e32 vcc, v23, v219
	s_nop 1
	v_cndmask_b32_e32 v23, v24, v23, vcc
	v_div_scale_f32 v24, s[38:39], v23, v23, 1.0
	v_rcp_f32_e32 v25, v24
	s_add_i32 s38, s49, 64
	s_cmpk_lt_i32 s49, 0x1c0
	s_mov_b32 s49, s38
	v_fma_f32 v26, -v24, v25, 1.0
	v_fmac_f32_e32 v25, v26, v25
	v_div_scale_f32 v26, vcc, 1.0, v23, 1.0
	v_mul_f32_e32 v27, v26, v25
	v_fma_f32 v36, -v24, v27, v26
	v_fmac_f32_e32 v27, v36, v25
	v_fma_f32 v24, -v24, v27, v26
	v_div_fmas_f32 v24, v24, v25, v27
	v_div_fixup_f32 v36, v24, v23, 1.0
	v_pk_mul_f32 v[24:25], v[36:37], v[40:41] op_sel_hi:[0,1]
	v_pk_mul_f32 v[26:27], v[36:37], v[46:47] op_sel_hi:[0,1]
	v_pk_mul_f32 v[24:25], v[16:17], v[24:25]
	v_pk_mul_f32 v[26:27], v[14:15], v[26:27]
	v_cvt_pk_bf16_f32 v24, v24, v25
	v_cvt_pk_bf16_f32 v25, v26, v27
	v_pk_mul_f32 v[26:27], v[36:37], v[38:39] op_sel_hi:[0,1]
	v_pk_mul_f32 v[34:35], v[36:37], v[34:35] op_sel_hi:[0,1]
	v_pk_mul_f32 v[26:27], v[12:13], v[26:27]
	v_pk_mul_f32 v[34:35], v[10:11], v[34:35]
	v_cvt_pk_bf16_f32 v26, v26, v27
	v_cvt_pk_bf16_f32 v27, v34, v35
	global_store_dwordx4 v[32:33], v[24:27], off sc1
	s_nop 1
	v_pk_mul_f32 v[24:25], v[36:37], v[44:45] op_sel_hi:[0,1]
	v_pk_mul_f32 v[26:27], v[36:37], v[54:55] op_sel_hi:[0,1]
	v_pk_mul_f32 v[24:25], v[8:9], v[24:25]
	v_pk_mul_f32 v[26:27], v[6:7], v[26:27]
	v_cvt_pk_bf16_f32 v24, v24, v25
	v_cvt_pk_bf16_f32 v25, v26, v27
	v_pk_mul_f32 v[26:27], v[36:37], v[28:29] op_sel_hi:[0,1]
	v_pk_mul_f32 v[28:29], v[36:37], v[30:31] op_sel_hi:[0,1]
	v_pk_mul_f32 v[26:27], v[4:5], v[26:27]
	v_pk_mul_f32 v[28:29], v[2:3], v[28:29]
	v_cvt_pk_bf16_f32 v26, v26, v27
	v_cvt_pk_bf16_f32 v27, v28, v29
	global_store_dwordx4 v[32:33], v[24:27], off offset:256 sc1
	s_cbranch_scc1 .LBB0_484

; __device__ __forceinline__ float bflo(unsigned w) { return __uint_as_float(w << 16); }
; __device__ __forceinline__ float bfhi(unsigned w) { return __uint_as_float(w & 0xffff0000u); }
; __device__ __forceinline__ u32x4 pack8f(f32x4 v0, f32x4 v1) { u32x4 w; w.x = cvt_pk_bf16(v0[0], v0[1]); w.y = cvt_pk_bf16(v0[2], v0[3]); w.z = cvt_pk_bf16(v1[0], v1[1]); w.w = cvt_pk_bf16(v1[2], v1[3]); return w; }
;     __device__ __forceinline__ void operator()(const f32x4 (&acc)[2][2][4][2], const Unit& u, int wr, int wc, int fr, int fq) const {
;     ...
;             for (int m = 0; m < 4; ++m) { const size_t r = (size_t)(row0 + ai * HALF + m * 16);
; #pragma unroll
;                 for (int bj = 0; bj < 2; ++bj) { gg[m][bj] = *(const u32x4*)(G + r * 4096 + c0 + bj * HALF); if (ADD) oo[m][bj] = *(const u32x4*)(MG + r * 2048 + c0 + bj * HALF); } }
; #pragma unroll
;             for (int m = 0; m < 4; ++m) { const size_t r = (size_t)(row0 + ai * HALF + m * 16);
; #pragma unroll
;                 for (int bj = 0; bj < 2; ++bj) { const u32x4 g = gg[m][bj]; bf16_t* op = MG + r * 2048 + c0 + bj * HALF;
;                     f32x4 v0 = acc[ai][bj][m][0], v1 = acc[ai][bj][m][1];
;                     v0[0] *= bflo(g.x); v0[1] *= bfhi(g.x); v0[2] *= bflo(g.y); v0[3] *= bfhi(g.y); v1[0] *= bflo(g.z); v1[1] *= bfhi(g.z); v1[2] *= bflo(g.w); v1[3] *= bfhi(g.w);
;                     if (ADD) { const u32x4 o = oo[m][bj]; v0[0] += bflo(o.x); v0[1] += bfhi(o.x); v0[2] += bflo(o.y); v0[3] += bfhi(o.y); v1[0] += bflo(o.z); v1[1] += bfhi(o.z); v1[2] += bflo(o.w); v1[3] += bfhi(o.w); }
;                     *(u32x4*)op = pack8f(v0, v1); } }
.LBB0_576:
	v_lshl_or_b32 v128, s35, 8, v219
	v_lshl_add_u32 v206, s34, 8, v193
	v_ashrrev_i32_e32 v129, 31, v128
	v_lshlrev_b64 v[202:203], 1, v[128:129]
	v_ashrrev_i32_e32 v207, 31, v206
	v_lshl_add_u64 v[208:209], s[16:17], 0, v[202:203]
	v_lshlrev_b64 v[128:129], 13, v[206:207]
	v_lshl_add_u64 v[204:205], s[14:15], 0, v[202:203]
	v_lshl_add_u64 v[128:129], v[208:209], 0, v[128:129]
	v_lshlrev_b64 v[232:233], 12, v[206:207]
	v_lshl_add_u64 v[130:131], v[204:205], 0, v[232:233]
	global_load_dwordx4 v[224:227], v[128:129], off
	global_load_dwordx4 v[228:231], v[130:131], off
	global_load_dwordx4 v[180:183], v[128:129], off offset:256
	global_load_dwordx4 v[176:179], v[130:131], off offset:256
	v_or_b32_e32 v128, 16, v206
	v_ashrrev_i32_e32 v129, 31, v128
	v_lshlrev_b64 v[130:131], 13, v[128:129]
	v_lshl_add_u64 v[130:131], v[208:209], 0, v[130:131]
	v_lshlrev_b64 v[214:215], 12, v[128:129]
	v_lshl_add_u64 v[128:129], v[204:205], 0, v[214:215]
	global_load_dwordx4 v[172:175], v[130:131], off
	global_load_dwordx4 v[168:171], v[128:129], off
	global_load_dwordx4 v[164:167], v[130:131], off offset:256
	global_load_dwordx4 v[160:163], v[128:129], off offset:256
	v_or_b32_e32 v128, 32, v206
	v_ashrrev_i32_e32 v129, 31, v128
	v_lshlrev_b64 v[130:131], 13, v[128:129]
	v_lshl_add_u64 v[130:131], v[208:209], 0, v[130:131]
	v_lshlrev_b64 v[212:213], 12, v[128:129]
	v_lshl_add_u64 v[128:129], v[204:205], 0, v[212:213]
	global_load_dwordx4 v[156:159], v[130:131], off
	global_load_dwordx4 v[152:155], v[128:129], off
	global_load_dwordx4 v[144:147], v[130:131], off offset:256
	global_load_dwordx4 v[136:139], v[128:129], off offset:256
	v_or_b32_e32 v128, 48, v206
	v_ashrrev_i32_e32 v129, 31, v128
	v_lshlrev_b64 v[130:131], 13, v[128:129]
	v_lshlrev_b64 v[210:211], 12, v[128:129]
	v_lshl_add_u64 v[130:131], v[208:209], 0, v[130:131]
	v_lshl_add_u64 v[128:129], v[204:205], 0, v[210:211]
	global_load_dwordx4 v[148:151], v[130:131], off
	global_load_dwordx4 v[140:143], v[128:129], off
	global_load_dwordx4 v[132:135], v[130:131], off offset:256
	s_nop 0
	global_load_dwordx4 v[128:131], v[128:129], off offset:256
	v_lshl_add_u64 v[232:233], s[14:15], 0, v[232:233]
	v_lshl_add_u64 v[232:233], v[232:233], 0, v[202:203]
	s_mov_b64 s[34:35], -1
	s_andn2_b64 vcc, exec, s[40:41]
	s_waitcnt vmcnt(0)
	v_lshlrev_b32_e32 v234, 16, v224
	v_and_b32_e32 v235, 0xffff0000, v224
	v_lshlrev_b32_e32 v236, 16, v228
	v_and_b32_e32 v237, 0xffff0000, v228
	v_lshlrev_b32_e32 v224, 16, v225
	v_and_b32_e32 v225, 0xffff0000, v225
	v_lshlrev_b32_e32 v228, 16, v229
	v_and_b32_e32 v229, 0xffff0000, v229
	v_pk_fma_f32 v[126:127], v[126:127], v[224:225], v[228:229]
	v_lshlrev_b32_e32 v224, 16, v226
	v_and_b32_e32 v225, 0xffff0000, v226
	v_lshlrev_b32_e32 v228, 16, v230
	v_and_b32_e32 v229, 0xffff0000, v230
	v_pk_fma_f32 v[224:225], v[120:121], v[224:225], v[228:229]
	v_lshlrev_b32_e32 v120, 16, v227
	v_and_b32_e32 v121, 0xffff0000, v227
	v_lshlrev_b32_e32 v226, 16, v231
	v_and_b32_e32 v227, 0xffff0000, v231
	v_pk_fma_f32 v[124:125], v[124:125], v[234:235], v[236:237]
	v_pk_fma_f32 v[226:227], v[122:123], v[120:121], v[226:227]
	v_cvt_pk_bf16_f32 v120, v124, v125
	v_cvt_pk_bf16_f32 v121, v126, v127
	v_cvt_pk_bf16_f32 v122, v224, v225
	v_cvt_pk_bf16_f32 v123, v226, v227
	global_store_dwordx4 v[232:233], v[120:123], off sc1
	s_nop 1
	v_lshlrev_b32_e32 v120, 16, v180
	v_and_b32_e32 v121, 0xffff0000, v180
	v_lshlrev_b32_e32 v122, 16, v176
	v_and_b32_e32 v123, 0xffff0000, v176
	v_pk_fma_f32 v[116:117], v[116:117], v[120:121], v[122:123]
	v_lshlrev_b32_e32 v120, 16, v181
	v_and_b32_e32 v121, 0xffff0000, v181
	v_lshlrev_b32_e32 v122, 16, v177
	v_and_b32_e32 v123, 0xffff0000, v177
	v_pk_fma_f32 v[118:119], v[118:119], v[120:121], v[122:123]
	v_lshlrev_b32_e32 v120, 16, v182
	v_and_b32_e32 v121, 0xffff0000, v182
	v_lshlrev_b32_e32 v122, 16, v178
	v_and_b32_e32 v123, 0xffff0000, v178
	v_pk_fma_f32 v[120:121], v[112:113], v[120:121], v[122:123]
	v_lshlrev_b32_e32 v112, 16, v183
	v_and_b32_e32 v113, 0xffff0000, v183
	v_lshlrev_b32_e32 v122, 16, v179
	v_and_b32_e32 v123, 0xffff0000, v179
	v_pk_fma_f32 v[122:123], v[114:115], v[112:113], v[122:123]
	v_cvt_pk_bf16_f32 v112, v116, v117
	v_cvt_pk_bf16_f32 v113, v118, v119
	v_cvt_pk_bf16_f32 v114, v120, v121
	v_cvt_pk_bf16_f32 v115, v122, v123
	global_store_dwordx4 v[232:233], v[112:115], off offset:256 sc1
	v_lshlrev_b32_e32 v116, 16, v168
	v_and_b32_e32 v117, 0xffff0000, v168
	v_lshlrev_b32_e32 v114, 16, v172
	v_and_b32_e32 v115, 0xffff0000, v172
	v_pk_fma_f32 v[108:109], v[108:109], v[114:115], v[116:117]
	v_lshlrev_b32_e32 v114, 16, v173
	v_and_b32_e32 v115, 0xffff0000, v173
	v_lshlrev_b32_e32 v116, 16, v169
	v_and_b32_e32 v117, 0xffff0000, v169
	v_pk_fma_f32 v[110:111], v[110:111], v[114:115], v[116:117]
	v_lshlrev_b32_e32 v114, 16, v174
	v_and_b32_e32 v115, 0xffff0000, v174
	v_lshlrev_b32_e32 v116, 16, v170
	v_and_b32_e32 v117, 0xffff0000, v170
	v_pk_fma_f32 v[114:115], v[104:105], v[114:115], v[116:117]
	v_lshlrev_b32_e32 v104, 16, v175
	v_and_b32_e32 v105, 0xffff0000, v175
	v_lshlrev_b32_e32 v116, 16, v171
	v_and_b32_e32 v117, 0xffff0000, v171
	v_lshl_add_u64 v[112:113], s[14:15], 0, v[214:215]
	v_pk_fma_f32 v[116:117], v[106:107], v[104:105], v[116:117]
	v_lshl_add_u64 v[112:113], v[112:113], 0, v[202:203]
	v_cvt_pk_bf16_f32 v104, v108, v109
	v_cvt_pk_bf16_f32 v105, v110, v111
	v_cvt_pk_bf16_f32 v106, v114, v115
	v_cvt_pk_bf16_f32 v107, v116, v117
	global_store_dwordx4 v[112:113], v[104:107], off sc1
	s_nop 1
	v_lshlrev_b32_e32 v104, 16, v164
	v_and_b32_e32 v105, 0xffff0000, v164
	v_lshlrev_b32_e32 v106, 16, v160
	v_and_b32_e32 v107, 0xffff0000, v160
; __device__ __forceinline__ float bflo(unsigned w) { return __uint_as_float(w << 16); }
; __device__ __forceinline__ float bfhi(unsigned w) { return __uint_as_float(w & 0xffff0000u); }
; __device__ __forceinline__ u32x4 pack8f(f32x4 v0, f32x4 v1) { u32x4 w; w.x = cvt_pk_bf16(v0[0], v0[1]); w.y = cvt_pk_bf16(v0[2], v0[3]); w.z = cvt_pk_bf16(v1[0], v1[1]); w.w = cvt_pk_bf16(v1[2], v1[3]); return w; }
;     __device__ __forceinline__ void operator()(const f32x4 (&acc)[2][2][4][2], const Unit& u, int wr, int wc, int fr, int fq) const {
;     ...
;             for (int m = 0; m < 4; ++m) { const size_t r = (size_t)(row0 + ai * HALF + m * 16);
; #pragma unroll
;                 for (int bj = 0; bj < 2; ++bj) { gg[m][bj] = *(const u32x4*)(G + r * 4096 + c0 + bj * HALF); if (ADD) oo[m][bj] = *(const u32x4*)(MG + r * 2048 + c0 + bj * HALF); } }
; #pragma unroll
;             for (int m = 0; m < 4; ++m) { const size_t r = (size_t)(row0 + ai * HALF + m * 16);
; #pragma unroll
;                 for (int bj = 0; bj < 2; ++bj) { const u32x4 g = gg[m][bj]; bf16_t* op = MG + r * 2048 + c0 + bj * HALF;
;                     f32x4 v0 = acc[ai][bj][m][0], v1 = acc[ai][bj][m][1];
;                     v0[0] *= bflo(g.x); v0[1] *= bfhi(g.x); v0[2] *= bflo(g.y); v0[3] *= bfhi(g.y); v1[0] *= bflo(g.z); v1[1] *= bfhi(g.z); v1[2] *= bflo(g.w); v1[3] *= bfhi(g.w);
;                     if (ADD) { const u32x4 o = oo[m][bj]; v0[0] += bflo(o.x); v0[1] += bfhi(o.x); v0[2] += bflo(o.y); v0[3] += bfhi(o.y); v1[0] += bflo(o.z); v1[1] += bfhi(o.z); v1[2] += bflo(o.w); v1[3] += bfhi(o.w); }
;                     *(u32x4*)op = pack8f(v0, v1); } }
	v_pk_fma_f32 v[100:101], v[100:101], v[104:105], v[106:107]
	v_lshlrev_b32_e32 v104, 16, v165
	v_and_b32_e32 v105, 0xffff0000, v165
	v_lshlrev_b32_e32 v106, 16, v161
	v_and_b32_e32 v107, 0xffff0000, v161
	v_pk_fma_f32 v[102:103], v[102:103], v[104:105], v[106:107]
	v_lshlrev_b32_e32 v104, 16, v166
	v_and_b32_e32 v105, 0xffff0000, v166
	v_lshlrev_b32_e32 v106, 16, v162
	v_and_b32_e32 v107, 0xffff0000, v162
	v_pk_fma_f32 v[104:105], v[96:97], v[104:105], v[106:107]
	v_lshlrev_b32_e32 v96, 16, v167
	v_and_b32_e32 v97, 0xffff0000, v167
	v_lshlrev_b32_e32 v106, 16, v163
	v_and_b32_e32 v107, 0xffff0000, v163
	v_pk_fma_f32 v[106:107], v[98:99], v[96:97], v[106:107]
	v_cvt_pk_bf16_f32 v96, v100, v101
	v_cvt_pk_bf16_f32 v97, v102, v103
	v_cvt_pk_bf16_f32 v98, v104, v105
	v_cvt_pk_bf16_f32 v99, v106, v107
	global_store_dwordx4 v[112:113], v[96:99], off offset:256 sc1
	v_lshlrev_b32_e32 v100, 16, v152
	v_and_b32_e32 v101, 0xffff0000, v152
	v_lshlrev_b32_e32 v98, 16, v156
	v_and_b32_e32 v99, 0xffff0000, v156
	v_pk_fma_f32 v[92:93], v[92:93], v[98:99], v[100:101]
	v_lshlrev_b32_e32 v98, 16, v157
	v_and_b32_e32 v99, 0xffff0000, v157
	v_lshlrev_b32_e32 v100, 16, v153
	v_and_b32_e32 v101, 0xffff0000, v153
	v_pk_fma_f32 v[94:95], v[94:95], v[98:99], v[100:101]
	v_lshlrev_b32_e32 v98, 16, v158
	v_and_b32_e32 v99, 0xffff0000, v158
	v_lshlrev_b32_e32 v100, 16, v154
	v_and_b32_e32 v101, 0xffff0000, v154
	v_pk_fma_f32 v[98:99], v[88:89], v[98:99], v[100:101]
	v_lshlrev_b32_e32 v88, 16, v159
	v_and_b32_e32 v89, 0xffff0000, v159
	v_lshlrev_b32_e32 v100, 16, v155
	v_and_b32_e32 v101, 0xffff0000, v155
	v_lshl_add_u64 v[96:97], s[14:15], 0, v[212:213]
	v_pk_fma_f32 v[100:101], v[90:91], v[88:89], v[100:101]
	v_lshl_add_u64 v[96:97], v[96:97], 0, v[202:203]
	v_cvt_pk_bf16_f32 v88, v92, v93
	v_cvt_pk_bf16_f32 v89, v94, v95
	v_cvt_pk_bf16_f32 v90, v98, v99
	v_cvt_pk_bf16_f32 v91, v100, v101
	global_store_dwordx4 v[96:97], v[88:91], off sc1
	s_nop 1
	v_lshlrev_b32_e32 v88, 16, v144
	v_and_b32_e32 v89, 0xffff0000, v144
	v_lshlrev_b32_e32 v90, 16, v136
	v_and_b32_e32 v91, 0xffff0000, v136
	v_pk_fma_f32 v[84:85], v[84:85], v[88:89], v[90:91]
	v_lshlrev_b32_e32 v88, 16, v145
	v_and_b32_e32 v89, 0xffff0000, v145
	v_lshlrev_b32_e32 v90, 16, v137
	v_and_b32_e32 v91, 0xffff0000, v137
	v_pk_fma_f32 v[86:87], v[86:87], v[88:89], v[90:91]
	v_lshlrev_b32_e32 v88, 16, v146
	v_and_b32_e32 v89, 0xffff0000, v146
	v_lshlrev_b32_e32 v90, 16, v138
	v_and_b32_e32 v91, 0xffff0000, v138
	v_pk_fma_f32 v[88:89], v[80:81], v[88:89], v[90:91]
	v_lshlrev_b32_e32 v80, 16, v147
	v_and_b32_e32 v81, 0xffff0000, v147
	v_lshlrev_b32_e32 v90, 16, v139
	v_and_b32_e32 v91, 0xffff0000, v139
	v_pk_fma_f32 v[90:91], v[82:83], v[80:81], v[90:91]
	v_cvt_pk_bf16_f32 v80, v84, v85
	v_cvt_pk_bf16_f32 v81, v86, v87
	v_cvt_pk_bf16_f32 v82, v88, v89
	v_cvt_pk_bf16_f32 v83, v90, v91
	global_store_dwordx4 v[96:97], v[80:83], off offset:256 sc1
	v_lshlrev_b32_e32 v84, 16, v140
	v_and_b32_e32 v85, 0xffff0000, v140
	v_lshlrev_b32_e32 v82, 16, v148
	v_and_b32_e32 v83, 0xffff0000, v148
	v_pk_fma_f32 v[76:77], v[76:77], v[82:83], v[84:85]
	v_lshlrev_b32_e32 v82, 16, v149
	v_and_b32_e32 v83, 0xffff0000, v149
	v_lshlrev_b32_e32 v84, 16, v141
	v_and_b32_e32 v85, 0xffff0000, v141
	v_pk_fma_f32 v[78:79], v[78:79], v[82:83], v[84:85]
	v_lshlrev_b32_e32 v82, 16, v150
	v_and_b32_e32 v83, 0xffff0000, v150
	v_lshlrev_b32_e32 v84, 16, v142
	v_and_b32_e32 v85, 0xffff0000, v142
	v_pk_fma_f32 v[82:83], v[72:73], v[82:83], v[84:85]
	v_lshlrev_b32_e32 v72, 16, v151
	v_and_b32_e32 v73, 0xffff0000, v151
	v_lshlrev_b32_e32 v84, 16, v143
	v_and_b32_e32 v85, 0xffff0000, v143
	v_lshl_add_u64 v[80:81], s[14:15], 0, v[210:211]
	v_pk_fma_f32 v[84:85], v[74:75], v[72:73], v[84:85]
	v_lshl_add_u64 v[80:81], v[80:81], 0, v[202:203]
	v_cvt_pk_bf16_f32 v72, v76, v77
	v_cvt_pk_bf16_f32 v73, v78, v79
	v_cvt_pk_bf16_f32 v74, v82, v83
	v_cvt_pk_bf16_f32 v75, v84, v85
	global_store_dwordx4 v[80:81], v[72:75], off sc1
	s_nop 1
	v_lshlrev_b32_e32 v72, 16, v132
	v_and_b32_e32 v73, 0xffff0000, v132
	v_lshlrev_b32_e32 v74, 16, v128
	v_and_b32_e32 v75, 0xffff0000, v128
	v_pk_fma_f32 v[68:69], v[68:69], v[72:73], v[74:75]
	v_lshlrev_b32_e32 v72, 16, v133
	v_and_b32_e32 v73, 0xffff0000, v133
	v_lshlrev_b32_e32 v74, 16, v129
	v_and_b32_e32 v75, 0xffff0000, v129
	v_pk_fma_f32 v[70:71], v[70:71], v[72:73], v[74:75]
	v_lshlrev_b32_e32 v72, 16, v134
	v_and_b32_e32 v73, 0xffff0000, v134
	v_lshlrev_b32_e32 v74, 16, v130
	v_and_b32_e32 v75, 0xffff0000, v130
	v_pk_fma_f32 v[72:73], v[64:65], v[72:73], v[74:75]
	v_lshlrev_b32_e32 v64, 16, v135
	v_and_b32_e32 v65, 0xffff0000, v135
	v_lshlrev_b32_e32 v74, 16, v131
	v_and_b32_e32 v75, 0xffff0000, v131
	v_pk_fma_f32 v[74:75], v[66:67], v[64:65], v[74:75]
	v_cvt_pk_bf16_f32 v64, v68, v69
	v_cvt_pk_bf16_f32 v65, v70, v71
	v_cvt_pk_bf16_f32 v66, v72, v73
	v_cvt_pk_bf16_f32 v67, v74, v75
	global_store_dwordx4 v[80:81], v[64:67], off offset:256 sc1
	s_nop 1
	v_add_u32_e32 v64, 0x80, v206
	v_ashrrev_i32_e32 v65, 31, v64
	v_lshlrev_b64 v[66:67], 13, v[64:65]
	v_lshl_add_u64 v[66:67], v[208:209], 0, v[66:67]
	v_lshlrev_b64 v[130:131], 12, v[64:65]
	v_lshl_add_u64 v[64:65], v[204:205], 0, v[130:131]
	global_load_dwordx4 v[98:101], v[66:67], off
	global_load_dwordx4 v[102:105], v[64:65], off
	global_load_dwordx4 v[106:109], v[66:67], off offset:256
	global_load_dwordx4 v[110:113], v[64:65], off offset:256
	v_add_u32_e32 v64, 0x90, v206
	v_ashrrev_i32_e32 v65, 31, v64
	v_lshlrev_b64 v[66:67], 13, v[64:65]
	v_lshl_add_u64 v[66:67], v[208:209], 0, v[66:67]
	v_lshlrev_b64 v[132:133], 12, v[64:65]
	v_lshl_add_u64 v[64:65], v[204:205], 0, v[132:133]
	global_load_dwordx4 v[114:117], v[66:67], off
	global_load_dwordx4 v[118:121], v[64:65], off
	global_load_dwordx4 v[122:125], v[66:67], off offset:256
	global_load_dwordx4 v[126:129], v[64:65], off offset:256
	v_add_u32_e32 v64, 0xa0, v206
	v_ashrrev_i32_e32 v65, 31, v64
	v_lshlrev_b64 v[66:67], 13, v[64:65]
	v_lshl_add_u64 v[66:67], v[208:209], 0, v[66:67]
	v_lshlrev_b64 v[134:135], 12, v[64:65]
	v_lshl_add_u64 v[64:65], v[204:205], 0, v[134:135]
	global_load_dwordx4 v[92:95], v[66:67], off
	global_load_dwordx4 v[88:91], v[64:65], off
	global_load_dwordx4 v[84:87], v[66:67], off offset:256
	global_load_dwordx4 v[80:83], v[64:65], off offset:256
	v_add_u32_e32 v64, 0xb0, v206
	v_ashrrev_i32_e32 v65, 31, v64
	v_lshlrev_b64 v[66:67], 13, v[64:65]
	v_lshlrev_b64 v[96:97], 12, v[64:65]
	v_lshl_add_u64 v[66:67], v[208:209], 0, v[66:67]
	v_lshl_add_u64 v[64:65], v[204:205], 0, v[96:97]
	global_load_dwordx4 v[76:79], v[66:67], off
	global_load_dwordx4 v[72:75], v[64:65], off
	global_load_dwordx4 v[68:71], v[66:67], off offset:256
	s_nop 0
	global_load_dwordx4 v[64:67], v[64:65], off offset:256
	v_lshl_add_u64 v[130:131], s[14:15], 0, v[130:131]
	v_lshl_add_u64 v[130:131], v[130:131], 0, v[202:203]
	s_waitcnt vmcnt(15)
; __device__ __forceinline__ float bflo(unsigned w) { return __uint_as_float(w << 16); }
; __device__ __forceinline__ float bfhi(unsigned w) { return __uint_as_float(w & 0xffff0000u); }
; __device__ __forceinline__ u32x4 pack8f(f32x4 v0, f32x4 v1) { u32x4 w; w.x = cvt_pk_bf16(v0[0], v0[1]); w.y = cvt_pk_bf16(v0[2], v0[3]); w.z = cvt_pk_bf16(v1[0], v1[1]); w.w = cvt_pk_bf16(v1[2], v1[3]); return w; }
;     __device__ __forceinline__ void operator()(const f32x4 (&acc)[2][2][4][2], const Unit& u, int wr, int wc, int fr, int fq) const {
;     ...
;             for (int m = 0; m < 4; ++m) { const size_t r = (size_t)(row0 + ai * HALF + m * 16);
; #pragma unroll
;                 for (int bj = 0; bj < 2; ++bj) { const u32x4 g = gg[m][bj]; bf16_t* op = MG + r * 2048 + c0 + bj * HALF;
;                     f32x4 v0 = acc[ai][bj][m][0], v1 = acc[ai][bj][m][1];
;                     v0[0] *= bflo(g.x); v0[1] *= bfhi(g.x); v0[2] *= bflo(g.y); v0[3] *= bfhi(g.y); v1[0] *= bflo(g.z); v1[1] *= bfhi(g.z); v1[2] *= bflo(g.w); v1[3] *= bfhi(g.w);
;                     if (ADD) { const u32x4 o = oo[m][bj]; v0[0] += bflo(o.x); v0[1] += bfhi(o.x); v0[2] += bflo(o.y); v0[3] += bfhi(o.y); v1[0] += bflo(o.z); v1[1] += bfhi(o.z); v1[2] += bflo(o.w); v1[3] += bfhi(o.w); }
;                     *(u32x4*)op = pack8f(v0, v1); } }
	v_lshlrev_b32_e32 v136, 16, v98
	v_and_b32_e32 v137, 0xffff0000, v98
	s_waitcnt vmcnt(14)
	v_lshlrev_b32_e32 v138, 16, v102
	v_and_b32_e32 v139, 0xffff0000, v102
	v_lshlrev_b32_e32 v98, 16, v99
	v_and_b32_e32 v99, 0xffff0000, v99
	v_lshlrev_b32_e32 v102, 16, v103
	v_and_b32_e32 v103, 0xffff0000, v103
	v_pk_fma_f32 v[62:63], v[62:63], v[98:99], v[102:103]
	v_lshlrev_b32_e32 v98, 16, v100
	v_and_b32_e32 v99, 0xffff0000, v100
	v_lshlrev_b32_e32 v102, 16, v104
	v_and_b32_e32 v103, 0xffff0000, v104
	v_pk_fma_f32 v[98:99], v[56:57], v[98:99], v[102:103]
	v_lshlrev_b32_e32 v56, 16, v101
	v_and_b32_e32 v57, 0xffff0000, v101
	v_lshlrev_b32_e32 v100, 16, v105
	v_and_b32_e32 v101, 0xffff0000, v105
	v_pk_fma_f32 v[60:61], v[60:61], v[136:137], v[138:139]
	v_pk_fma_f32 v[100:101], v[58:59], v[56:57], v[100:101]
	v_cvt_pk_bf16_f32 v56, v60, v61
	v_cvt_pk_bf16_f32 v57, v62, v63
	v_cvt_pk_bf16_f32 v58, v98, v99
	v_cvt_pk_bf16_f32 v59, v100, v101
	global_store_dwordx4 v[130:131], v[56:59], off sc1
	s_waitcnt vmcnt(14)
	s_nop 0
	v_lshlrev_b32_e32 v56, 16, v106
	v_and_b32_e32 v57, 0xffff0000, v106
	s_waitcnt vmcnt(13)
	v_lshlrev_b32_e32 v58, 16, v110
	v_and_b32_e32 v59, 0xffff0000, v110
	v_pk_fma_f32 v[52:53], v[52:53], v[56:57], v[58:59]
	v_lshlrev_b32_e32 v56, 16, v107
	v_and_b32_e32 v57, 0xffff0000, v107
	v_lshlrev_b32_e32 v58, 16, v111
	v_and_b32_e32 v59, 0xffff0000, v111
	v_pk_fma_f32 v[54:55], v[54:55], v[56:57], v[58:59]
	v_lshlrev_b32_e32 v56, 16, v108
	v_and_b32_e32 v57, 0xffff0000, v108
	v_lshlrev_b32_e32 v58, 16, v112
	v_and_b32_e32 v59, 0xffff0000, v112
	v_pk_fma_f32 v[56:57], v[48:49], v[56:57], v[58:59]
	v_lshlrev_b32_e32 v48, 16, v109
	v_and_b32_e32 v49, 0xffff0000, v109
	v_lshlrev_b32_e32 v58, 16, v113
	v_and_b32_e32 v59, 0xffff0000, v113
	v_pk_fma_f32 v[58:59], v[50:51], v[48:49], v[58:59]
	v_cvt_pk_bf16_f32 v48, v52, v53
	v_cvt_pk_bf16_f32 v49, v54, v55
	v_cvt_pk_bf16_f32 v50, v56, v57
	v_cvt_pk_bf16_f32 v51, v58, v59
	global_store_dwordx4 v[130:131], v[48:51], off offset:256 sc1
	s_waitcnt vmcnt(12)
	v_lshlrev_b32_e32 v52, 16, v118
	v_and_b32_e32 v53, 0xffff0000, v118
	v_lshlrev_b32_e32 v50, 16, v114
	v_and_b32_e32 v51, 0xffff0000, v114
	v_pk_fma_f32 v[44:45], v[44:45], v[50:51], v[52:53]
	v_lshlrev_b32_e32 v50, 16, v115
	v_and_b32_e32 v51, 0xffff0000, v115
	v_lshlrev_b32_e32 v52, 16, v119
	v_and_b32_e32 v53, 0xffff0000, v119
	v_pk_fma_f32 v[46:47], v[46:47], v[50:51], v[52:53]
	v_lshlrev_b32_e32 v50, 16, v116
	v_and_b32_e32 v51, 0xffff0000, v116
	v_lshlrev_b32_e32 v52, 16, v120
	v_and_b32_e32 v53, 0xffff0000, v120
	v_pk_fma_f32 v[50:51], v[40:41], v[50:51], v[52:53]
	v_lshlrev_b32_e32 v40, 16, v117
	v_and_b32_e32 v41, 0xffff0000, v117
	v_lshlrev_b32_e32 v52, 16, v121
	v_and_b32_e32 v53, 0xffff0000, v121
	v_lshl_add_u64 v[48:49], s[14:15], 0, v[132:133]
	v_pk_fma_f32 v[52:53], v[42:43], v[40:41], v[52:53]
	v_lshl_add_u64 v[48:49], v[48:49], 0, v[202:203]
	v_cvt_pk_bf16_f32 v40, v44, v45
	v_cvt_pk_bf16_f32 v41, v46, v47
	v_cvt_pk_bf16_f32 v42, v50, v51
	v_cvt_pk_bf16_f32 v43, v52, v53
	global_store_dwordx4 v[48:49], v[40:43], off sc1
	s_waitcnt vmcnt(12)
	s_nop 0
	v_lshlrev_b32_e32 v40, 16, v122
	v_and_b32_e32 v41, 0xffff0000, v122
	s_waitcnt vmcnt(11)
	v_lshlrev_b32_e32 v42, 16, v126
	v_and_b32_e32 v43, 0xffff0000, v126
	v_pk_fma_f32 v[36:37], v[36:37], v[40:41], v[42:43]
	v_lshlrev_b32_e32 v40, 16, v123
	v_and_b32_e32 v41, 0xffff0000, v123
	v_lshlrev_b32_e32 v42, 16, v127
	v_and_b32_e32 v43, 0xffff0000, v127
	v_pk_fma_f32 v[38:39], v[38:39], v[40:41], v[42:43]
	v_lshlrev_b32_e32 v40, 16, v124
	v_and_b32_e32 v41, 0xffff0000, v124
	v_lshlrev_b32_e32 v42, 16, v128
	v_and_b32_e32 v43, 0xffff0000, v128
	v_pk_fma_f32 v[40:41], v[32:33], v[40:41], v[42:43]
	v_lshlrev_b32_e32 v32, 16, v125
	v_and_b32_e32 v33, 0xffff0000, v125
	v_lshlrev_b32_e32 v42, 16, v129
	v_and_b32_e32 v43, 0xffff0000, v129
	v_pk_fma_f32 v[42:43], v[34:35], v[32:33], v[42:43]
	v_cvt_pk_bf16_f32 v32, v36, v37
	v_cvt_pk_bf16_f32 v33, v38, v39
	v_cvt_pk_bf16_f32 v34, v40, v41
	v_cvt_pk_bf16_f32 v35, v42, v43
	global_store_dwordx4 v[48:49], v[32:35], off offset:256 sc1
	s_waitcnt vmcnt(10)
; __device__ __forceinline__ float bflo(unsigned w) { return __uint_as_float(w << 16); }
; __device__ __forceinline__ float bfhi(unsigned w) { return __uint_as_float(w & 0xffff0000u); }
; __device__ __forceinline__ u32x4 pack8f(f32x4 v0, f32x4 v1) { u32x4 w; w.x = cvt_pk_bf16(v0[0], v0[1]); w.y = cvt_pk_bf16(v0[2], v0[3]); w.z = cvt_pk_bf16(v1[0], v1[1]); w.w = cvt_pk_bf16(v1[2], v1[3]); return w; }
;     __device__ __forceinline__ void operator()(const f32x4 (&acc)[2][2][4][2], const Unit& u, int wr, int wc, int fr, int fq) const {
;     ...
;             for (int m = 0; m < 4; ++m) { const size_t r = (size_t)(row0 + ai * HALF + m * 16);
; #pragma unroll
;                 for (int bj = 0; bj < 2; ++bj) { const u32x4 g = gg[m][bj]; bf16_t* op = MG + r * 2048 + c0 + bj * HALF;
;                     f32x4 v0 = acc[ai][bj][m][0], v1 = acc[ai][bj][m][1];
;                     v0[0] *= bflo(g.x); v0[1] *= bfhi(g.x); v0[2] *= bflo(g.y); v0[3] *= bfhi(g.y); v1[0] *= bflo(g.z); v1[1] *= bfhi(g.z); v1[2] *= bflo(g.w); v1[3] *= bfhi(g.w);
;                     if (ADD) { const u32x4 o = oo[m][bj]; v0[0] += bflo(o.x); v0[1] += bfhi(o.x); v0[2] += bflo(o.y); v0[3] += bfhi(o.y); v1[0] += bflo(o.z); v1[1] += bfhi(o.z); v1[2] += bflo(o.w); v1[3] += bfhi(o.w); }
;                     *(u32x4*)op = pack8f(v0, v1); } }
	v_lshlrev_b32_e32 v36, 16, v88
	v_and_b32_e32 v37, 0xffff0000, v88
	v_lshlrev_b32_e32 v34, 16, v92
	v_and_b32_e32 v35, 0xffff0000, v92
	v_pk_fma_f32 v[28:29], v[28:29], v[34:35], v[36:37]
	v_lshlrev_b32_e32 v34, 16, v93
	v_and_b32_e32 v35, 0xffff0000, v93
	v_lshlrev_b32_e32 v36, 16, v89
	v_and_b32_e32 v37, 0xffff0000, v89
	v_pk_fma_f32 v[30:31], v[30:31], v[34:35], v[36:37]
	v_lshlrev_b32_e32 v34, 16, v94
	v_and_b32_e32 v35, 0xffff0000, v94
	v_lshlrev_b32_e32 v36, 16, v90
	v_and_b32_e32 v37, 0xffff0000, v90
	v_pk_fma_f32 v[34:35], v[24:25], v[34:35], v[36:37]
	v_lshlrev_b32_e32 v24, 16, v95
	v_and_b32_e32 v25, 0xffff0000, v95
	v_lshlrev_b32_e32 v36, 16, v91
	v_and_b32_e32 v37, 0xffff0000, v91
	v_lshl_add_u64 v[32:33], s[14:15], 0, v[134:135]
	v_pk_fma_f32 v[36:37], v[26:27], v[24:25], v[36:37]
	v_lshl_add_u64 v[32:33], v[32:33], 0, v[202:203]
	v_cvt_pk_bf16_f32 v24, v28, v29
	v_cvt_pk_bf16_f32 v25, v30, v31
	v_cvt_pk_bf16_f32 v26, v34, v35
	v_cvt_pk_bf16_f32 v27, v36, v37
	global_store_dwordx4 v[32:33], v[24:27], off sc1
	s_waitcnt vmcnt(10)
	s_nop 0
	v_lshlrev_b32_e32 v24, 16, v84
	v_and_b32_e32 v25, 0xffff0000, v84
	s_waitcnt vmcnt(9)
	v_lshlrev_b32_e32 v26, 16, v80
	v_and_b32_e32 v27, 0xffff0000, v80
	v_pk_fma_f32 v[20:21], v[20:21], v[24:25], v[26:27]
	v_lshlrev_b32_e32 v24, 16, v85
	v_and_b32_e32 v25, 0xffff0000, v85
	v_lshlrev_b32_e32 v26, 16, v81
	v_and_b32_e32 v27, 0xffff0000, v81
	v_pk_fma_f32 v[22:23], v[22:23], v[24:25], v[26:27]
	v_lshlrev_b32_e32 v24, 16, v86
	v_and_b32_e32 v25, 0xffff0000, v86
	v_lshlrev_b32_e32 v26, 16, v82
	v_and_b32_e32 v27, 0xffff0000, v82
	v_pk_fma_f32 v[24:25], v[16:17], v[24:25], v[26:27]
	v_lshlrev_b32_e32 v16, 16, v87
	v_and_b32_e32 v17, 0xffff0000, v87
	v_lshlrev_b32_e32 v26, 16, v83
	v_and_b32_e32 v27, 0xffff0000, v83
	v_pk_fma_f32 v[26:27], v[18:19], v[16:17], v[26:27]
	v_cvt_pk_bf16_f32 v16, v20, v21
	v_cvt_pk_bf16_f32 v17, v22, v23
	v_cvt_pk_bf16_f32 v18, v24, v25
	v_cvt_pk_bf16_f32 v19, v26, v27
	global_store_dwordx4 v[32:33], v[16:19], off offset:256 sc1
	s_waitcnt vmcnt(8)
	v_lshlrev_b32_e32 v20, 16, v72
	v_and_b32_e32 v21, 0xffff0000, v72
	v_lshlrev_b32_e32 v18, 16, v76
	v_and_b32_e32 v19, 0xffff0000, v76
	v_pk_fma_f32 v[12:13], v[12:13], v[18:19], v[20:21]
	v_lshlrev_b32_e32 v18, 16, v77
	v_and_b32_e32 v19, 0xffff0000, v77
	v_lshlrev_b32_e32 v20, 16, v73
	v_and_b32_e32 v21, 0xffff0000, v73
	v_pk_fma_f32 v[14:15], v[14:15], v[18:19], v[20:21]
	v_lshlrev_b32_e32 v18, 16, v78
	v_and_b32_e32 v19, 0xffff0000, v78
	v_lshlrev_b32_e32 v20, 16, v74
	v_and_b32_e32 v21, 0xffff0000, v74
	v_pk_fma_f32 v[18:19], v[8:9], v[18:19], v[20:21]
	v_lshlrev_b32_e32 v8, 16, v79
	v_and_b32_e32 v9, 0xffff0000, v79
	v_lshlrev_b32_e32 v20, 16, v75
	v_and_b32_e32 v21, 0xffff0000, v75
	v_lshl_add_u64 v[16:17], s[14:15], 0, v[96:97]
	v_pk_fma_f32 v[20:21], v[10:11], v[8:9], v[20:21]
	v_lshl_add_u64 v[16:17], v[16:17], 0, v[202:203]
	v_cvt_pk_bf16_f32 v8, v12, v13
	v_cvt_pk_bf16_f32 v9, v14, v15
	v_cvt_pk_bf16_f32 v10, v18, v19
	v_cvt_pk_bf16_f32 v11, v20, v21
	global_store_dwordx4 v[16:17], v[8:11], off sc1
	s_waitcnt vmcnt(8)
	s_nop 0
	v_lshlrev_b32_e32 v8, 16, v68
	v_and_b32_e32 v9, 0xffff0000, v68
	s_waitcnt vmcnt(7)
	v_lshlrev_b32_e32 v10, 16, v64
	v_and_b32_e32 v11, 0xffff0000, v64
	v_pk_fma_f32 v[4:5], v[4:5], v[8:9], v[10:11]
	v_lshlrev_b32_e32 v8, 16, v69
	v_and_b32_e32 v9, 0xffff0000, v69
	v_lshlrev_b32_e32 v10, 16, v65
	v_and_b32_e32 v11, 0xffff0000, v65
	v_pk_fma_f32 v[6:7], v[6:7], v[8:9], v[10:11]
	v_lshlrev_b32_e32 v8, 16, v70
	v_and_b32_e32 v9, 0xffff0000, v70
	v_lshlrev_b32_e32 v10, 16, v66
	v_and_b32_e32 v11, 0xffff0000, v66
	v_pk_fma_f32 v[8:9], v[0:1], v[8:9], v[10:11]
	v_lshlrev_b32_e32 v0, 16, v71
	v_and_b32_e32 v1, 0xffff0000, v71
	v_lshlrev_b32_e32 v10, 16, v67
	v_and_b32_e32 v11, 0xffff0000, v67
	v_pk_fma_f32 v[10:11], v[2:3], v[0:1], v[10:11]
	v_cvt_pk_bf16_f32 v0, v4, v5
	v_cvt_pk_bf16_f32 v1, v6, v7
	v_cvt_pk_bf16_f32 v2, v8, v9
	v_cvt_pk_bf16_f32 v3, v10, v11
	global_store_dwordx4 v[16:17], v[0:3], off offset:256 sc1
	s_cbranch_vccnz .LBB0_565
	s_andn2_b64 vcc, exec, s[18:19]
	s_cbranch_vccnz .LBB0_564
	s_barrier
	s_branch .LBB0_564

;     __device__ __forceinline__ void operator()(const f32x4 (&acc)[2][2][4][2], const Unit& u, int wr, int wc, int fr, int fq) const {
;         const int row0 = u.pm * BM + wr * 64 + fr, c0 = u.pn * BM + wc * 32 + 4 * fq; const float* gp = gate + (size_t)(u.pm >> 5) * 12288 + c0;
;         f32x4 gv[2][2];
; #pragma unroll
;         for (int bj = 0; bj < 2; ++bj)
; #pragma unroll
;             for (int n = 0; n < 2; ++n) gv[bj][n] = *(const f32x4*)(gp + bj * HALF + n * 16);
; #pragma unroll
;         for (int ai = 0; ai < 2; ++ai) {
;             f32x4 bs[4][2][2];
; #pragma unroll
;             for (int m = 0; m < 4; ++m) { const size_t off = (size_t)(row0 + ai * HALF + m * 16) * 2048 + c0;
; #pragma unroll
;                 for (int bj = 0; bj < 2; ++bj)
; #pragma unroll
;                     for (int n = 0; n < 2; ++n) bs[m][bj][n] = *(const f32x4*)(base + off + bj * HALF + n * 16); }
; #pragma unroll
;             for (int m = 0; m < 4; ++m) { const size_t off = (size_t)(row0 + ai * HALF + m * 16) * 2048 + c0;
; #pragma unroll
;                 for (int bj = 0; bj < 2; ++bj)
; #pragma unroll
;                     for (int n = 0; n < 2; ++n) *(f32x4*)(out + off + bj * HALF + n * 16) = bs[m][bj][n] + gv[bj][n] * acc[ai][bj][m][n]; }
.LBB0_648:
	v_lshl_or_b32 v92, s35, 8, v195
	s_ashr_i32 s25, s34, 5
	s_mul_hi_i32 s27, s25, 0xc000
	s_mul_i32 s25, s25, 0xc000
	v_ashrrev_i32_e32 v93, 31, v92
	v_lshl_add_u32 v144, s34, 8, v193
	s_add_u32 s36, s64, s25
	v_lshlrev_b64 v[184:185], 2, v[92:93]
	v_ashrrev_i32_e32 v145, 31, v144
	s_addc_u32 s37, s65, s27
	v_lshl_add_u64 v[186:187], s[14:15], 0, v[184:185]
	v_lshlrev_b64 v[188:189], 13, v[144:145]
	v_lshl_add_u64 v[92:93], s[36:37], 0, v[184:185]
	v_lshl_add_u64 v[146:147], v[186:187], 0, v[188:189]
	global_load_dwordx4 v[116:119], v[92:93], off
	global_load_dwordx4 v[108:111], v[92:93], off offset:64
	global_load_dwordx4 v[100:103], v[92:93], off offset:512
	s_nop 0
	global_load_dwordx4 v[92:95], v[92:93], off offset:576
	s_nop 0
	global_load_dwordx4 v[200:203], v[146:147], off
	global_load_dwordx4 v[204:207], v[146:147], off offset:64
	global_load_dwordx4 v[208:211], v[146:147], off offset:512
	global_load_dwordx4 v[212:215], v[146:147], off offset:576
	v_or_b32_e32 v146, 16, v144
	v_ashrrev_i32_e32 v147, 31, v146
	v_lshlrev_b64 v[238:239], 13, v[146:147]
	v_lshl_add_u64 v[146:147], v[186:187], 0, v[238:239]
	global_load_dwordx4 v[218:221], v[146:147], off
	global_load_dwordx4 v[222:225], v[146:147], off offset:64
	global_load_dwordx4 v[226:229], v[146:147], off offset:512
	global_load_dwordx4 v[230:233], v[146:147], off offset:576
	v_or_b32_e32 v146, 32, v144
	v_ashrrev_i32_e32 v147, 31, v146
	v_lshlrev_b64 v[240:241], 13, v[146:147]
	v_or_b32_e32 v144, 48, v144
	v_lshl_add_u64 v[146:147], v[186:187], 0, v[240:241]
	v_ashrrev_i32_e32 v145, 31, v144
	global_load_dwordx4 v[234:237], v[146:147], off
	global_load_dwordx4 v[168:171], v[146:147], off offset:64
	global_load_dwordx4 v[164:167], v[146:147], off offset:512
	global_load_dwordx4 v[160:163], v[146:147], off offset:576
	v_lshlrev_b64 v[190:191], 13, v[144:145]
	v_lshl_add_u64 v[144:145], v[186:187], 0, v[190:191]
	global_load_dwordx4 v[156:159], v[144:145], off
	global_load_dwordx4 v[152:155], v[144:145], off offset:64
	global_load_dwordx4 v[148:151], v[144:145], off offset:512
	s_nop 0
	global_load_dwordx4 v[144:147], v[144:145], off offset:576
	s_mov_b64 s[34:35], 0x100000
	s_andn2_b64 vcc, exec, s[38:39]
	s_waitcnt vmcnt(0)
	v_pk_fma_f32 v[140:141], v[140:141], v[116:117], v[200:201]
	v_lshl_add_u64 v[200:201], s[16:17], 0, v[188:189]
	v_lshl_add_u64 v[200:201], v[200:201], 0, v[184:185]
	v_pk_fma_f32 v[130:131], v[130:131], v[102:103], v[210:211]
	v_pk_fma_f32 v[128:129], v[128:129], v[100:101], v[208:209]
	global_store_dwordx4 v[200:201], v[128:131], off offset:512 sc1
	v_pk_fma_f32 v[126:127], v[126:127], v[94:95], v[214:215]
	v_pk_fma_f32 v[106:107], v[106:107], v[102:103], v[228:229]
	v_lshl_add_u64 v[128:129], s[16:17], 0, v[238:239]
	v_lshl_add_u64 v[128:129], v[128:129], 0, v[184:185]
	v_pk_fma_f32 v[104:105], v[104:105], v[100:101], v[226:227]
	global_store_dwordx4 v[128:129], v[104:107], off offset:512 sc1
	v_pk_fma_f32 v[98:99], v[98:99], v[94:95], v[232:233]
	v_pk_fma_f32 v[96:97], v[96:97], v[92:93], v[230:231]
	v_lshl_add_u64 v[104:105], s[16:17], 0, v[240:241]
	v_lshl_add_u64 v[104:105], v[104:105], 0, v[184:185]
	v_pk_fma_f32 v[82:83], v[82:83], v[94:95], v[162:163]
	v_pk_fma_f32 v[80:81], v[80:81], v[92:93], v[160:161]
	v_pk_fma_f32 v[124:125], v[124:125], v[92:93], v[212:213]
	global_store_dwordx4 v[128:129], v[96:99], off offset:576 sc1
	global_store_dwordx4 v[104:105], v[80:83], off offset:576 sc1
	v_pk_fma_f32 v[142:143], v[142:143], v[118:119], v[202:203]
	v_pk_fma_f32 v[98:99], v[114:115], v[118:119], v[236:237]
	v_pk_fma_f32 v[96:97], v[112:113], v[116:117], v[234:235]
	v_lshl_add_u64 v[80:81], s[16:17], 0, v[190:191]
	v_pk_fma_f32 v[138:139], v[138:139], v[110:111], v[206:207]
	v_pk_fma_f32 v[136:137], v[136:137], v[108:109], v[204:205]
	global_store_dwordx4 v[200:201], v[124:127], off offset:576 sc1
	v_pk_fma_f32 v[122:123], v[122:123], v[110:111], v[224:225]
	v_pk_fma_f32 v[120:121], v[120:121], v[108:109], v[222:223]
	v_pk_fma_f32 v[126:127], v[134:135], v[118:119], v[220:221]
	v_pk_fma_f32 v[124:125], v[132:133], v[116:117], v[218:219]
	global_store_dwordx4 v[104:105], v[96:99], off sc1
	v_pk_fma_f32 v[90:91], v[90:91], v[110:111], v[170:171]
	v_pk_fma_f32 v[88:89], v[88:89], v[108:109], v[168:169]
	v_pk_fma_f32 v[86:87], v[86:87], v[102:103], v[166:167]
	v_pk_fma_f32 v[84:85], v[84:85], v[100:101], v[164:165]
	v_pk_fma_f32 v[78:79], v[78:79], v[118:119], v[158:159]
	v_pk_fma_f32 v[76:77], v[76:77], v[116:117], v[156:157]
	v_lshl_add_u64 v[80:81], v[80:81], 0, v[184:185]
	v_pk_fma_f32 v[74:75], v[74:75], v[110:111], v[154:155]
	v_pk_fma_f32 v[72:73], v[72:73], v[108:109], v[152:153]
	v_pk_fma_f32 v[70:71], v[70:71], v[102:103], v[150:151]
	v_pk_fma_f32 v[68:69], v[68:69], v[100:101], v[148:149]
	v_pk_fma_f32 v[66:67], v[66:67], v[94:95], v[146:147]
	v_pk_fma_f32 v[64:65], v[64:65], v[92:93], v[144:145]
	v_lshl_add_u64 v[98:99], v[188:189], 0, s[34:35]
	global_store_dwordx4 v[200:201], v[140:143], off sc1
	global_store_dwordx4 v[200:201], v[136:139], off offset:64 sc1
	global_store_dwordx4 v[128:129], v[124:127], off sc1
	global_store_dwordx4 v[128:129], v[120:123], off offset:64 sc1
	global_store_dwordx4 v[104:105], v[88:91], off offset:64 sc1
	global_store_dwordx4 v[104:105], v[84:87], off offset:512 sc1
	global_store_dwordx4 v[80:81], v[76:79], off sc1
	global_store_dwordx4 v[80:81], v[72:75], off offset:64 sc1
	global_store_dwordx4 v[80:81], v[68:71], off offset:512 sc1
	global_store_dwordx4 v[80:81], v[64:67], off offset:576 sc1
	s_mov_b64 s[34:35], 0x120000
	v_lshl_add_u64 v[148:149], v[188:189], 0, s[34:35]
	v_lshl_add_u64 v[64:65], v[186:187], 0, v[98:99]
	global_load_dwordx4 v[104:107], v[64:65], off
	global_load_dwordx4 v[112:115], v[64:65], off offset:64
	global_load_dwordx4 v[120:123], v[64:65], off offset:512
	global_load_dwordx4 v[124:127], v[64:65], off offset:576
	s_mov_b64 s[34:35], 0x140000
	v_lshl_add_u64 v[64:65], v[186:187], 0, v[148:149]
	v_lshl_add_u64 v[150:151], v[188:189], 0, s[34:35]
	global_load_dwordx4 v[128:131], v[64:65], off
	global_load_dwordx4 v[132:135], v[64:65], off offset:64
	global_load_dwordx4 v[136:139], v[64:65], off offset:512
	global_load_dwordx4 v[140:143], v[64:65], off offset:576
	v_lshl_add_u64 v[64:65], v[186:187], 0, v[150:151]
	s_mov_b64 s[34:35], 0x160000
	global_load_dwordx4 v[144:147], v[64:65], off
	global_load_dwordx4 v[88:91], v[64:65], off offset:64
	global_load_dwordx4 v[84:87], v[64:65], off offset:512
	global_load_dwordx4 v[80:83], v[64:65], off offset:576
	v_lshl_add_u64 v[96:97], v[188:189], 0, s[34:35]
	v_lshl_add_u64 v[64:65], v[186:187], 0, v[96:97]
	global_load_dwordx4 v[76:79], v[64:65], off
	global_load_dwordx4 v[72:75], v[64:65], off offset:64
	global_load_dwordx4 v[68:71], v[64:65], off offset:512
	s_nop 0
	global_load_dwordx4 v[64:67], v[64:65], off offset:576
	v_lshl_add_u64 v[98:99], s[16:17], 0, v[98:99]
	v_lshl_add_u64 v[98:99], v[98:99], 0, v[184:185]
	s_mov_b64 s[34:35], -1
	s_waitcnt vmcnt(15)
;     __device__ __forceinline__ void operator()(const f32x4 (&acc)[2][2][4][2], const Unit& u, int wr, int wc, int fr, int fq) const {
;     ...
;             for (int m = 0; m < 4; ++m) { const size_t off = (size_t)(row0 + ai * HALF + m * 16) * 2048 + c0;
; #pragma unroll
;                 for (int bj = 0; bj < 2; ++bj)
; #pragma unroll
;                     for (int n = 0; n < 2; ++n) *(f32x4*)(out + off + bj * HALF + n * 16) = bs[m][bj][n] + gv[bj][n] * acc[ai][bj][m][n]; }
	v_pk_fma_f32 v[62:63], v[62:63], v[118:119], v[106:107]
	v_pk_fma_f32 v[60:61], v[60:61], v[116:117], v[104:105]
	s_waitcnt vmcnt(13)
	v_pk_fma_f32 v[50:51], v[50:51], v[102:103], v[122:123]
	v_pk_fma_f32 v[48:49], v[48:49], v[100:101], v[120:121]
	global_store_dwordx4 v[98:99], v[48:51], off offset:512 sc1
	s_waitcnt vmcnt(13)
	v_pk_fma_f32 v[46:47], v[46:47], v[94:95], v[126:127]
	s_waitcnt vmcnt(10)
	v_pk_fma_f32 v[34:35], v[34:35], v[102:103], v[138:139]
	v_lshl_add_u64 v[48:49], s[16:17], 0, v[148:149]
	v_lshl_add_u64 v[48:49], v[48:49], 0, v[184:185]
	v_pk_fma_f32 v[32:33], v[32:33], v[100:101], v[136:137]
	global_store_dwordx4 v[48:49], v[32:35], off offset:512 sc1
	s_waitcnt vmcnt(6)
	v_pk_fma_f32 v[18:19], v[18:19], v[94:95], v[82:83]
	v_pk_fma_f32 v[16:17], v[16:17], v[92:93], v[80:81]
	v_lshl_add_u64 v[32:33], s[16:17], 0, v[150:151]
	v_lshl_add_u64 v[32:33], v[32:33], 0, v[184:185]
	v_pk_fma_f32 v[44:45], v[44:45], v[92:93], v[124:125]
	v_pk_fma_f32 v[30:31], v[30:31], v[94:95], v[142:143]
	v_pk_fma_f32 v[28:29], v[28:29], v[92:93], v[140:141]
	global_store_dwordx4 v[32:33], v[16:19], off offset:576 sc1
	v_pk_fma_f32 v[58:59], v[58:59], v[110:111], v[114:115]
	v_pk_fma_f32 v[56:57], v[56:57], v[108:109], v[112:113]
	v_lshl_add_u64 v[16:17], s[16:17], 0, v[96:97]
	global_store_dwordx4 v[98:99], v[44:47], off offset:576 sc1
	v_pk_fma_f32 v[42:43], v[42:43], v[110:111], v[134:135]
	v_pk_fma_f32 v[40:41], v[40:41], v[108:109], v[132:133]
	v_pk_fma_f32 v[46:47], v[54:55], v[118:119], v[130:131]
	v_pk_fma_f32 v[44:45], v[52:53], v[116:117], v[128:129]
	global_store_dwordx4 v[48:49], v[28:31], off offset:576 sc1
	v_pk_fma_f32 v[26:27], v[26:27], v[110:111], v[90:91]
	v_pk_fma_f32 v[24:25], v[24:25], v[108:109], v[88:89]
	v_pk_fma_f32 v[30:31], v[38:39], v[118:119], v[146:147]
	v_pk_fma_f32 v[28:29], v[36:37], v[116:117], v[144:145]
	v_pk_fma_f32 v[22:23], v[22:23], v[102:103], v[86:87]
	v_pk_fma_f32 v[20:21], v[20:21], v[100:101], v[84:85]
	s_waitcnt vmcnt(8)
	v_pk_fma_f32 v[14:15], v[14:15], v[118:119], v[78:79]
	v_pk_fma_f32 v[12:13], v[12:13], v[116:117], v[76:77]
	v_lshl_add_u64 v[16:17], v[16:17], 0, v[184:185]
	s_waitcnt vmcnt(7)
	v_pk_fma_f32 v[10:11], v[10:11], v[110:111], v[74:75]
	v_pk_fma_f32 v[8:9], v[8:9], v[108:109], v[72:73]
	s_waitcnt vmcnt(6)
	v_pk_fma_f32 v[6:7], v[6:7], v[102:103], v[70:71]
	v_pk_fma_f32 v[4:5], v[4:5], v[100:101], v[68:69]
	s_waitcnt vmcnt(5)
	v_pk_fma_f32 v[2:3], v[2:3], v[94:95], v[66:67]
	v_pk_fma_f32 v[0:1], v[0:1], v[92:93], v[64:65]
	global_store_dwordx4 v[98:99], v[60:63], off sc1
	global_store_dwordx4 v[98:99], v[56:59], off offset:64 sc1
	global_store_dwordx4 v[48:49], v[44:47], off sc1
	global_store_dwordx4 v[48:49], v[40:43], off offset:64 sc1
	global_store_dwordx4 v[32:33], v[28:31], off sc1
	global_store_dwordx4 v[32:33], v[24:27], off offset:64 sc1
	global_store_dwordx4 v[32:33], v[20:23], off offset:512 sc1
	global_store_dwordx4 v[16:17], v[12:15], off sc1
	global_store_dwordx4 v[16:17], v[8:11], off offset:64 sc1
	global_store_dwordx4 v[16:17], v[4:7], off offset:512 sc1
	global_store_dwordx4 v[16:17], v[0:3], off offset:576 sc1
	s_cbranch_vccnz .LBB0_637
	s_andn2_b64 vcc, exec, s[18:19]
	s_cbranch_vccnz .LBB0_636
	s_barrier
	s_branch .LBB0_636

; __device__ __forceinline__ u32x4 pack8f(f32x4 v0, f32x4 v1) { u32x4 w; w.x = cvt_pk_bf16(v0[0], v0[1]); w.y = cvt_pk_bf16(v0[2], v0[3]); w.z = cvt_pk_bf16(v1[0], v1[1]); w.w = cvt_pk_bf16(v1[2], v1[3]); return w; }
;     __device__ __forceinline__ void operator()(const f32x4 (&acc)[2][2][4][2], const Unit& u, int wr, int wc, int fr, int fq) const {
;     ...
;             for (int m = 0; m < 4; ++m) { bf16_t* rowp = O + (size_t)(row0 + ai * HALF + m * 16) * ldc + c0;
; #pragma unroll
;                 for (int bj = 0; bj < 2; ++bj) { f32x4 v0 = acc[ai][bj][m][0], v1 = acc[ai][bj][m][1];
; #pragma unroll
;                     for (int e = 0; e < 4; ++e) { const float a = fmaxf(v0[e], 0.f), b = fmaxf(v1[e], 0.f); v0[e] = a * a; v1[e] = b * b; }
;                     *(u32x4*)(rowp + bj * HALF) = pack8f(v0, v1); } }
.LBB0_778:
	v_lshl_add_u32 v152, s28, 8, v146
	v_lshl_or_b32 v144, s29, 8, v148
	v_ashrrev_i32_e32 v153, 31, v152
	v_ashrrev_i32_e32 v145, 31, v144
	v_lshlrev_b64 v[154:155], 14, v[152:153]
	v_max_f32_e32 v120, v120, v120
	v_max_f32_e32 v121, v121, v121
	v_lshl_add_u64 v[154:155], s[14:15], 0, v[154:155]
	v_lshlrev_b64 v[156:157], 1, v[144:145]
	v_max_f32_e32 v120, 0, v120
	v_max_f32_e32 v121, 0, v121
	v_lshl_add_u64 v[144:145], v[154:155], 0, v[156:157]
	v_pk_mul_f32 v[154:155], v[120:121], v[120:121]
	v_max_f32_e32 v121, v122, v122
	v_max_f32_e32 v124, v124, v124
	v_max_f32_e32 v125, v125, v125
	v_max_f32_e32 v120, v126, v126
	v_max_f32_e32 v122, 0, v121
	v_max_f32_e32 v121, v127, v127
	v_max_f32_e32 v123, v123, v123
	v_max_f32_e32 v124, 0, v124
	v_max_f32_e32 v125, 0, v125
	v_max_f32_e32 v120, 0, v120
	v_max_f32_e32 v121, 0, v121
	v_max_f32_e32 v123, 0, v123
	v_pk_mul_f32 v[124:125], v[124:125], v[124:125]
	v_pk_mul_f32 v[126:127], v[120:121], v[120:121]
	v_pk_mul_f32 v[158:159], v[122:123], v[122:123]
	v_max_f32_e32 v112, v112, v112
	v_max_f32_e32 v113, v113, v113
	v_cvt_pk_bf16_f32 v120, v124, v125
	v_cvt_pk_bf16_f32 v121, v126, v127
	v_cvt_pk_bf16_f32 v122, v154, v155
	v_cvt_pk_bf16_f32 v123, v158, v159
	v_max_f32_e32 v112, 0, v112
	v_max_f32_e32 v113, 0, v113
	global_store_dwordx4 v[144:145], v[120:123], off sc1
	v_max_f32_e32 v116, v116, v116
	v_max_f32_e32 v117, v117, v117
	v_pk_mul_f32 v[120:121], v[112:113], v[112:113]
	v_max_f32_e32 v113, v114, v114
	v_max_f32_e32 v112, v118, v118
	v_max_f32_e32 v114, 0, v113
	v_max_f32_e32 v113, v119, v119
	v_max_f32_e32 v115, v115, v115
	v_max_f32_e32 v116, 0, v116
	v_max_f32_e32 v117, 0, v117
	v_max_f32_e32 v112, 0, v112
	v_max_f32_e32 v113, 0, v113
	v_max_f32_e32 v115, 0, v115
	v_pk_mul_f32 v[116:117], v[116:117], v[116:117]
	v_pk_mul_f32 v[118:119], v[112:113], v[112:113]
	v_pk_mul_f32 v[122:123], v[114:115], v[114:115]
	v_max_f32_e32 v104, v104, v104
	v_max_f32_e32 v105, v105, v105
	v_cvt_pk_bf16_f32 v112, v116, v117
	v_cvt_pk_bf16_f32 v113, v118, v119
	v_cvt_pk_bf16_f32 v114, v120, v121
	v_cvt_pk_bf16_f32 v115, v122, v123
	v_max_f32_e32 v104, 0, v104
	v_max_f32_e32 v105, 0, v105
	global_store_dwordx4 v[144:145], v[112:115], off offset:256 sc1
	v_max_f32_e32 v108, v108, v108
	v_max_f32_e32 v109, v109, v109
	v_or_b32_e32 v112, 16, v152
	v_pk_mul_f32 v[114:115], v[104:105], v[104:105]
	v_max_f32_e32 v105, v106, v106
	v_ashrrev_i32_e32 v113, 31, v112
	v_max_f32_e32 v104, v110, v110
	v_max_f32_e32 v106, 0, v105
	v_max_f32_e32 v105, v111, v111
	v_max_f32_e32 v107, v107, v107
	v_lshlrev_b64 v[112:113], 14, v[112:113]
	v_max_f32_e32 v108, 0, v108
	v_max_f32_e32 v109, 0, v109
	v_max_f32_e32 v104, 0, v104
	v_max_f32_e32 v105, 0, v105
	v_max_f32_e32 v107, 0, v107
	v_lshl_add_u64 v[112:113], s[14:15], 0, v[112:113]
	v_pk_mul_f32 v[108:109], v[108:109], v[108:109]
	v_pk_mul_f32 v[110:111], v[104:105], v[104:105]
	v_pk_mul_f32 v[116:117], v[106:107], v[106:107]
	v_max_f32_e32 v96, v96, v96
	v_max_f32_e32 v97, v97, v97
	v_lshl_add_u64 v[112:113], v[112:113], 0, v[156:157]
	v_cvt_pk_bf16_f32 v104, v108, v109
	v_cvt_pk_bf16_f32 v105, v110, v111
	v_cvt_pk_bf16_f32 v106, v114, v115
	v_cvt_pk_bf16_f32 v107, v116, v117
	v_max_f32_e32 v96, 0, v96
	v_max_f32_e32 v97, 0, v97
	global_store_dwordx4 v[112:113], v[104:107], off sc1
	v_max_f32_e32 v100, v100, v100
	v_max_f32_e32 v101, v101, v101
	v_pk_mul_f32 v[104:105], v[96:97], v[96:97]
	v_max_f32_e32 v97, v98, v98
	v_max_f32_e32 v96, v102, v102
	v_max_f32_e32 v98, 0, v97
	v_max_f32_e32 v97, v103, v103
	v_max_f32_e32 v99, v99, v99
	v_max_f32_e32 v100, 0, v100
	v_max_f32_e32 v101, 0, v101
	v_max_f32_e32 v96, 0, v96
	v_max_f32_e32 v97, 0, v97
	v_max_f32_e32 v99, 0, v99
	v_pk_mul_f32 v[100:101], v[100:101], v[100:101]
	v_pk_mul_f32 v[102:103], v[96:97], v[96:97]
	v_pk_mul_f32 v[106:107], v[98:99], v[98:99]
	v_max_f32_e32 v88, v88, v88
	v_max_f32_e32 v89, v89, v89
	v_cvt_pk_bf16_f32 v96, v100, v101
	v_cvt_pk_bf16_f32 v97, v102, v103
	v_cvt_pk_bf16_f32 v98, v104, v105
	v_cvt_pk_bf16_f32 v99, v106, v107
	v_max_f32_e32 v88, 0, v88
	v_max_f32_e32 v89, 0, v89
	global_store_dwordx4 v[112:113], v[96:99], off offset:256 sc1
	v_max_f32_e32 v92, v92, v92
	v_max_f32_e32 v93, v93, v93
	v_or_b32_e32 v96, 32, v152
	v_pk_mul_f32 v[98:99], v[88:89], v[88:89]
	v_max_f32_e32 v89, v90, v90
	v_ashrrev_i32_e32 v97, 31, v96
	v_max_f32_e32 v88, v94, v94
	v_max_f32_e32 v90, 0, v89
	v_max_f32_e32 v89, v95, v95
	v_max_f32_e32 v91, v91, v91
	v_lshlrev_b64 v[96:97], 14, v[96:97]
	v_max_f32_e32 v92, 0, v92
	v_max_f32_e32 v93, 0, v93
	v_max_f32_e32 v88, 0, v88
	v_max_f32_e32 v89, 0, v89
	v_max_f32_e32 v91, 0, v91
	v_lshl_add_u64 v[96:97], s[14:15], 0, v[96:97]
	v_pk_mul_f32 v[92:93], v[92:93], v[92:93]
	v_pk_mul_f32 v[94:95], v[88:89], v[88:89]
	v_pk_mul_f32 v[100:101], v[90:91], v[90:91]
	v_max_f32_e32 v80, v80, v80
	v_max_f32_e32 v81, v81, v81
	v_lshl_add_u64 v[96:97], v[96:97], 0, v[156:157]
	v_cvt_pk_bf16_f32 v88, v92, v93
	v_cvt_pk_bf16_f32 v89, v94, v95
	v_cvt_pk_bf16_f32 v90, v98, v99
	v_cvt_pk_bf16_f32 v91, v100, v101
	v_max_f32_e32 v80, 0, v80
	v_max_f32_e32 v81, 0, v81
	global_store_dwordx4 v[96:97], v[88:91], off sc1
	v_max_f32_e32 v84, v84, v84
	v_max_f32_e32 v85, v85, v85
	v_pk_mul_f32 v[88:89], v[80:81], v[80:81]
	v_max_f32_e32 v81, v82, v82
	v_max_f32_e32 v80, v86, v86
	v_max_f32_e32 v82, 0, v81
	v_max_f32_e32 v81, v87, v87
	v_max_f32_e32 v83, v83, v83
	v_max_f32_e32 v84, 0, v84
	v_max_f32_e32 v85, 0, v85
	v_max_f32_e32 v80, 0, v80
	v_max_f32_e32 v81, 0, v81
	v_max_f32_e32 v83, 0, v83
	v_pk_mul_f32 v[84:85], v[84:85], v[84:85]
	v_pk_mul_f32 v[86:87], v[80:81], v[80:81]
; __device__ __forceinline__ u32x4 pack8f(f32x4 v0, f32x4 v1) { u32x4 w; w.x = cvt_pk_bf16(v0[0], v0[1]); w.y = cvt_pk_bf16(v0[2], v0[3]); w.z = cvt_pk_bf16(v1[0], v1[1]); w.w = cvt_pk_bf16(v1[2], v1[3]); return w; }
;     __device__ __forceinline__ void operator()(const f32x4 (&acc)[2][2][4][2], const Unit& u, int wr, int wc, int fr, int fq) const {
;     ...
;             for (int m = 0; m < 4; ++m) { bf16_t* rowp = O + (size_t)(row0 + ai * HALF + m * 16) * ldc + c0;
; #pragma unroll
;                 for (int bj = 0; bj < 2; ++bj) { f32x4 v0 = acc[ai][bj][m][0], v1 = acc[ai][bj][m][1];
; #pragma unroll
;                     for (int e = 0; e < 4; ++e) { const float a = fmaxf(v0[e], 0.f), b = fmaxf(v1[e], 0.f); v0[e] = a * a; v1[e] = b * b; }
;                     *(u32x4*)(rowp + bj * HALF) = pack8f(v0, v1); } }
	v_pk_mul_f32 v[90:91], v[82:83], v[82:83]
	v_max_f32_e32 v72, v72, v72
	v_max_f32_e32 v73, v73, v73
	v_cvt_pk_bf16_f32 v80, v84, v85
	v_cvt_pk_bf16_f32 v81, v86, v87
	v_cvt_pk_bf16_f32 v82, v88, v89
	v_cvt_pk_bf16_f32 v83, v90, v91
	v_max_f32_e32 v72, 0, v72
	v_max_f32_e32 v73, 0, v73
	global_store_dwordx4 v[96:97], v[80:83], off offset:256 sc1
	v_max_f32_e32 v76, v76, v76
	v_max_f32_e32 v77, v77, v77
	v_or_b32_e32 v80, 48, v152
	v_pk_mul_f32 v[82:83], v[72:73], v[72:73]
	v_max_f32_e32 v73, v74, v74
	v_ashrrev_i32_e32 v81, 31, v80
	v_max_f32_e32 v72, v78, v78
	v_max_f32_e32 v74, 0, v73
	v_max_f32_e32 v73, v79, v79
	v_max_f32_e32 v75, v75, v75
	v_lshlrev_b64 v[80:81], 14, v[80:81]
	v_max_f32_e32 v76, 0, v76
	v_max_f32_e32 v77, 0, v77
	v_max_f32_e32 v72, 0, v72
	v_max_f32_e32 v73, 0, v73
	v_max_f32_e32 v75, 0, v75
	v_lshl_add_u64 v[80:81], s[14:15], 0, v[80:81]
	v_pk_mul_f32 v[76:77], v[76:77], v[76:77]
	v_pk_mul_f32 v[78:79], v[72:73], v[72:73]
	v_pk_mul_f32 v[84:85], v[74:75], v[74:75]
	v_max_f32_e32 v64, v64, v64
	v_max_f32_e32 v65, v65, v65
	v_lshl_add_u64 v[80:81], v[80:81], 0, v[156:157]
	v_cvt_pk_bf16_f32 v72, v76, v77
	v_cvt_pk_bf16_f32 v73, v78, v79
	v_cvt_pk_bf16_f32 v74, v82, v83
	v_cvt_pk_bf16_f32 v75, v84, v85
	v_max_f32_e32 v64, 0, v64
	v_max_f32_e32 v65, 0, v65
	global_store_dwordx4 v[80:81], v[72:75], off sc1
	v_max_f32_e32 v68, v68, v68
	v_max_f32_e32 v69, v69, v69
	v_pk_mul_f32 v[72:73], v[64:65], v[64:65]
	v_max_f32_e32 v65, v66, v66
	v_max_f32_e32 v64, v70, v70
	v_max_f32_e32 v66, 0, v65
	v_max_f32_e32 v65, v71, v71
	v_max_f32_e32 v67, v67, v67
	v_max_f32_e32 v68, 0, v68
	v_max_f32_e32 v69, 0, v69
	v_max_f32_e32 v64, 0, v64
	v_max_f32_e32 v65, 0, v65
	v_max_f32_e32 v67, 0, v67
	v_pk_mul_f32 v[68:69], v[68:69], v[68:69]
	v_pk_mul_f32 v[70:71], v[64:65], v[64:65]
	v_pk_mul_f32 v[74:75], v[66:67], v[66:67]
	v_max_f32_e32 v56, v56, v56
	v_max_f32_e32 v57, v57, v57
	v_cvt_pk_bf16_f32 v64, v68, v69
	v_cvt_pk_bf16_f32 v65, v70, v71
	v_cvt_pk_bf16_f32 v66, v72, v73
	v_cvt_pk_bf16_f32 v67, v74, v75
	v_max_f32_e32 v56, 0, v56
	v_max_f32_e32 v57, 0, v57
	global_store_dwordx4 v[80:81], v[64:67], off offset:256 sc1
	v_max_f32_e32 v60, v60, v60
	v_max_f32_e32 v61, v61, v61
	v_pk_mul_f32 v[66:67], v[56:57], v[56:57]
	v_max_f32_e32 v57, v58, v58
	v_max_f32_e32 v60, 0, v60
	v_max_f32_e32 v61, 0, v61
	v_max_f32_e32 v56, v62, v62
	v_max_f32_e32 v58, 0, v57
	v_max_f32_e32 v57, v63, v63
	v_max_f32_e32 v59, v59, v59
	v_pk_mul_f32 v[60:61], v[60:61], v[60:61]
	v_max_f32_e32 v56, 0, v56
	v_max_f32_e32 v57, 0, v57
	v_max_f32_e32 v59, 0, v59
	s_mov_b32 s21, 0x200000
	v_pk_mul_f32 v[62:63], v[56:57], v[56:57]
	v_pk_mul_f32 v[68:69], v[58:59], v[58:59]
	v_cvt_pk_bf16_f32 v56, v60, v61
	v_add_co_u32_e32 v60, vcc, s21, v144
	v_max_f32_e32 v48, v48, v48
	v_max_f32_e32 v49, v49, v49
	v_cvt_pk_bf16_f32 v57, v62, v63
	v_cvt_pk_bf16_f32 v58, v66, v67
	v_cvt_pk_bf16_f32 v59, v68, v69
	v_addc_co_u32_e32 v61, vcc, 0, v145, vcc
	v_max_f32_e32 v48, 0, v48
	v_max_f32_e32 v49, 0, v49
	global_store_dwordx4 v[60:61], v[56:59], off sc1
	v_max_f32_e32 v52, v52, v52
	v_max_f32_e32 v53, v53, v53
	v_pk_mul_f32 v[56:57], v[48:49], v[48:49]
	v_max_f32_e32 v49, v50, v50
	v_max_f32_e32 v48, v54, v54
	v_max_f32_e32 v50, 0, v49
	v_max_f32_e32 v49, v55, v55
	v_max_f32_e32 v51, v51, v51
	v_max_f32_e32 v52, 0, v52
	v_max_f32_e32 v53, 0, v53
	v_max_f32_e32 v48, 0, v48
	v_max_f32_e32 v49, 0, v49
	v_max_f32_e32 v51, 0, v51
	s_mov_b64 s[28:29], 0x200000
	v_pk_mul_f32 v[52:53], v[52:53], v[52:53]
	v_pk_mul_f32 v[54:55], v[48:49], v[48:49]
	v_pk_mul_f32 v[58:59], v[50:51], v[50:51]
	v_max_f32_e32 v40, v40, v40
	v_max_f32_e32 v41, v41, v41
	v_lshl_add_u64 v[64:65], v[144:145], 0, s[28:29]
	v_cvt_pk_bf16_f32 v48, v52, v53
	v_cvt_pk_bf16_f32 v49, v54, v55
	v_cvt_pk_bf16_f32 v50, v56, v57
	v_cvt_pk_bf16_f32 v51, v58, v59
	v_max_f32_e32 v40, 0, v40
	v_max_f32_e32 v41, 0, v41
	global_store_dwordx4 v[64:65], v[48:51], off offset:256 sc1
	v_max_f32_e32 v44, v44, v44
	v_max_f32_e32 v45, v45, v45
	v_pk_mul_f32 v[50:51], v[40:41], v[40:41]
	v_max_f32_e32 v41, v42, v42
	v_max_f32_e32 v44, 0, v44
	v_max_f32_e32 v45, 0, v45
	v_max_f32_e32 v40, v46, v46
	v_max_f32_e32 v42, 0, v41
	v_max_f32_e32 v41, v47, v47
	v_max_f32_e32 v43, v43, v43
	v_pk_mul_f32 v[44:45], v[44:45], v[44:45]
	v_max_f32_e32 v40, 0, v40
	v_max_f32_e32 v41, 0, v41
	v_max_f32_e32 v43, 0, v43
	s_mov_b32 s21, 0x240000
	v_pk_mul_f32 v[46:47], v[40:41], v[40:41]
	v_pk_mul_f32 v[52:53], v[42:43], v[42:43]
	v_cvt_pk_bf16_f32 v40, v44, v45
	v_add_co_u32_e32 v44, vcc, s21, v144
	v_max_f32_e32 v32, v32, v32
	v_max_f32_e32 v33, v33, v33
	v_cvt_pk_bf16_f32 v41, v46, v47
; __device__ __forceinline__ u32x4 pack8f(f32x4 v0, f32x4 v1) { u32x4 w; w.x = cvt_pk_bf16(v0[0], v0[1]); w.y = cvt_pk_bf16(v0[2], v0[3]); w.z = cvt_pk_bf16(v1[0], v1[1]); w.w = cvt_pk_bf16(v1[2], v1[3]); return w; }
;     __device__ __forceinline__ void operator()(const f32x4 (&acc)[2][2][4][2], const Unit& u, int wr, int wc, int fr, int fq) const {
;         const int row0 = u.pm * BM + wr * 64 + fr, c0 = u.pn * BM + wc * 32 + 8 * fq;
; #pragma unroll
;         for (int ai = 0; ai < 2; ++ai)
; #pragma unroll
;             for (int m = 0; m < 4; ++m) { bf16_t* rowp = O + (size_t)(row0 + ai * HALF + m * 16) * ldc + c0;
; #pragma unroll
;                 for (int bj = 0; bj < 2; ++bj) { f32x4 v0 = acc[ai][bj][m][0], v1 = acc[ai][bj][m][1];
; #pragma unroll
;                     for (int e = 0; e < 4; ++e) { const float a = fmaxf(v0[e], 0.f), b = fmaxf(v1[e], 0.f); v0[e] = a * a; v1[e] = b * b; }
;                     *(u32x4*)(rowp + bj * HALF) = pack8f(v0, v1); } }
;     }
	v_cvt_pk_bf16_f32 v42, v50, v51
	v_cvt_pk_bf16_f32 v43, v52, v53
	v_addc_co_u32_e32 v45, vcc, 0, v145, vcc
	v_max_f32_e32 v32, 0, v32
	v_max_f32_e32 v33, 0, v33
	global_store_dwordx4 v[44:45], v[40:43], off sc1
	v_max_f32_e32 v36, v36, v36
	v_max_f32_e32 v37, v37, v37
	v_pk_mul_f32 v[40:41], v[32:33], v[32:33]
	v_max_f32_e32 v33, v34, v34
	v_max_f32_e32 v32, v38, v38
	v_max_f32_e32 v34, 0, v33
	v_max_f32_e32 v33, v39, v39
	v_max_f32_e32 v35, v35, v35
	v_max_f32_e32 v36, 0, v36
	v_max_f32_e32 v37, 0, v37
	v_max_f32_e32 v32, 0, v32
	v_max_f32_e32 v33, 0, v33
	v_max_f32_e32 v35, 0, v35
	s_mov_b64 s[28:29], 0x240000
	v_pk_mul_f32 v[36:37], v[36:37], v[36:37]
	v_pk_mul_f32 v[38:39], v[32:33], v[32:33]
	v_pk_mul_f32 v[42:43], v[34:35], v[34:35]
	v_max_f32_e32 v24, v24, v24
	v_max_f32_e32 v25, v25, v25
	v_lshl_add_u64 v[48:49], v[144:145], 0, s[28:29]
	v_cvt_pk_bf16_f32 v32, v36, v37
	v_cvt_pk_bf16_f32 v33, v38, v39
	v_cvt_pk_bf16_f32 v34, v40, v41
	v_cvt_pk_bf16_f32 v35, v42, v43
	v_max_f32_e32 v24, 0, v24
	v_max_f32_e32 v25, 0, v25
	global_store_dwordx4 v[48:49], v[32:35], off offset:256 sc1
	v_max_f32_e32 v28, v28, v28
	v_max_f32_e32 v29, v29, v29
	v_pk_mul_f32 v[34:35], v[24:25], v[24:25]
	v_max_f32_e32 v25, v26, v26
	v_max_f32_e32 v28, 0, v28
	v_max_f32_e32 v29, 0, v29
	v_max_f32_e32 v24, v30, v30
	v_max_f32_e32 v26, 0, v25
	v_max_f32_e32 v25, v31, v31
	v_max_f32_e32 v27, v27, v27
	v_pk_mul_f32 v[28:29], v[28:29], v[28:29]
	v_max_f32_e32 v24, 0, v24
	v_max_f32_e32 v25, 0, v25
	v_max_f32_e32 v27, 0, v27
	s_mov_b32 s21, 0x280000
	v_pk_mul_f32 v[30:31], v[24:25], v[24:25]
	v_pk_mul_f32 v[36:37], v[26:27], v[26:27]
	v_cvt_pk_bf16_f32 v24, v28, v29
	v_add_co_u32_e32 v28, vcc, s21, v144
	v_max_f32_e32 v16, v16, v16
	v_max_f32_e32 v17, v17, v17
	v_cvt_pk_bf16_f32 v25, v30, v31
	v_cvt_pk_bf16_f32 v26, v34, v35
	v_cvt_pk_bf16_f32 v27, v36, v37
	v_addc_co_u32_e32 v29, vcc, 0, v145, vcc
	v_max_f32_e32 v16, 0, v16
	v_max_f32_e32 v17, 0, v17
	global_store_dwordx4 v[28:29], v[24:27], off sc1
	v_max_f32_e32 v20, v20, v20
	v_max_f32_e32 v21, v21, v21
	v_pk_mul_f32 v[24:25], v[16:17], v[16:17]
	v_max_f32_e32 v17, v18, v18
	v_max_f32_e32 v16, v22, v22
	v_max_f32_e32 v18, 0, v17
	v_max_f32_e32 v17, v23, v23
	v_max_f32_e32 v19, v19, v19
	v_max_f32_e32 v20, 0, v20
	v_max_f32_e32 v21, 0, v21
	v_max_f32_e32 v16, 0, v16
	v_max_f32_e32 v17, 0, v17
	v_max_f32_e32 v19, 0, v19
	s_mov_b64 s[28:29], 0x280000
	v_pk_mul_f32 v[20:21], v[20:21], v[20:21]
	v_pk_mul_f32 v[22:23], v[16:17], v[16:17]
	v_pk_mul_f32 v[26:27], v[18:19], v[18:19]
	v_max_f32_e32 v8, v8, v8
	v_max_f32_e32 v9, v9, v9
	v_lshl_add_u64 v[32:33], v[144:145], 0, s[28:29]
	v_cvt_pk_bf16_f32 v16, v20, v21
	v_cvt_pk_bf16_f32 v17, v22, v23
	v_cvt_pk_bf16_f32 v18, v24, v25
	v_cvt_pk_bf16_f32 v19, v26, v27
	v_max_f32_e32 v8, 0, v8
	v_max_f32_e32 v9, 0, v9
	global_store_dwordx4 v[32:33], v[16:19], off offset:256 sc1
	v_max_f32_e32 v12, v12, v12
	v_max_f32_e32 v13, v13, v13
	v_pk_mul_f32 v[18:19], v[8:9], v[8:9]
	v_max_f32_e32 v9, v10, v10
	v_max_f32_e32 v12, 0, v12
	v_max_f32_e32 v13, 0, v13
	v_max_f32_e32 v8, v14, v14
	v_max_f32_e32 v10, 0, v9
	v_max_f32_e32 v9, v15, v15
	v_max_f32_e32 v11, v11, v11
	v_pk_mul_f32 v[12:13], v[12:13], v[12:13]
	v_max_f32_e32 v8, 0, v8
	v_max_f32_e32 v9, 0, v9
	v_max_f32_e32 v11, 0, v11
	s_mov_b32 s21, 0x2c0000
	v_pk_mul_f32 v[14:15], v[8:9], v[8:9]
	v_pk_mul_f32 v[20:21], v[10:11], v[10:11]
	v_cvt_pk_bf16_f32 v8, v12, v13
	v_add_co_u32_e32 v12, vcc, s21, v144
	v_max_f32_e32 v0, v0, v0
	v_max_f32_e32 v1, v1, v1
	v_cvt_pk_bf16_f32 v9, v14, v15
	v_cvt_pk_bf16_f32 v10, v18, v19
	v_cvt_pk_bf16_f32 v11, v20, v21
	v_addc_co_u32_e32 v13, vcc, 0, v145, vcc
	v_max_f32_e32 v0, 0, v0
	v_max_f32_e32 v1, 0, v1
	global_store_dwordx4 v[12:13], v[8:11], off sc1
	v_max_f32_e32 v4, v4, v4
	v_max_f32_e32 v5, v5, v5
	v_pk_mul_f32 v[8:9], v[0:1], v[0:1]
	v_max_f32_e32 v1, v2, v2
	v_max_f32_e32 v0, v6, v6
	v_max_f32_e32 v2, 0, v1
	v_max_f32_e32 v1, v7, v7
	v_max_f32_e32 v3, v3, v3
	v_max_f32_e32 v4, 0, v4
	v_max_f32_e32 v5, 0, v5
	v_max_f32_e32 v0, 0, v0
	v_max_f32_e32 v1, 0, v1
	v_max_f32_e32 v3, 0, v3
	s_mov_b64 s[28:29], 0x2c0000
	v_pk_mul_f32 v[4:5], v[4:5], v[4:5]
	v_pk_mul_f32 v[6:7], v[0:1], v[0:1]
	v_pk_mul_f32 v[10:11], v[2:3], v[2:3]
	v_lshl_add_u64 v[16:17], v[144:145], 0, s[28:29]
	v_cvt_pk_bf16_f32 v0, v4, v5
	v_cvt_pk_bf16_f32 v1, v6, v7
	v_cvt_pk_bf16_f32 v2, v8, v9
	v_cvt_pk_bf16_f32 v3, v10, v11
	s_andn2_b64 vcc, exec, s[38:39]
	s_mov_b64 s[28:29], -1
	global_store_dwordx4 v[16:17], v[0:3], off offset:256 sc1
	s_cbranch_vccnz .LBB0_767
	s_andn2_b64 vcc, exec, s[12:13]
	s_cbranch_vccnz .LBB0_766
	s_barrier
	s_branch .LBB0_766

;     __device__ __forceinline__ void operator()(const f32x4 (&acc)[2][2][4][2], const Unit& u, int wr, int wc, int fr, int fq) const {
;         const int row0 = u.pm * BM + wr * 64 + fr, c0 = u.pn * BM + wc * 32 + 4 * fq; const float* gp = gate + (size_t)(u.pm >> 5) * 12288 + c0;
;         f32x4 gv[2][2];
; #pragma unroll
;         for (int bj = 0; bj < 2; ++bj)
; #pragma unroll
;             for (int n = 0; n < 2; ++n) gv[bj][n] = *(const f32x4*)(gp + bj * HALF + n * 16);
; #pragma unroll
;         for (int ai = 0; ai < 2; ++ai) {
;             f32x4 bs[4][2][2];
; #pragma unroll
;             for (int m = 0; m < 4; ++m) { const size_t off = (size_t)(row0 + ai * HALF + m * 16) * 2048 + c0;
; #pragma unroll
;                 for (int bj = 0; bj < 2; ++bj)
; #pragma unroll
;                     for (int n = 0; n < 2; ++n) bs[m][bj][n] = *(const f32x4*)(base + off + bj * HALF + n * 16); }
; #pragma unroll
;             for (int m = 0; m < 4; ++m) { const size_t off = (size_t)(row0 + ai * HALF + m * 16) * 2048 + c0;
; #pragma unroll
;                 for (int bj = 0; bj < 2; ++bj)
; #pragma unroll
;                     for (int n = 0; n < 2; ++n) *(f32x4*)(out + off + bj * HALF + n * 16) = bs[m][bj][n] + gv[bj][n] * acc[ai][bj][m][n]; }
;         }
;     }
.LBB0_850:
	v_lshl_or_b32 v72, s29, 8, v164
	s_ashr_i32 s21, s28, 5
	s_mul_hi_i32 s23, s21, 0xc000
	s_mul_i32 s21, s21, 0xc000
	v_ashrrev_i32_e32 v73, 31, v72
	v_lshl_add_u32 v216, s28, 8, v162
	s_add_u32 s30, s51, s21
	v_lshlrev_b64 v[156:157], 2, v[72:73]
	v_ashrrev_i32_e32 v217, 31, v216
	s_addc_u32 s31, s52, s23
	v_lshl_add_u64 v[158:159], s[4:5], 0, v[156:157]
	v_lshlrev_b64 v[160:161], 13, v[216:217]
	v_or_b32_e32 v184, 16, v216
	v_lshl_add_u64 v[72:73], s[30:31], 0, v[156:157]
	v_lshl_add_u64 v[180:181], v[158:159], 0, v[160:161]
	v_ashrrev_i32_e32 v185, 31, v184
	global_load_dwordx4 v[108:111], v[72:73], off
	global_load_dwordx4 v[92:95], v[72:73], off offset:64
	global_load_dwordx4 v[84:87], v[72:73], off offset:512
	s_nop 0
	global_load_dwordx4 v[72:75], v[72:73], off offset:576
	s_nop 0
	global_load_dwordx4 v[168:171], v[180:181], off
	global_load_dwordx4 v[172:175], v[180:181], off offset:64
	global_load_dwordx4 v[176:179], v[180:181], off offset:512
	s_nop 0
	global_load_dwordx4 v[180:183], v[180:181], off offset:576
	v_lshlrev_b64 v[232:233], 13, v[184:185]
	v_or_b32_e32 v200, 32, v216
	v_lshl_add_u64 v[196:197], v[158:159], 0, v[232:233]
	v_ashrrev_i32_e32 v201, 31, v200
	global_load_dwordx4 v[184:187], v[196:197], off
	global_load_dwordx4 v[188:191], v[196:197], off offset:64
	global_load_dwordx4 v[192:195], v[196:197], off offset:512
	s_nop 0
	global_load_dwordx4 v[196:199], v[196:197], off offset:576
	v_lshlrev_b64 v[234:235], 13, v[200:201]
	v_or_b32_e32 v216, 48, v216
	v_lshl_add_u64 v[212:213], v[158:159], 0, v[234:235]
	v_ashrrev_i32_e32 v217, 31, v216
	global_load_dwordx4 v[200:203], v[212:213], off
	global_load_dwordx4 v[204:207], v[212:213], off offset:64
	global_load_dwordx4 v[208:211], v[212:213], off offset:512
	s_nop 0
	global_load_dwordx4 v[212:215], v[212:213], off offset:576
	v_lshlrev_b64 v[236:237], 13, v[216:217]
	v_lshl_add_u64 v[228:229], v[158:159], 0, v[236:237]
	global_load_dwordx4 v[216:219], v[228:229], off
	global_load_dwordx4 v[220:223], v[228:229], off offset:64
	global_load_dwordx4 v[224:227], v[228:229], off offset:512
	s_nop 0
	global_load_dwordx4 v[228:231], v[228:229], off offset:576
	s_mov_b64 s[28:29], -1
	s_andn2_b64 vcc, exec, s[0:1]
	s_waitcnt vmcnt(0)
	v_pk_fma_f32 v[140:141], v[140:141], v[108:109], v[168:169]
	v_lshl_add_u64 v[168:169], s[4:5], 0, v[160:161]
	v_lshl_add_u64 v[168:169], v[168:169], 0, v[156:157]
	v_pk_fma_f32 v[126:127], v[126:127], v[86:87], v[178:179]
	v_pk_fma_f32 v[124:125], v[124:125], v[84:85], v[176:177]
	global_store_dwordx4 v[168:169], v[124:127], off offset:512 sc1
	v_pk_fma_f32 v[118:119], v[118:119], v[74:75], v[182:183]
	v_pk_fma_f32 v[106:107], v[106:107], v[86:87], v[194:195]
	v_lshl_add_u64 v[124:125], s[4:5], 0, v[232:233]
	v_lshl_add_u64 v[124:125], v[124:125], 0, v[156:157]
	v_pk_fma_f32 v[104:105], v[104:105], v[84:85], v[192:193]
	global_store_dwordx4 v[124:125], v[104:107], off offset:512 sc1
	v_pk_fma_f32 v[82:83], v[82:83], v[86:87], v[210:211]
	v_pk_fma_f32 v[80:81], v[80:81], v[84:85], v[208:209]
	v_lshl_add_u64 v[104:105], s[4:5], 0, v[234:235]
	v_lshl_add_u64 v[104:105], v[104:105], 0, v[156:157]
	v_pk_fma_f32 v[116:117], v[116:117], v[72:73], v[180:181]
	v_pk_fma_f32 v[98:99], v[98:99], v[74:75], v[198:199]
	v_pk_fma_f32 v[96:97], v[96:97], v[72:73], v[196:197]
	global_store_dwordx4 v[104:105], v[80:83], off offset:512 sc1
	v_pk_fma_f32 v[78:79], v[78:79], v[74:75], v[214:215]
	v_pk_fma_f32 v[76:77], v[76:77], v[72:73], v[212:213]
	v_lshl_add_u64 v[80:81], s[4:5], 0, v[236:237]
	v_pk_fma_f32 v[142:143], v[142:143], v[110:111], v[170:171]
	global_store_dwordx4 v[168:169], v[116:119], off offset:576 sc1
	global_store_dwordx4 v[124:125], v[96:99], off offset:576 sc1
	global_store_dwordx4 v[104:105], v[76:79], off offset:576 sc1
	v_pk_fma_f32 v[118:119], v[134:135], v[110:111], v[186:187]
	v_pk_fma_f32 v[116:117], v[132:133], v[108:109], v[184:185]
	v_pk_fma_f32 v[98:99], v[122:123], v[110:111], v[202:203]
	v_pk_fma_f32 v[96:97], v[120:121], v[108:109], v[200:201]
	v_pk_fma_f32 v[78:79], v[102:103], v[110:111], v[218:219]
	v_pk_fma_f32 v[76:77], v[100:101], v[108:109], v[216:217]
	v_lshl_add_u64 v[80:81], v[80:81], 0, v[156:157]
	global_store_dwordx4 v[168:169], v[140:143], off sc1
	v_pk_fma_f32 v[138:139], v[138:139], v[94:95], v[174:175]
	v_pk_fma_f32 v[136:137], v[136:137], v[92:93], v[172:173]
	global_store_dwordx4 v[124:125], v[116:119], off sc1
	global_store_dwordx4 v[104:105], v[96:99], off sc1
	global_store_dwordx4 v[80:81], v[76:79], off sc1
	v_pk_fma_f32 v[118:119], v[130:131], v[94:95], v[190:191]
	v_pk_fma_f32 v[116:117], v[128:129], v[92:93], v[188:189]
	v_pk_fma_f32 v[98:99], v[114:115], v[94:95], v[206:207]
	v_pk_fma_f32 v[96:97], v[112:113], v[92:93], v[204:205]
	v_pk_fma_f32 v[78:79], v[90:91], v[94:95], v[222:223]
	v_pk_fma_f32 v[76:77], v[88:89], v[92:93], v[220:221]
	v_pk_fma_f32 v[70:71], v[70:71], v[86:87], v[226:227]
	v_pk_fma_f32 v[68:69], v[68:69], v[84:85], v[224:225]
	v_pk_fma_f32 v[66:67], v[66:67], v[74:75], v[230:231]
	v_pk_fma_f32 v[64:65], v[64:65], v[72:73], v[228:229]
	v_lshl_add_u64 v[142:143], v[160:161], 0, s[12:13]
	global_store_dwordx4 v[168:169], v[136:139], off offset:64 sc1
	global_store_dwordx4 v[124:125], v[116:119], off offset:64 sc1
	global_store_dwordx4 v[104:105], v[96:99], off offset:64 sc1
	global_store_dwordx4 v[80:81], v[76:79], off offset:64 sc1
	global_store_dwordx4 v[80:81], v[68:71], off offset:512 sc1
	global_store_dwordx4 v[80:81], v[64:67], off offset:576 sc1
	v_lshl_add_u64 v[140:141], v[160:161], 0, s[14:15]
	v_lshl_add_u64 v[138:139], v[160:161], 0, s[16:17]
	v_lshl_add_u64 v[64:65], v[158:159], 0, v[142:143]
	global_load_dwordx4 v[124:127], v[64:65], off
	global_load_dwordx4 v[120:123], v[64:65], off offset:64
	global_load_dwordx4 v[116:119], v[64:65], off offset:512
	global_load_dwordx4 v[104:107], v[64:65], off offset:576
	v_lshl_add_u64 v[64:65], v[158:159], 0, v[140:141]
	global_load_dwordx4 v[112:115], v[64:65], off
	global_load_dwordx4 v[100:103], v[64:65], off offset:64
	global_load_dwordx4 v[88:91], v[64:65], off offset:512
	global_load_dwordx4 v[76:79], v[64:65], off offset:576
	v_lshl_add_u64 v[64:65], v[158:159], 0, v[138:139]
	global_load_dwordx4 v[96:99], v[64:65], off
	global_load_dwordx4 v[80:83], v[64:65], off offset:64
	global_load_dwordx4 v[68:71], v[64:65], off offset:512
	s_nop 0
	global_load_dwordx4 v[64:67], v[64:65], off offset:576
	v_lshl_add_u64 v[136:137], v[160:161], 0, s[18:19]
	v_lshl_add_u64 v[128:129], v[158:159], 0, v[136:137]
	global_load_dwordx4 v[158:161], v[128:129], off
	global_load_dwordx4 v[168:171], v[128:129], off offset:64
	global_load_dwordx4 v[132:135], v[128:129], off offset:512
	s_nop 0
	global_load_dwordx4 v[128:131], v[128:129], off offset:576
	s_waitcnt vmcnt(15)
;     __device__ __forceinline__ void operator()(const f32x4 (&acc)[2][2][4][2], const Unit& u, int wr, int wc, int fr, int fq) const {
;     ...
;         for (int ai = 0; ai < 2; ++ai) {
;             f32x4 bs[4][2][2];
; #pragma unroll
;             for (int m = 0; m < 4; ++m) { const size_t off = (size_t)(row0 + ai * HALF + m * 16) * 2048 + c0;
; #pragma unroll
;                 for (int bj = 0; bj < 2; ++bj)
; #pragma unroll
;                     for (int n = 0; n < 2; ++n) bs[m][bj][n] = *(const f32x4*)(base + off + bj * HALF + n * 16); }
; #pragma unroll
;             for (int m = 0; m < 4; ++m) { const size_t off = (size_t)(row0 + ai * HALF + m * 16) * 2048 + c0;
; #pragma unroll
;                 for (int bj = 0; bj < 2; ++bj)
; #pragma unroll
;                     for (int n = 0; n < 2; ++n) *(f32x4*)(out + off + bj * HALF + n * 16) = bs[m][bj][n] + gv[bj][n] * acc[ai][bj][m][n]; }
;         }
;     }
	v_pk_fma_f32 v[60:61], v[60:61], v[108:109], v[124:125]
	v_lshl_add_u64 v[124:125], s[4:5], 0, v[142:143]
	v_lshl_add_u64 v[124:125], v[124:125], 0, v[156:157]
	s_waitcnt vmcnt(13)
	v_pk_fma_f32 v[50:51], v[50:51], v[86:87], v[118:119]
	v_pk_fma_f32 v[48:49], v[48:49], v[84:85], v[116:117]
	global_store_dwordx4 v[124:125], v[48:51], off offset:512 sc1
	s_waitcnt vmcnt(10)
	v_pk_fma_f32 v[34:35], v[34:35], v[86:87], v[90:91]
	v_pk_fma_f32 v[32:33], v[32:33], v[84:85], v[88:89]
	v_lshl_add_u64 v[48:49], s[4:5], 0, v[140:141]
	v_lshl_add_u64 v[48:49], v[48:49], 0, v[156:157]
	global_store_dwordx4 v[48:49], v[32:35], off offset:512 sc1
	s_waitcnt vmcnt(7)
	v_pk_fma_f32 v[18:19], v[18:19], v[86:87], v[70:71]
	v_pk_fma_f32 v[16:17], v[16:17], v[84:85], v[68:69]
	v_lshl_add_u64 v[32:33], s[4:5], 0, v[138:139]
	v_lshl_add_u64 v[32:33], v[32:33], 0, v[156:157]
	v_pk_fma_f32 v[42:43], v[42:43], v[74:75], v[106:107]
	v_pk_fma_f32 v[40:41], v[40:41], v[72:73], v[104:105]
	v_pk_fma_f32 v[26:27], v[26:27], v[74:75], v[78:79]
	v_pk_fma_f32 v[24:25], v[24:25], v[72:73], v[76:77]
	global_store_dwordx4 v[32:33], v[16:19], off offset:512 sc1
	s_waitcnt vmcnt(7)
	v_pk_fma_f32 v[10:11], v[10:11], v[74:75], v[66:67]
	v_pk_fma_f32 v[8:9], v[8:9], v[72:73], v[64:65]
	v_lshl_add_u64 v[16:17], s[4:5], 0, v[136:137]
	global_store_dwordx4 v[124:125], v[40:43], off offset:576 sc1
	global_store_dwordx4 v[48:49], v[24:27], off offset:576 sc1
	global_store_dwordx4 v[32:33], v[8:11], off offset:576 sc1
	v_pk_fma_f32 v[42:43], v[54:55], v[110:111], v[114:115]
	v_pk_fma_f32 v[40:41], v[52:53], v[108:109], v[112:113]
	v_pk_fma_f32 v[26:27], v[38:39], v[110:111], v[98:99]
	v_pk_fma_f32 v[24:25], v[36:37], v[108:109], v[96:97]
	s_waitcnt vmcnt(9)
	v_pk_fma_f32 v[10:11], v[22:23], v[110:111], v[160:161]
	v_pk_fma_f32 v[8:9], v[20:21], v[108:109], v[158:159]
	v_lshl_add_u64 v[16:17], v[16:17], 0, v[156:157]
	v_pk_fma_f32 v[62:63], v[62:63], v[110:111], v[126:127]
	v_pk_fma_f32 v[58:59], v[58:59], v[94:95], v[122:123]
	v_pk_fma_f32 v[56:57], v[56:57], v[92:93], v[120:121]
	global_store_dwordx4 v[48:49], v[40:43], off sc1
	global_store_dwordx4 v[32:33], v[24:27], off sc1
	global_store_dwordx4 v[16:17], v[8:11], off sc1
	v_pk_fma_f32 v[42:43], v[46:47], v[94:95], v[102:103]
	v_pk_fma_f32 v[40:41], v[44:45], v[92:93], v[100:101]
	v_pk_fma_f32 v[26:27], v[30:31], v[94:95], v[82:83]
	v_pk_fma_f32 v[24:25], v[28:29], v[92:93], v[80:81]
	s_waitcnt vmcnt(11)
	v_pk_fma_f32 v[10:11], v[14:15], v[94:95], v[170:171]
	v_pk_fma_f32 v[8:9], v[12:13], v[92:93], v[168:169]
	s_waitcnt vmcnt(10)
	v_pk_fma_f32 v[6:7], v[6:7], v[86:87], v[134:135]
	v_pk_fma_f32 v[4:5], v[4:5], v[84:85], v[132:133]
	s_waitcnt vmcnt(9)
	v_pk_fma_f32 v[2:3], v[2:3], v[74:75], v[130:131]
	v_pk_fma_f32 v[0:1], v[0:1], v[72:73], v[128:129]
	global_store_dwordx4 v[124:125], v[60:63], off sc1
	global_store_dwordx4 v[124:125], v[56:59], off offset:64 sc1
	global_store_dwordx4 v[48:49], v[40:43], off offset:64 sc1
	global_store_dwordx4 v[32:33], v[24:27], off offset:64 sc1
	global_store_dwordx4 v[16:17], v[8:11], off offset:64 sc1
	global_store_dwordx4 v[16:17], v[4:7], off offset:512 sc1
	global_store_dwordx4 v[16:17], v[0:3], off offset:576 sc1
	s_cbranch_vccnz .LBB0_839
	s_andn2_b64 vcc, exec, s[6:7]
	s_cbranch_vccnz .LBB0_838
	s_barrier
	s_branch .LBB0_838
